# v016 + scan waves s_setprio 3 in rwkv fused phase + nt on weight-conversion f32 loads
# speedup vs baseline: 1.0020x; 1.0020x over previous
; #define LAS __attribute__((address_space(3)))
; __device__ __forceinline__ void phase_rwkv_fused(const Frame& F, const Args& a, int l) {
;     if (F.bid >= 160) return;
;     const int sc = F.bid, seq = sc >> 4, h = (sc >> 1) & 7, z = sc & 1;
;     constexpr int NCH = SEQ / 16, FR_RING = 6 * 15360, FR_FLAGS = FR_RING + 3 * RW_PBB;
;     LAS unsigned char* ring = F.lds + RING_OFF + FR_RING;
;     volatile LAS unsigned* ready = (volatile LAS unsigned*)(F.lds + RING_OFF + FR_FLAGS);
;     volatile LAS unsigned* done = ready + 4;
;     bf16* YS = (bf16*)(F.ws + WS_AR + AR_YSB);
;     __syncthreads();
;     if (F.tid < 16) ready[F.tid] = 0u;
;     __syncthreads();
;     ...
;     const int L = F.lane, li = L & 31, hh = L >> 5, vt = F.wave;
;     f32x16 st[2];
; #pragma unroll
;     for (int kt = 0; kt < 2; ++kt)
; #pragma unroll
;         for (int e = 0; e < 16; ++e) st[kt][e] = 0.f;
.LBB0_612:
	s_cmp_ge_i32 s50, s74
	s_cselect_b64 s[46:47], -1, 0
	s_and_b64 s[4:5], s[46:47], s[44:45]
	s_andn2_b64 vcc, exec, s[4:5]
	s_cbranch_vccnz .LBB0_781
	v_readlane_b32 s4, v254, 5
	s_mov_b32 s52, 0
	v_mbcnt_lo_u32_b32 v0, -1, 0
	v_mbcnt_hi_u32_b32 v0, -1, v0
	v_readlane_b32 s6, v254, 1
	v_readlane_b32 s5, v254, 10
	v_add_u32_e32 v148, s4, v0
	v_readlane_b32 s7, v254, 2
	v_readfirstlane_b32 s4, v148
	s_ashr_i32 s58, s4, 6
	v_readlane_b32 s4, v254, 0
	s_load_dwordx2 s[50:51], s[6:7], 0xf8
	s_waitcnt lgkmcnt(0)
	s_mov_b32 s8, s5
	s_mov_b32 s9, s4
	s_load_dwordx2 s[4:5], s[6:7], 0xf0
	s_waitcnt lgkmcnt(0)
	v_and_b32_e32 v149, 63, v148
	v_writelane_b32 v254, s8, 58
	v_writelane_b32 v254, s9, 60
	s_cmpk_gt_i32 s9, 0x9f
	s_mov_b64 s[4:5], -1
	s_cbranch_scc1 .LBB0_699
	v_cmp_gt_i32_e32 vcc, 16, v148
	s_waitcnt vmcnt(0)
	s_barrier
	s_and_saveexec_b64 s[4:5], vcc
	v_lshl_add_u32 v0, v148, 2, 0
	v_add_u32_e32 v0, 0x1fe00, v0
	ds_write_b32 v0, v185
	s_or_b64 exec, exec, s[4:5]
	v_readlane_b32 s4, v254, 60
	s_ashr_i32 s8, s4, 4
	s_bfe_u32 s15, s4, 0x30001
	s_and_b32 s17, s4, 1
	s_cmp_lt_i32 s58, 2
	s_mov_b64 s[4:5], -1
	s_waitcnt lgkmcnt(0)
	s_barrier
	s_cbranch_scc0 .LBB0_633
	s_setprio 3
	s_lshl_b32 s4, s58, 2
	s_add_i32 s14, s4, 0
	s_add_i32 s14, s14, 0x1fe10
	s_lshl_b32 s16, s58, 10
	s_cmp_eq_u32 s17, 0
	s_cselect_b64 s[6:7], -1, 0
	s_ashr_i32 s9, s8, 31
	s_lshl_b64 s[10:11], s[8:9], 12
	s_mul_i32 s9, s17, 0xa000
	s_add_u32 s10, s10, s9
	s_addc_u32 s11, s11, 0
	s_lshl_b32 s12, s58, 5
	s_ashr_i32 s13, s12, 31
	s_lshl_b32 s9, s15, 7
	s_add_u32 s9, s50, s9
	s_addc_u32 s19, s51, 0
	s_lshl_b64 s[12:13], s[12:13], 1
	v_and_b32_e32 v0, 31, v148
	s_add_u32 s12, s9, s12
	v_lshrrev_b32_e32 v1, 5, v149
	s_addc_u32 s13, s19, s13
	v_lshlrev_b32_e32 v184, 1, v0
	v_lshlrev_b32_e32 v123, 4, v1
	v_lshlrev_b32_e32 v124, 2, v1
	v_lshl_add_u64 v[0:1], s[12:13], 0, v[184:185]
	s_mov_b64 s[12:13], 0x19e00000
	v_lshl_add_u64 v[120:121], v[0:1], 0, s[12:13]
	v_mov_b32_e32 v0, 0
	v_lshlrev_b32_e32 v122, 4, v149
	s_mov_b32 s18, 0
	v_cmp_eq_u32_e64 s[4:5], 0, v149
	v_or_b32_e32 v125, -16, v124
	v_mov_b32_e32 v1, v0
	v_mov_b32_e32 v2, v0
	v_mov_b32_e32 v3, v0
	v_mov_b32_e32 v4, v0
	v_mov_b32_e32 v5, v0
	v_mov_b32_e32 v6, v0
	v_mov_b32_e32 v7, v0
	v_mov_b32_e32 v8, v0
	v_mov_b32_e32 v9, v0
	v_mov_b32_e32 v10, v0
	v_mov_b32_e32 v11, v0
	v_mov_b32_e32 v12, v0
	v_mov_b32_e32 v13, v0
	v_mov_b32_e32 v14, v0
	v_mov_b32_e32 v15, v0
	v_mov_b32_e32 v16, v0
	v_mov_b32_e32 v17, v0
	v_mov_b32_e32 v18, v0
	v_mov_b32_e32 v19, v0
	v_mov_b32_e32 v20, v0
	v_mov_b32_e32 v21, v0
	v_mov_b32_e32 v22, v0
	v_mov_b32_e32 v23, v0
	v_mov_b32_e32 v24, v0
	v_mov_b32_e32 v25, v0
	v_mov_b32_e32 v26, v0
	v_mov_b32_e32 v27, v0
	v_mov_b32_e32 v28, v0
	v_mov_b32_e32 v29, v0
	v_mov_b32_e32 v30, v0
	v_mov_b32_e32 v31, v0
	s_branch .LBB0_619

; __device__ __forceinline__ void phase_rwkv_fused(const Frame& F, const Args& a, int l) {
;     ...
;     }
; }
.LBB0_632:
	s_setprio 0
	s_mov_b64 s[4:5], 0

; #define LAS __attribute__((address_space(3)))
; __device__ __forceinline__ void transpose_item(const float* W, int ldw, int k0, int n0, bf16* WT, int Kdst, int dst_row0, LAS float* scr, int lane) {
;     float tv[32];
; #pragma unroll
;     for (int i = 0; i < 32; ++i) { const int kk = 2 * i + (lane >> 5); tv[i] = W[(size_t)(k0 + kk) * ldw + n0 + (lane & 31)]; }
; __device__ __forceinline__ void phase_wconv(const Frame& F, const Args& a, int l, unsigned char* wt, unsigned char* wth, int part) {
;     ...
;         r -= I_IN;
;         if (!(part & 2)) break;
;         if (r < I_BA) { const int kb = r / 64, nb = r % 64; transpose_item(a.in[F.z + 21] + (size_t)l * 512 * D, D, 64 * kb, 32 * nb, (bf16*)(wth + WO_BA), 512, 32 * nb, scr, F.lane); continue; }
;         r -= I_BA;
;         if (r < I_BB) { const int kb = r / 64, nb = r % 64; transpose_item(a.in[F.z + 22] + (size_t)l * 1024 * D, D, 64 * kb, 32 * nb, (bf16*)(wth + WO_BB), 1024, 32 * nb, scr, F.lane); continue; }
;         r -= I_BB;
;         if (r < I_BC) { const int kb = r / 64, nb = r % 64; transpose_item(a.in[F.z + 23] + (size_t)l * 512 * D, D, 64 * kb, 32 * nb, (bf16*)(wth + WO_BC), 512, 32 * nb, scr, F.lane); continue; }
;         r -= I_BC;
;         { const int kb = r / 64, nb = r % 64; transpose_item(a.in[F.z + 24] + (size_t)l * D * D, D, 64 * kb, 32 * nb, (bf16*)(wth + WO_OUT), D, 32 * nb, scr, F.lane); }
.LBB0_703:
	s_cmp_gt_i32 s30, 0x83ff
	s_mov_b64 s[16:17], -1
	s_cbranch_scc0 .LBB0_731
	s_cmpk_gt_u32 s30, 0xc17f
	s_cbranch_scc0 .LBB0_718
	s_cmpk_gt_u32 s30, 0xc37f
	s_cbranch_scc0 .LBB0_715
	s_cmpk_gt_u32 s30, 0xc77f
	s_cbranch_scc0 .LBB0_712
	s_and_b32 s18, s28, 0x7e0
	s_cmpk_gt_u32 s30, 0xc97f
	v_or_b32_e32 v28, s18, v21
	v_or_b32_e32 v27, s18, v23
	v_or_b32_e32 v26, s18, v24
	v_or_b32_e32 v15, s18, v25
	s_cbranch_scc0 .LBB0_709
	s_and_b32 s16, s30, 0x7fffffc0
	s_add_i32 s82, s16, 0xffff3680
	s_load_dwordx2 s[16:17], s[14:15], 0xc0
	v_readlane_b32 s20, v254, 48
	v_readlane_b32 s21, v254, 49
	v_or_b32_e32 v16, s82, v1
	v_lshlrev_b32_e32 v184, 2, v0
	s_waitcnt lgkmcnt(0)
	s_add_u32 s16, s16, s20
	s_addc_u32 s17, s17, s21
	s_lshl_b32 s19, s18, 2
	s_add_u32 s16, s16, s19
	s_addc_u32 s17, s17, 0
	v_mov_b32_e32 v17, v185
	v_lshl_add_u64 v[18:19], s[16:17], 0, v[184:185]
	v_lshlrev_b64 v[30:31], 13, v[16:17]
	v_lshl_add_u64 v[30:31], v[18:19], 0, v[30:31]
	v_or_b32_e32 v184, 2, v16
	global_load_dword v29, v[30:31], off nt
	v_lshlrev_b64 v[30:31], 13, v[184:185]
	v_lshl_add_u64 v[30:31], v[18:19], 0, v[30:31]
	v_or_b32_e32 v184, 4, v16
	global_load_dword v32, v[30:31], off nt
	v_lshlrev_b64 v[30:31], 13, v[184:185]
	v_lshl_add_u64 v[30:31], v[18:19], 0, v[30:31]
	v_or_b32_e32 v184, 6, v16
	global_load_dword v33, v[30:31], off nt
	v_lshlrev_b64 v[30:31], 13, v[184:185]
	v_lshl_add_u64 v[30:31], v[18:19], 0, v[30:31]
	v_or_b32_e32 v184, 8, v16
	global_load_dword v34, v[30:31], off nt
	v_lshlrev_b64 v[30:31], 13, v[184:185]
	v_lshl_add_u64 v[30:31], v[18:19], 0, v[30:31]
	v_or_b32_e32 v184, 10, v16
	global_load_dword v35, v[30:31], off nt
	v_lshlrev_b64 v[30:31], 13, v[184:185]
	v_lshl_add_u64 v[30:31], v[18:19], 0, v[30:31]
	v_or_b32_e32 v184, 12, v16
	global_load_dword v36, v[30:31], off nt
	v_lshlrev_b64 v[30:31], 13, v[184:185]
	v_lshl_add_u64 v[30:31], v[18:19], 0, v[30:31]
	v_or_b32_e32 v184, 14, v16
	global_load_dword v37, v[30:31], off nt
	v_lshlrev_b64 v[30:31], 13, v[184:185]
	v_lshl_add_u64 v[30:31], v[18:19], 0, v[30:31]
	v_or_b32_e32 v184, 16, v16
	global_load_dword v38, v[30:31], off nt
	v_lshlrev_b64 v[30:31], 13, v[184:185]
	v_lshl_add_u64 v[30:31], v[18:19], 0, v[30:31]
	v_or_b32_e32 v184, 18, v16
	global_load_dword v39, v[30:31], off nt
	v_lshlrev_b64 v[30:31], 13, v[184:185]
	v_lshl_add_u64 v[30:31], v[18:19], 0, v[30:31]
	v_or_b32_e32 v184, 20, v16
	global_load_dword v40, v[30:31], off nt
	v_lshlrev_b64 v[30:31], 13, v[184:185]
	v_lshl_add_u64 v[30:31], v[18:19], 0, v[30:31]
	v_or_b32_e32 v184, 22, v16
	global_load_dword v41, v[30:31], off nt
	v_lshlrev_b64 v[30:31], 13, v[184:185]
	v_lshl_add_u64 v[30:31], v[18:19], 0, v[30:31]
	v_or_b32_e32 v184, 24, v16
	global_load_dword v42, v[30:31], off nt
	v_lshlrev_b64 v[30:31], 13, v[184:185]
	v_lshl_add_u64 v[30:31], v[18:19], 0, v[30:31]
	v_or_b32_e32 v184, 26, v16
	global_load_dword v43, v[30:31], off nt
	v_lshlrev_b64 v[30:31], 13, v[184:185]
	v_lshl_add_u64 v[30:31], v[18:19], 0, v[30:31]
	v_or_b32_e32 v184, 28, v16
	global_load_dword v44, v[30:31], off nt
	v_lshlrev_b64 v[30:31], 13, v[184:185]
	v_lshl_add_u64 v[30:31], v[18:19], 0, v[30:31]
	v_or_b32_e32 v184, 30, v16
	global_load_dword v45, v[30:31], off nt
	v_lshlrev_b64 v[30:31], 13, v[184:185]
	v_lshl_add_u64 v[30:31], v[18:19], 0, v[30:31]
	v_or_b32_e32 v184, 32, v16
	global_load_dword v46, v[30:31], off nt
	v_lshlrev_b64 v[30:31], 13, v[184:185]
	v_lshl_add_u64 v[30:31], v[18:19], 0, v[30:31]
	v_or_b32_e32 v184, 34, v16
	global_load_dword v47, v[30:31], off nt
	v_lshlrev_b64 v[30:31], 13, v[184:185]
	v_lshl_add_u64 v[30:31], v[18:19], 0, v[30:31]
	v_or_b32_e32 v184, 36, v16
	global_load_dword v48, v[30:31], off nt
	v_lshlrev_b64 v[30:31], 13, v[184:185]
	v_lshl_add_u64 v[30:31], v[18:19], 0, v[30:31]
	v_or_b32_e32 v184, 38, v16
	global_load_dword v49, v[30:31], off nt
	v_lshlrev_b64 v[30:31], 13, v[184:185]
	v_lshl_add_u64 v[30:31], v[18:19], 0, v[30:31]
	v_or_b32_e32 v184, 40, v16
	global_load_dword v50, v[30:31], off nt
	v_lshlrev_b64 v[30:31], 13, v[184:185]
	v_lshl_add_u64 v[30:31], v[18:19], 0, v[30:31]
	v_or_b32_e32 v184, 42, v16
	global_load_dword v51, v[30:31], off nt
	v_lshlrev_b64 v[30:31], 13, v[184:185]
	v_lshl_add_u64 v[30:31], v[18:19], 0, v[30:31]
	v_or_b32_e32 v184, 44, v16
	global_load_dword v52, v[30:31], off nt
	v_lshlrev_b64 v[30:31], 13, v[184:185]
	v_lshl_add_u64 v[30:31], v[18:19], 0, v[30:31]
	v_or_b32_e32 v184, 46, v16
	global_load_dword v53, v[30:31], off nt
	v_lshlrev_b64 v[30:31], 13, v[184:185]
	v_lshl_add_u64 v[30:31], v[18:19], 0, v[30:31]
	v_or_b32_e32 v184, 48, v16
	global_load_dword v54, v[30:31], off nt
	v_lshlrev_b64 v[30:31], 13, v[184:185]
	v_lshl_add_u64 v[30:31], v[18:19], 0, v[30:31]
	v_or_b32_e32 v184, 50, v16
	global_load_dword v55, v[30:31], off nt
	v_lshlrev_b64 v[30:31], 13, v[184:185]
	v_lshl_add_u64 v[30:31], v[18:19], 0, v[30:31]
	v_or_b32_e32 v184, 52, v16
	global_load_dword v56, v[30:31], off nt
	v_lshlrev_b64 v[30:31], 13, v[184:185]
	v_lshl_add_u64 v[30:31], v[18:19], 0, v[30:31]
	v_or_b32_e32 v184, 54, v16
	global_load_dword v57, v[30:31], off nt
	v_lshlrev_b64 v[30:31], 13, v[184:185]
	v_lshl_add_u64 v[30:31], v[18:19], 0, v[30:31]
	v_or_b32_e32 v184, 56, v16
	global_load_dword v58, v[30:31], off nt
	v_lshlrev_b64 v[30:31], 13, v[184:185]
	v_lshl_add_u64 v[30:31], v[18:19], 0, v[30:31]
	v_or_b32_e32 v184, 58, v16
	global_load_dword v59, v[30:31], off nt
	v_lshlrev_b64 v[30:31], 13, v[184:185]
	v_lshl_add_u64 v[30:31], v[18:19], 0, v[30:31]
	v_or_b32_e32 v184, 60, v16
	global_load_dword v60, v[30:31], off nt
	v_lshlrev_b64 v[30:31], 13, v[184:185]
	v_or_b32_e32 v184, 62, v16
	v_lshlrev_b64 v[16:17], 13, v[184:185]
	v_lshl_add_u64 v[30:31], v[18:19], 0, v[30:31]
	v_lshl_add_u64 v[16:17], v[18:19], 0, v[16:17]
	global_load_dword v30, v[30:31], off nt
	v_lshlrev_b32_e32 v184, 12, v28
	global_load_dword v16, v[16:17], off nt
	v_add_u32_e32 v17, 0x400, v20
	s_waitcnt vmcnt(30)
; #define LAS __attribute__((address_space(3)))
; #define LDS_WAIT() asm volatile("s_waitcnt lgkmcnt(0)" ::: "memory")
; __device__ __forceinline__ unsigned pk2(float lo, float hi) { return cvt_pk_bf16(lo, hi); }
; __device__ __forceinline__ void transpose_item(const float* W, int ldw, int k0, int n0, bf16* WT, int Kdst, int dst_row0, LAS float* scr, int lane) {
;     float tv[32];
; #pragma unroll
;     for (int i = 0; i < 32; ++i) { const int kk = 2 * i + (lane >> 5); tv[i] = W[(size_t)(k0 + kk) * ldw + n0 + (lane & 31)]; }
; #pragma unroll
;     for (int i = 0; i < 32; ++i) { const int kk = 2 * i + (lane >> 5); scr[kk * 33 + (lane & 31)] = tv[i]; }
;     LDS_WAIT(); asm volatile("" ::: "memory");
;     const int c = lane & 7;
; #pragma unroll
;     for (int j = 0; j < 4; ++j) { const int n = (lane >> 3) + 8 * j; const LAS float* s = scr + (8 * c) * 33 + n;
;         v4u o; o.x = pk2(s[0 * 33], s[1 * 33]); o.y = pk2(s[2 * 33], s[3 * 33]); o.z = pk2(s[4 * 33], s[5 * 33]); o.w = pk2(s[6 * 33], s[7 * 33]);
;         *(v4u*)(WT + (size_t)(dst_row0 + n) * Kdst + k0 + 8 * c) = o; }
;     LDS_WAIT(); asm volatile("" ::: "memory");
; __device__ __forceinline__ void phase_wconv(const Frame& F, const Args& a, int l, unsigned char* wt, unsigned char* wth, int part) {
;     ...
;         if (r < I_BC) { const int kb = r / 64, nb = r % 64; transpose_item(a.in[F.z + 23] + (size_t)l * 512 * D, D, 64 * kb, 32 * nb, (bf16*)(wth + WO_BC), 512, 32 * nb, scr, F.lane); continue; }
	ds_write2_b32 v20, v29, v32 offset1:66
	s_waitcnt vmcnt(28)
	ds_write2_b32 v20, v33, v34 offset0:132 offset1:198
	s_waitcnt vmcnt(26)
	ds_write2_b32 v17, v35, v36 offset0:8 offset1:74
	s_waitcnt vmcnt(24)
	ds_write2_b32 v17, v37, v38 offset0:140 offset1:206
	v_add_u32_e32 v17, 0x800, v20
	s_waitcnt vmcnt(22)
	ds_write2_b32 v17, v39, v40 offset0:16 offset1:82
	s_waitcnt vmcnt(20)
	ds_write2_b32 v17, v41, v42 offset0:148 offset1:214
	v_add_u32_e32 v17, 0xc00, v20
	s_waitcnt vmcnt(18)
	ds_write2_b32 v17, v43, v44 offset0:24 offset1:90
	s_waitcnt vmcnt(16)
	ds_write2_b32 v17, v45, v46 offset0:156 offset1:222
	v_add_u32_e32 v17, 0x1000, v20
	s_waitcnt vmcnt(14)
	ds_write2_b32 v17, v47, v48 offset0:32 offset1:98
	s_waitcnt vmcnt(12)
	ds_write2_b32 v17, v49, v50 offset0:164 offset1:230
	v_add_u32_e32 v17, 0x1400, v20
	s_waitcnt vmcnt(10)
	ds_write2_b32 v17, v51, v52 offset0:40 offset1:106
	s_waitcnt vmcnt(8)
	ds_write2_b32 v17, v53, v54 offset0:172 offset1:238
	v_add_u32_e32 v17, 0x1800, v20
	s_waitcnt vmcnt(6)
	ds_write2_b32 v17, v55, v56 offset0:48 offset1:114
	s_waitcnt vmcnt(4)
	ds_write2_b32 v17, v57, v58 offset0:180 offset1:246
	v_add_u32_e32 v17, 0x1c00, v20
	s_waitcnt vmcnt(2)
	ds_write2_b32 v17, v59, v60 offset0:56 offset1:122
	s_waitcnt vmcnt(0)
	ds_write2_b32 v17, v30, v16 offset0:188 offset1:254
	s_waitcnt lgkmcnt(0)
	ds_read2_b32 v[32:33], v22 offset0:33 offset1:41
	ds_read2_b32 v[34:35], v22 offset1:8
	ds_read2_b32 v[36:37], v22 offset0:66 offset1:74
	ds_read2_b32 v[38:39], v22 offset0:99 offset1:107
	ds_read2_b32 v[40:41], v22 offset0:132 offset1:140
	ds_read2_b32 v[42:43], v22 offset0:165 offset1:173
	ds_read2_b32 v[44:45], v22 offset0:198 offset1:206
	ds_read2_b32 v[46:47], v22 offset0:231 offset1:239
	v_lshl_add_u64 v[30:31], s[82:83], 1, v[2:3]
	s_waitcnt lgkmcnt(6)
	v_cvt_pk_bf16_f32 v16, v34, v32
	s_waitcnt lgkmcnt(4)
	v_cvt_pk_bf16_f32 v17, v36, v38
	s_waitcnt lgkmcnt(2)
	v_cvt_pk_bf16_f32 v18, v40, v42
	s_waitcnt lgkmcnt(0)
	v_cvt_pk_bf16_f32 v19, v44, v46
	v_lshl_add_u64 v[48:49], v[30:31], 0, v[184:185]
	v_lshlrev_b32_e32 v184, 12, v27
	global_store_dwordx4 v[48:49], v[16:19], off
	s_mov_b64 s[16:17], 0
	s_nop 0
	v_cvt_pk_bf16_f32 v16, v35, v33
	v_cvt_pk_bf16_f32 v17, v37, v39
	v_cvt_pk_bf16_f32 v18, v41, v43
	v_cvt_pk_bf16_f32 v19, v45, v47
	v_lshl_add_u64 v[32:33], v[30:31], 0, v[184:185]
	global_store_dwordx4 v[32:33], v[16:19], off
	ds_read2_b32 v[32:33], v22 offset0:49 offset1:57
	ds_read2_b32 v[34:35], v22 offset0:16 offset1:24
	ds_read2_b32 v[36:37], v22 offset0:82 offset1:90
	ds_read2_b32 v[38:39], v22 offset0:115 offset1:123
	ds_read2_b32 v[40:41], v22 offset0:148 offset1:156
	ds_read2_b32 v[42:43], v22 offset0:181 offset1:189
	ds_read2_b32 v[44:45], v22 offset0:214 offset1:222
	ds_read2_b32 v[46:47], v22 offset0:247 offset1:255
	v_lshlrev_b32_e32 v184, 12, v26
	s_waitcnt lgkmcnt(6)
	v_cvt_pk_bf16_f32 v16, v34, v32
	s_waitcnt lgkmcnt(4)
	v_cvt_pk_bf16_f32 v17, v36, v38
	s_waitcnt lgkmcnt(2)
	v_cvt_pk_bf16_f32 v18, v40, v42
	s_waitcnt lgkmcnt(0)
	v_cvt_pk_bf16_f32 v19, v44, v46
	v_lshl_add_u64 v[48:49], v[30:31], 0, v[184:185]
	v_lshlrev_b32_e32 v184, 12, v15
	global_store_dwordx4 v[48:49], v[16:19], off
	v_lshl_add_u64 v[30:31], v[30:31], 0, v[184:185]
	s_nop 0
	v_cvt_pk_bf16_f32 v16, v35, v33
	v_cvt_pk_bf16_f32 v17, v37, v39
	v_cvt_pk_bf16_f32 v18, v41, v43
	v_cvt_pk_bf16_f32 v19, v45, v47
	global_store_dwordx4 v[30:31], v[16:19], off
	s_waitcnt lgkmcnt(0)
.LBB0_709:
	s_andn2_b64 vcc, exec, s[16:17]
	s_cbranch_vccnz .LBB0_711
	s_and_b32 s16, s30, 0xffc0
	s_add_i32 s82, s16, 0xffff3880
	s_load_dwordx2 s[16:17], s[14:15], 0xb8
	v_readlane_b32 s20, v254, 36
	v_readlane_b32 s21, v254, 37
	s_lshl_b64 s[20:21], s[20:21], 2
	v_or_b32_e32 v16, s82, v1
	s_waitcnt lgkmcnt(0)
	s_add_u32 s16, s16, s20
	s_addc_u32 s17, s17, s21
	s_lshl_b32 s18, s18, 2
	s_add_u32 s16, s16, s18
	s_addc_u32 s17, s17, 0
	v_lshlrev_b32_e32 v184, 2, v0
	v_mov_b32_e32 v17, v185
	v_lshl_add_u64 v[18:19], s[16:17], 0, v[184:185]
	v_lshlrev_b64 v[30:31], 13, v[16:17]
	v_lshl_add_u64 v[30:31], v[18:19], 0, v[30:31]
	v_or_b32_e32 v184, 2, v16
	global_load_dword v29, v[30:31], off nt
	v_lshlrev_b64 v[30:31], 13, v[184:185]
	v_lshl_add_u64 v[30:31], v[18:19], 0, v[30:31]
	v_or_b32_e32 v184, 4, v16
	global_load_dword v32, v[30:31], off nt
	v_lshlrev_b64 v[30:31], 13, v[184:185]
	v_lshl_add_u64 v[30:31], v[18:19], 0, v[30:31]
	v_or_b32_e32 v184, 6, v16
	global_load_dword v33, v[30:31], off nt
	v_lshlrev_b64 v[30:31], 13, v[184:185]
	v_lshl_add_u64 v[30:31], v[18:19], 0, v[30:31]
	v_or_b32_e32 v184, 8, v16
	global_load_dword v34, v[30:31], off nt
	v_lshlrev_b64 v[30:31], 13, v[184:185]
	v_lshl_add_u64 v[30:31], v[18:19], 0, v[30:31]
	v_or_b32_e32 v184, 10, v16
	global_load_dword v35, v[30:31], off nt
	v_lshlrev_b64 v[30:31], 13, v[184:185]
	v_lshl_add_u64 v[30:31], v[18:19], 0, v[30:31]
	v_or_b32_e32 v184, 12, v16
	global_load_dword v36, v[30:31], off nt
	v_lshlrev_b64 v[30:31], 13, v[184:185]
	v_lshl_add_u64 v[30:31], v[18:19], 0, v[30:31]
	v_or_b32_e32 v184, 14, v16
	global_load_dword v37, v[30:31], off nt
	v_lshlrev_b64 v[30:31], 13, v[184:185]
	v_lshl_add_u64 v[30:31], v[18:19], 0, v[30:31]
	v_or_b32_e32 v184, 16, v16
	global_load_dword v38, v[30:31], off nt
	v_lshlrev_b64 v[30:31], 13, v[184:185]
	v_lshl_add_u64 v[30:31], v[18:19], 0, v[30:31]
	v_or_b32_e32 v184, 18, v16
	global_load_dword v39, v[30:31], off nt
	v_lshlrev_b64 v[30:31], 13, v[184:185]
	v_lshl_add_u64 v[30:31], v[18:19], 0, v[30:31]
	v_or_b32_e32 v184, 20, v16
	global_load_dword v40, v[30:31], off nt
	v_lshlrev_b64 v[30:31], 13, v[184:185]
	v_lshl_add_u64 v[30:31], v[18:19], 0, v[30:31]
; #define LAS __attribute__((address_space(3)))
; #define LDS_WAIT() asm volatile("s_waitcnt lgkmcnt(0)" ::: "memory")
; __device__ __forceinline__ unsigned pk2(float lo, float hi) { return cvt_pk_bf16(lo, hi); }
; __device__ __forceinline__ void transpose_item(const float* W, int ldw, int k0, int n0, bf16* WT, int Kdst, int dst_row0, LAS float* scr, int lane) {
;     float tv[32];
; #pragma unroll
;     for (int i = 0; i < 32; ++i) { const int kk = 2 * i + (lane >> 5); tv[i] = W[(size_t)(k0 + kk) * ldw + n0 + (lane & 31)]; }
; #pragma unroll
;     for (int i = 0; i < 32; ++i) { const int kk = 2 * i + (lane >> 5); scr[kk * 33 + (lane & 31)] = tv[i]; }
;     LDS_WAIT(); asm volatile("" ::: "memory");
;     const int c = lane & 7;
; #pragma unroll
;     for (int j = 0; j < 4; ++j) { const int n = (lane >> 3) + 8 * j; const LAS float* s = scr + (8 * c) * 33 + n;
;         v4u o; o.x = pk2(s[0 * 33], s[1 * 33]); o.y = pk2(s[2 * 33], s[3 * 33]); o.z = pk2(s[4 * 33], s[5 * 33]); o.w = pk2(s[6 * 33], s[7 * 33]);
;         *(v4u*)(WT + (size_t)(dst_row0 + n) * Kdst + k0 + 8 * c) = o; }
;     LDS_WAIT(); asm volatile("" ::: "memory");
	v_or_b32_e32 v184, 22, v16
	global_load_dword v41, v[30:31], off nt
	v_lshlrev_b64 v[30:31], 13, v[184:185]
	v_lshl_add_u64 v[30:31], v[18:19], 0, v[30:31]
	v_or_b32_e32 v184, 24, v16
	global_load_dword v42, v[30:31], off nt
	v_lshlrev_b64 v[30:31], 13, v[184:185]
	v_lshl_add_u64 v[30:31], v[18:19], 0, v[30:31]
	v_or_b32_e32 v184, 26, v16
	global_load_dword v43, v[30:31], off nt
	v_lshlrev_b64 v[30:31], 13, v[184:185]
	v_lshl_add_u64 v[30:31], v[18:19], 0, v[30:31]
	v_or_b32_e32 v184, 28, v16
	global_load_dword v44, v[30:31], off nt
	v_lshlrev_b64 v[30:31], 13, v[184:185]
	v_lshl_add_u64 v[30:31], v[18:19], 0, v[30:31]
	v_or_b32_e32 v184, 30, v16
	global_load_dword v45, v[30:31], off nt
	v_lshlrev_b64 v[30:31], 13, v[184:185]
	v_lshl_add_u64 v[30:31], v[18:19], 0, v[30:31]
	v_or_b32_e32 v184, 32, v16
	global_load_dword v46, v[30:31], off nt
	v_lshlrev_b64 v[30:31], 13, v[184:185]
	v_lshl_add_u64 v[30:31], v[18:19], 0, v[30:31]
	v_or_b32_e32 v184, 34, v16
	global_load_dword v47, v[30:31], off nt
	v_lshlrev_b64 v[30:31], 13, v[184:185]
	v_lshl_add_u64 v[30:31], v[18:19], 0, v[30:31]
	v_or_b32_e32 v184, 36, v16
	global_load_dword v48, v[30:31], off nt
	v_lshlrev_b64 v[30:31], 13, v[184:185]
	v_lshl_add_u64 v[30:31], v[18:19], 0, v[30:31]
	v_or_b32_e32 v184, 38, v16
	global_load_dword v49, v[30:31], off nt
	v_lshlrev_b64 v[30:31], 13, v[184:185]
	v_lshl_add_u64 v[30:31], v[18:19], 0, v[30:31]
	v_or_b32_e32 v184, 40, v16
	global_load_dword v50, v[30:31], off nt
	v_lshlrev_b64 v[30:31], 13, v[184:185]
	v_lshl_add_u64 v[30:31], v[18:19], 0, v[30:31]
	v_or_b32_e32 v184, 42, v16
	global_load_dword v51, v[30:31], off nt
	v_lshlrev_b64 v[30:31], 13, v[184:185]
	v_lshl_add_u64 v[30:31], v[18:19], 0, v[30:31]
	v_or_b32_e32 v184, 44, v16
	global_load_dword v52, v[30:31], off nt
	v_lshlrev_b64 v[30:31], 13, v[184:185]
	v_lshl_add_u64 v[30:31], v[18:19], 0, v[30:31]
	v_or_b32_e32 v184, 46, v16
	global_load_dword v53, v[30:31], off nt
	v_lshlrev_b64 v[30:31], 13, v[184:185]
	v_lshl_add_u64 v[30:31], v[18:19], 0, v[30:31]
	v_or_b32_e32 v184, 48, v16
	global_load_dword v54, v[30:31], off nt
	v_lshlrev_b64 v[30:31], 13, v[184:185]
	v_lshl_add_u64 v[30:31], v[18:19], 0, v[30:31]
	v_or_b32_e32 v184, 50, v16
	global_load_dword v55, v[30:31], off nt
	v_lshlrev_b64 v[30:31], 13, v[184:185]
	v_lshl_add_u64 v[30:31], v[18:19], 0, v[30:31]
	v_or_b32_e32 v184, 52, v16
	global_load_dword v56, v[30:31], off nt
	v_lshlrev_b64 v[30:31], 13, v[184:185]
	v_lshl_add_u64 v[30:31], v[18:19], 0, v[30:31]
	v_or_b32_e32 v184, 54, v16
	global_load_dword v57, v[30:31], off nt
	v_lshlrev_b64 v[30:31], 13, v[184:185]
	v_lshl_add_u64 v[30:31], v[18:19], 0, v[30:31]
	v_or_b32_e32 v184, 56, v16
	global_load_dword v58, v[30:31], off nt
	v_lshlrev_b64 v[30:31], 13, v[184:185]
	v_lshl_add_u64 v[30:31], v[18:19], 0, v[30:31]
	v_or_b32_e32 v184, 58, v16
	global_load_dword v59, v[30:31], off nt
	v_lshlrev_b64 v[30:31], 13, v[184:185]
	v_lshl_add_u64 v[30:31], v[18:19], 0, v[30:31]
	v_or_b32_e32 v184, 60, v16
	global_load_dword v60, v[30:31], off nt
	v_lshlrev_b64 v[30:31], 13, v[184:185]
	v_or_b32_e32 v184, 62, v16
	v_lshlrev_b64 v[16:17], 13, v[184:185]
	v_lshl_add_u64 v[30:31], v[18:19], 0, v[30:31]
	v_lshl_add_u64 v[16:17], v[18:19], 0, v[16:17]
	global_load_dword v30, v[30:31], off nt
	v_lshlrev_b32_e32 v184, 10, v28
	global_load_dword v16, v[16:17], off nt
	v_add_u32_e32 v17, 0x400, v20
	s_waitcnt vmcnt(30)
	ds_write2_b32 v20, v29, v32 offset1:66
	s_waitcnt vmcnt(28)
	ds_write2_b32 v20, v33, v34 offset0:132 offset1:198
	s_waitcnt vmcnt(26)
	ds_write2_b32 v17, v35, v36 offset0:8 offset1:74
	s_waitcnt vmcnt(24)
	ds_write2_b32 v17, v37, v38 offset0:140 offset1:206
	v_add_u32_e32 v17, 0x800, v20
	s_waitcnt vmcnt(22)
	ds_write2_b32 v17, v39, v40 offset0:16 offset1:82
	s_waitcnt vmcnt(20)
	ds_write2_b32 v17, v41, v42 offset0:148 offset1:214
	v_add_u32_e32 v17, 0xc00, v20
	s_waitcnt vmcnt(18)
	ds_write2_b32 v17, v43, v44 offset0:24 offset1:90
	s_waitcnt vmcnt(16)
	ds_write2_b32 v17, v45, v46 offset0:156 offset1:222
	v_add_u32_e32 v17, 0x1000, v20
	s_waitcnt vmcnt(14)
	ds_write2_b32 v17, v47, v48 offset0:32 offset1:98
	s_waitcnt vmcnt(12)
	ds_write2_b32 v17, v49, v50 offset0:164 offset1:230
	v_add_u32_e32 v17, 0x1400, v20
	s_waitcnt vmcnt(10)
	ds_write2_b32 v17, v51, v52 offset0:40 offset1:106
	s_waitcnt vmcnt(8)
	ds_write2_b32 v17, v53, v54 offset0:172 offset1:238
	v_add_u32_e32 v17, 0x1800, v20
	s_waitcnt vmcnt(6)
	ds_write2_b32 v17, v55, v56 offset0:48 offset1:114
	s_waitcnt vmcnt(4)
	ds_write2_b32 v17, v57, v58 offset0:180 offset1:246
	v_add_u32_e32 v17, 0x1c00, v20
	s_waitcnt vmcnt(2)
	ds_write2_b32 v17, v59, v60 offset0:56 offset1:122
	s_waitcnt vmcnt(0)
	ds_write2_b32 v17, v30, v16 offset0:188 offset1:254
	s_waitcnt lgkmcnt(0)
	ds_read2_b32 v[32:33], v22 offset0:33 offset1:41
	ds_read2_b32 v[34:35], v22 offset1:8
	ds_read2_b32 v[36:37], v22 offset0:66 offset1:74
	ds_read2_b32 v[38:39], v22 offset0:99 offset1:107
	ds_read2_b32 v[40:41], v22 offset0:132 offset1:140
	ds_read2_b32 v[42:43], v22 offset0:165 offset1:173
	ds_read2_b32 v[44:45], v22 offset0:198 offset1:206
	ds_read2_b32 v[46:47], v22 offset0:231 offset1:239
	v_lshl_add_u64 v[30:31], s[82:83], 1, v[4:5]
	s_waitcnt lgkmcnt(6)
	v_cvt_pk_bf16_f32 v16, v34, v32
	s_waitcnt lgkmcnt(4)
	v_cvt_pk_bf16_f32 v17, v36, v38
	s_waitcnt lgkmcnt(2)
	v_cvt_pk_bf16_f32 v18, v40, v42
	s_waitcnt lgkmcnt(0)
	v_cvt_pk_bf16_f32 v19, v44, v46
	v_lshl_add_u64 v[28:29], v[30:31], 0, v[184:185]
	v_lshlrev_b32_e32 v184, 10, v27
	global_store_dwordx4 v[28:29], v[16:19], off
	v_lshl_add_u64 v[28:29], v[30:31], 0, v[184:185]
	v_lshlrev_b32_e32 v184, 10, v26
	v_cvt_pk_bf16_f32 v16, v35, v33
	v_cvt_pk_bf16_f32 v17, v37, v39
	v_cvt_pk_bf16_f32 v18, v41, v43
	v_cvt_pk_bf16_f32 v19, v45, v47
	global_store_dwordx4 v[28:29], v[16:19], off
	ds_read2_b32 v[28:29], v22 offset0:49 offset1:57
	ds_read2_b32 v[32:33], v22 offset0:16 offset1:24
	ds_read2_b32 v[34:35], v22 offset0:82 offset1:90
	ds_read2_b32 v[36:37], v22 offset0:115 offset1:123
	ds_read2_b32 v[38:39], v22 offset0:148 offset1:156
	ds_read2_b32 v[40:41], v22 offset0:181 offset1:189
	ds_read2_b32 v[42:43], v22 offset0:214 offset1:222
	ds_read2_b32 v[44:45], v22 offset0:247 offset1:255
	v_lshl_add_u64 v[26:27], v[30:31], 0, v[184:185]
	s_waitcnt lgkmcnt(6)
	v_cvt_pk_bf16_f32 v16, v32, v28
	s_waitcnt lgkmcnt(4)
	v_cvt_pk_bf16_f32 v17, v34, v36
	s_waitcnt lgkmcnt(2)
	v_cvt_pk_bf16_f32 v18, v38, v40
	s_waitcnt lgkmcnt(0)
	v_cvt_pk_bf16_f32 v19, v42, v44
	v_lshlrev_b32_e32 v184, 10, v15
	global_store_dwordx4 v[26:27], v[16:19], off
	v_lshl_add_u64 v[26:27], v[30:31], 0, v[184:185]
	s_nop 0
	v_cvt_pk_bf16_f32 v16, v33, v29
	v_cvt_pk_bf16_f32 v17, v35, v37
	v_cvt_pk_bf16_f32 v18, v39, v41
	v_cvt_pk_bf16_f32 v19, v43, v45
	global_store_dwordx4 v[26:27], v[16:19], off
	s_waitcnt lgkmcnt(0)

; #define LAS __attribute__((address_space(3)))
; __device__ __forceinline__ void transpose_item(const float* W, int ldw, int k0, int n0, bf16* WT, int Kdst, int dst_row0, LAS float* scr, int lane) {
;     float tv[32];
; #pragma unroll
;     for (int i = 0; i < 32; ++i) { const int kk = 2 * i + (lane >> 5); tv[i] = W[(size_t)(k0 + kk) * ldw + n0 + (lane & 31)]; }
; __device__ __forceinline__ void phase_wconv(const Frame& F, const Args& a, int l, unsigned char* wt, unsigned char* wth, int part) {
;     ...
;         if (r < I_BB) { const int kb = r / 64, nb = r % 64; transpose_item(a.in[F.z + 22] + (size_t)l * 1024 * D, D, 64 * kb, 32 * nb, (bf16*)(wth + WO_BB), 1024, 32 * nb, scr, F.lane); continue; }
.LBB0_712:
	s_andn2_b64 vcc, exec, s[16:17]
	s_cbranch_vccnz .LBB0_714
	s_and_b32 s16, s30, 0xffc0
	s_add_i32 s82, s16, 0xffff3c80
	s_load_dwordx2 s[16:17], s[14:15], 0xb0
	v_readlane_b32 s18, v254, 50
	v_readlane_b32 s19, v254, 51
	v_or_b32_e32 v16, s82, v1
	v_lshlrev_b32_e32 v184, 2, v0
	s_waitcnt lgkmcnt(0)
	s_add_u32 s18, s16, s18
	s_addc_u32 s17, s17, s19
	s_and_b32 s16, s28, 0x7e0
	s_lshl_b32 s19, s16, 2
	s_add_u32 s18, s18, s19
	s_addc_u32 s19, s17, 0
	v_mov_b32_e32 v17, v185
	v_lshl_add_u64 v[18:19], s[18:19], 0, v[184:185]
	v_lshlrev_b64 v[26:27], 13, v[16:17]
	v_lshl_add_u64 v[26:27], v[18:19], 0, v[26:27]
	v_or_b32_e32 v184, 2, v16
	global_load_dword v15, v[26:27], off nt
	v_lshlrev_b64 v[26:27], 13, v[184:185]
	v_lshl_add_u64 v[26:27], v[18:19], 0, v[26:27]
	v_or_b32_e32 v184, 4, v16
	global_load_dword v28, v[26:27], off nt
	v_lshlrev_b64 v[26:27], 13, v[184:185]
	v_lshl_add_u64 v[26:27], v[18:19], 0, v[26:27]
	v_or_b32_e32 v184, 6, v16
	global_load_dword v29, v[26:27], off nt
	v_lshlrev_b64 v[26:27], 13, v[184:185]
	v_lshl_add_u64 v[26:27], v[18:19], 0, v[26:27]
	v_or_b32_e32 v184, 8, v16
	global_load_dword v30, v[26:27], off nt
	v_lshlrev_b64 v[26:27], 13, v[184:185]
	v_lshl_add_u64 v[26:27], v[18:19], 0, v[26:27]
	v_or_b32_e32 v184, 10, v16
	global_load_dword v31, v[26:27], off nt
	v_lshlrev_b64 v[26:27], 13, v[184:185]
	v_lshl_add_u64 v[26:27], v[18:19], 0, v[26:27]
	v_or_b32_e32 v184, 12, v16
	global_load_dword v32, v[26:27], off nt
	v_lshlrev_b64 v[26:27], 13, v[184:185]
	v_lshl_add_u64 v[26:27], v[18:19], 0, v[26:27]
	v_or_b32_e32 v184, 14, v16
	global_load_dword v33, v[26:27], off nt
	v_lshlrev_b64 v[26:27], 13, v[184:185]
	v_lshl_add_u64 v[26:27], v[18:19], 0, v[26:27]
	v_or_b32_e32 v184, 16, v16
	global_load_dword v34, v[26:27], off nt
	v_lshlrev_b64 v[26:27], 13, v[184:185]
	v_lshl_add_u64 v[26:27], v[18:19], 0, v[26:27]
	v_or_b32_e32 v184, 18, v16
	global_load_dword v35, v[26:27], off nt
	v_lshlrev_b64 v[26:27], 13, v[184:185]
	v_lshl_add_u64 v[26:27], v[18:19], 0, v[26:27]
	v_or_b32_e32 v184, 20, v16
	global_load_dword v36, v[26:27], off nt
	v_lshlrev_b64 v[26:27], 13, v[184:185]
	v_lshl_add_u64 v[26:27], v[18:19], 0, v[26:27]
	v_or_b32_e32 v184, 22, v16
	global_load_dword v37, v[26:27], off nt
	v_lshlrev_b64 v[26:27], 13, v[184:185]
	v_lshl_add_u64 v[26:27], v[18:19], 0, v[26:27]
	v_or_b32_e32 v184, 24, v16
	global_load_dword v38, v[26:27], off nt
	v_lshlrev_b64 v[26:27], 13, v[184:185]
	v_lshl_add_u64 v[26:27], v[18:19], 0, v[26:27]
	v_or_b32_e32 v184, 26, v16
	global_load_dword v39, v[26:27], off nt
	v_lshlrev_b64 v[26:27], 13, v[184:185]
	v_lshl_add_u64 v[26:27], v[18:19], 0, v[26:27]
	v_or_b32_e32 v184, 28, v16
	global_load_dword v40, v[26:27], off nt
	v_lshlrev_b64 v[26:27], 13, v[184:185]
	v_lshl_add_u64 v[26:27], v[18:19], 0, v[26:27]
	v_or_b32_e32 v184, 30, v16
	global_load_dword v41, v[26:27], off nt
	v_lshlrev_b64 v[26:27], 13, v[184:185]
	v_lshl_add_u64 v[26:27], v[18:19], 0, v[26:27]
	v_or_b32_e32 v184, 32, v16
	global_load_dword v42, v[26:27], off nt
	v_lshlrev_b64 v[26:27], 13, v[184:185]
	v_lshl_add_u64 v[26:27], v[18:19], 0, v[26:27]
	v_or_b32_e32 v184, 34, v16
	global_load_dword v43, v[26:27], off nt
	v_lshlrev_b64 v[26:27], 13, v[184:185]
	v_lshl_add_u64 v[26:27], v[18:19], 0, v[26:27]
	v_or_b32_e32 v184, 36, v16
	global_load_dword v44, v[26:27], off nt
	v_lshlrev_b64 v[26:27], 13, v[184:185]
	v_lshl_add_u64 v[26:27], v[18:19], 0, v[26:27]
	v_or_b32_e32 v184, 38, v16
	global_load_dword v45, v[26:27], off nt
	v_lshlrev_b64 v[26:27], 13, v[184:185]
	v_lshl_add_u64 v[26:27], v[18:19], 0, v[26:27]
	v_or_b32_e32 v184, 40, v16
	global_load_dword v46, v[26:27], off nt
	v_lshlrev_b64 v[26:27], 13, v[184:185]
	v_lshl_add_u64 v[26:27], v[18:19], 0, v[26:27]
	v_or_b32_e32 v184, 42, v16
	global_load_dword v47, v[26:27], off nt
	v_lshlrev_b64 v[26:27], 13, v[184:185]
	v_lshl_add_u64 v[26:27], v[18:19], 0, v[26:27]
	v_or_b32_e32 v184, 44, v16
	global_load_dword v48, v[26:27], off nt
	v_lshlrev_b64 v[26:27], 13, v[184:185]
	v_lshl_add_u64 v[26:27], v[18:19], 0, v[26:27]
	v_or_b32_e32 v184, 46, v16
	global_load_dword v49, v[26:27], off nt
	v_lshlrev_b64 v[26:27], 13, v[184:185]
	v_lshl_add_u64 v[26:27], v[18:19], 0, v[26:27]
	v_or_b32_e32 v184, 48, v16
	global_load_dword v50, v[26:27], off nt
	v_lshlrev_b64 v[26:27], 13, v[184:185]
	v_lshl_add_u64 v[26:27], v[18:19], 0, v[26:27]
	v_or_b32_e32 v184, 50, v16
	global_load_dword v51, v[26:27], off nt
	v_lshlrev_b64 v[26:27], 13, v[184:185]
	v_lshl_add_u64 v[26:27], v[18:19], 0, v[26:27]
	v_or_b32_e32 v184, 52, v16
	global_load_dword v52, v[26:27], off nt
	v_lshlrev_b64 v[26:27], 13, v[184:185]
	v_lshl_add_u64 v[26:27], v[18:19], 0, v[26:27]
	v_or_b32_e32 v184, 54, v16
	global_load_dword v53, v[26:27], off nt
	v_lshlrev_b64 v[26:27], 13, v[184:185]
	v_lshl_add_u64 v[26:27], v[18:19], 0, v[26:27]
	v_or_b32_e32 v184, 56, v16
	global_load_dword v54, v[26:27], off nt
	v_lshlrev_b64 v[26:27], 13, v[184:185]
	v_lshl_add_u64 v[26:27], v[18:19], 0, v[26:27]
	v_or_b32_e32 v184, 58, v16
	global_load_dword v55, v[26:27], off nt
	v_lshlrev_b64 v[26:27], 13, v[184:185]
	v_lshl_add_u64 v[26:27], v[18:19], 0, v[26:27]
	v_or_b32_e32 v184, 60, v16
	global_load_dword v56, v[26:27], off nt
	v_lshlrev_b64 v[26:27], 13, v[184:185]
	v_or_b32_e32 v184, 62, v16
	v_lshlrev_b64 v[16:17], 13, v[184:185]
	v_lshl_add_u64 v[26:27], v[18:19], 0, v[26:27]
	v_lshl_add_u64 v[16:17], v[18:19], 0, v[16:17]
	global_load_dword v26, v[26:27], off nt
	s_nop 0
	global_load_dword v16, v[16:17], off nt
	s_waitcnt vmcnt(30)
; #define LAS __attribute__((address_space(3)))
; #define LDS_WAIT() asm volatile("s_waitcnt lgkmcnt(0)" ::: "memory")
; __device__ __forceinline__ unsigned pk2(float lo, float hi) { return cvt_pk_bf16(lo, hi); }
; __device__ __forceinline__ void transpose_item(const float* W, int ldw, int k0, int n0, bf16* WT, int Kdst, int dst_row0, LAS float* scr, int lane) {
;     ...
;     for (int i = 0; i < 32; ++i) { const int kk = 2 * i + (lane >> 5); scr[kk * 33 + (lane & 31)] = tv[i]; }
;     LDS_WAIT(); asm volatile("" ::: "memory");
;     const int c = lane & 7;
; #pragma unroll
;     for (int j = 0; j < 4; ++j) { const int n = (lane >> 3) + 8 * j; const LAS float* s = scr + (8 * c) * 33 + n;
;         v4u o; o.x = pk2(s[0 * 33], s[1 * 33]); o.y = pk2(s[2 * 33], s[3 * 33]); o.z = pk2(s[4 * 33], s[5 * 33]); o.w = pk2(s[6 * 33], s[7 * 33]);
;         *(v4u*)(WT + (size_t)(dst_row0 + n) * Kdst + k0 + 8 * c) = o; }
;     LDS_WAIT(); asm volatile("" ::: "memory");
	ds_write2_b32 v20, v15, v28 offset1:66
	s_waitcnt vmcnt(28)
	ds_write2_b32 v20, v29, v30 offset0:132 offset1:198
	v_add_u32_e32 v15, 0x400, v20
	s_waitcnt vmcnt(26)
	ds_write2_b32 v15, v31, v32 offset0:8 offset1:74
	s_waitcnt vmcnt(24)
	ds_write2_b32 v15, v33, v34 offset0:140 offset1:206
	v_add_u32_e32 v15, 0x800, v20
	s_waitcnt vmcnt(22)
	ds_write2_b32 v15, v35, v36 offset0:16 offset1:82
	s_waitcnt vmcnt(20)
	ds_write2_b32 v15, v37, v38 offset0:148 offset1:214
	v_add_u32_e32 v15, 0xc00, v20
	s_waitcnt vmcnt(18)
	ds_write2_b32 v15, v39, v40 offset0:24 offset1:90
	s_waitcnt vmcnt(16)
	ds_write2_b32 v15, v41, v42 offset0:156 offset1:222
	v_add_u32_e32 v15, 0x1000, v20
	s_waitcnt vmcnt(14)
	ds_write2_b32 v15, v43, v44 offset0:32 offset1:98
	s_waitcnt vmcnt(12)
	ds_write2_b32 v15, v45, v46 offset0:164 offset1:230
	v_add_u32_e32 v15, 0x1400, v20
	s_waitcnt vmcnt(10)
	ds_write2_b32 v15, v47, v48 offset0:40 offset1:106
	s_waitcnt vmcnt(8)
	ds_write2_b32 v15, v49, v50 offset0:172 offset1:238
	v_add_u32_e32 v15, 0x1800, v20
	s_waitcnt vmcnt(6)
	ds_write2_b32 v15, v51, v52 offset0:48 offset1:114
	s_waitcnt vmcnt(4)
	ds_write2_b32 v15, v53, v54 offset0:180 offset1:246
	v_add_u32_e32 v15, 0x1c00, v20
	s_waitcnt vmcnt(2)
	ds_write2_b32 v15, v55, v56 offset0:56 offset1:122
	s_waitcnt vmcnt(0)
	ds_write2_b32 v15, v26, v16 offset0:188 offset1:254
	s_waitcnt lgkmcnt(0)
	ds_read2_b32 v[28:29], v22 offset0:33 offset1:41
	ds_read2_b32 v[30:31], v22 offset1:8
	ds_read2_b32 v[32:33], v22 offset0:66 offset1:74
	ds_read2_b32 v[34:35], v22 offset0:99 offset1:107
	ds_read2_b32 v[36:37], v22 offset0:132 offset1:140
	ds_read2_b32 v[38:39], v22 offset0:165 offset1:173
	ds_read2_b32 v[40:41], v22 offset0:198 offset1:206
	ds_read2_b32 v[42:43], v22 offset0:231 offset1:239
	v_or_b32_e32 v15, s16, v21
	v_lshl_add_u64 v[26:27], s[82:83], 1, v[6:7]
	v_lshlrev_b32_e32 v184, 11, v15
	v_or_b32_e32 v15, s16, v23
	s_waitcnt lgkmcnt(6)
	v_cvt_pk_bf16_f32 v16, v30, v28
	s_waitcnt lgkmcnt(4)
	v_cvt_pk_bf16_f32 v17, v32, v34
	s_waitcnt lgkmcnt(2)
	v_cvt_pk_bf16_f32 v18, v36, v38
	s_waitcnt lgkmcnt(0)
	v_cvt_pk_bf16_f32 v19, v40, v42
	v_lshl_add_u64 v[44:45], v[26:27], 0, v[184:185]
	v_lshlrev_b32_e32 v184, 11, v15
	global_store_dwordx4 v[44:45], v[16:19], off
	v_or_b32_e32 v15, s16, v24
	s_nop 0
	v_cvt_pk_bf16_f32 v16, v31, v29
	v_cvt_pk_bf16_f32 v17, v33, v35
	v_cvt_pk_bf16_f32 v18, v37, v39
	v_cvt_pk_bf16_f32 v19, v41, v43
	v_lshl_add_u64 v[28:29], v[26:27], 0, v[184:185]
	global_store_dwordx4 v[28:29], v[16:19], off
	ds_read2_b32 v[28:29], v22 offset0:49 offset1:57
	ds_read2_b32 v[30:31], v22 offset0:16 offset1:24
	ds_read2_b32 v[32:33], v22 offset0:82 offset1:90
	ds_read2_b32 v[34:35], v22 offset0:115 offset1:123
	ds_read2_b32 v[36:37], v22 offset0:148 offset1:156
	ds_read2_b32 v[38:39], v22 offset0:181 offset1:189
	ds_read2_b32 v[40:41], v22 offset0:214 offset1:222
	ds_read2_b32 v[42:43], v22 offset0:247 offset1:255
	v_lshlrev_b32_e32 v184, 11, v15
	v_or_b32_e32 v15, s16, v25
	s_waitcnt lgkmcnt(6)
	v_cvt_pk_bf16_f32 v16, v30, v28
	s_waitcnt lgkmcnt(4)
	v_cvt_pk_bf16_f32 v17, v32, v34
	s_waitcnt lgkmcnt(2)
	v_cvt_pk_bf16_f32 v18, v36, v38
	s_waitcnt lgkmcnt(0)
	v_cvt_pk_bf16_f32 v19, v40, v42
	v_lshl_add_u64 v[44:45], v[26:27], 0, v[184:185]
	v_lshlrev_b32_e32 v184, 11, v15
	global_store_dwordx4 v[44:45], v[16:19], off
	v_lshl_add_u64 v[26:27], v[26:27], 0, v[184:185]
	s_nop 0
	v_cvt_pk_bf16_f32 v16, v31, v29
	v_cvt_pk_bf16_f32 v17, v33, v35
	v_cvt_pk_bf16_f32 v18, v37, v39
	v_cvt_pk_bf16_f32 v19, v41, v43
	global_store_dwordx4 v[26:27], v[16:19], off
	s_waitcnt lgkmcnt(0)

; #define LAS __attribute__((address_space(3)))
; __device__ __forceinline__ void transpose_item(const float* W, int ldw, int k0, int n0, bf16* WT, int Kdst, int dst_row0, LAS float* scr, int lane) {
;     float tv[32];
; #pragma unroll
;     for (int i = 0; i < 32; ++i) { const int kk = 2 * i + (lane >> 5); tv[i] = W[(size_t)(k0 + kk) * ldw + n0 + (lane & 31)]; }
; __device__ __forceinline__ void phase_wconv(const Frame& F, const Args& a, int l, unsigned char* wt, unsigned char* wth, int part) {
;     ...
;         if (r < I_BA) { const int kb = r / 64, nb = r % 64; transpose_item(a.in[F.z + 21] + (size_t)l * 512 * D, D, 64 * kb, 32 * nb, (bf16*)(wth + WO_BA), 512, 32 * nb, scr, F.lane); continue; }
.LBB0_715:
	s_andn2_b64 vcc, exec, s[16:17]
	s_cbranch_vccnz .LBB0_717
	s_and_b32 s16, s30, 0xffc0
	s_add_i32 s82, s16, 0xffff3e80
	s_load_dwordx2 s[16:17], s[14:15], 0xa8
	v_readlane_b32 s18, v254, 36
	v_readlane_b32 s19, v254, 37
	s_lshl_b64 s[18:19], s[18:19], 2
	v_or_b32_e32 v16, s82, v1
	s_waitcnt lgkmcnt(0)
	s_add_u32 s18, s16, s18
	s_addc_u32 s17, s17, s19
	s_and_b32 s16, s28, 0x7e0
	s_lshl_b32 s19, s16, 2
	s_add_u32 s18, s18, s19
	s_addc_u32 s19, s17, 0
	v_lshlrev_b32_e32 v184, 2, v0
	v_mov_b32_e32 v17, v185
	v_lshl_add_u64 v[18:19], s[18:19], 0, v[184:185]
	v_lshlrev_b64 v[26:27], 13, v[16:17]
	v_lshl_add_u64 v[26:27], v[18:19], 0, v[26:27]
	v_or_b32_e32 v184, 2, v16
	global_load_dword v15, v[26:27], off nt
	v_lshlrev_b64 v[26:27], 13, v[184:185]
	v_lshl_add_u64 v[26:27], v[18:19], 0, v[26:27]
	v_or_b32_e32 v184, 4, v16
	global_load_dword v28, v[26:27], off nt
	v_lshlrev_b64 v[26:27], 13, v[184:185]
	v_lshl_add_u64 v[26:27], v[18:19], 0, v[26:27]
	v_or_b32_e32 v184, 6, v16
	global_load_dword v29, v[26:27], off nt
	v_lshlrev_b64 v[26:27], 13, v[184:185]
	v_lshl_add_u64 v[26:27], v[18:19], 0, v[26:27]
	v_or_b32_e32 v184, 8, v16
	global_load_dword v30, v[26:27], off nt
	v_lshlrev_b64 v[26:27], 13, v[184:185]
	v_lshl_add_u64 v[26:27], v[18:19], 0, v[26:27]
	v_or_b32_e32 v184, 10, v16
	global_load_dword v31, v[26:27], off nt
	v_lshlrev_b64 v[26:27], 13, v[184:185]
	v_lshl_add_u64 v[26:27], v[18:19], 0, v[26:27]
	v_or_b32_e32 v184, 12, v16
	global_load_dword v32, v[26:27], off nt
	v_lshlrev_b64 v[26:27], 13, v[184:185]
	v_lshl_add_u64 v[26:27], v[18:19], 0, v[26:27]
	v_or_b32_e32 v184, 14, v16
	global_load_dword v33, v[26:27], off nt
	v_lshlrev_b64 v[26:27], 13, v[184:185]
	v_lshl_add_u64 v[26:27], v[18:19], 0, v[26:27]
	v_or_b32_e32 v184, 16, v16
	global_load_dword v34, v[26:27], off nt
	v_lshlrev_b64 v[26:27], 13, v[184:185]
	v_lshl_add_u64 v[26:27], v[18:19], 0, v[26:27]
	v_or_b32_e32 v184, 18, v16
	global_load_dword v35, v[26:27], off nt
	v_lshlrev_b64 v[26:27], 13, v[184:185]
	v_lshl_add_u64 v[26:27], v[18:19], 0, v[26:27]
	v_or_b32_e32 v184, 20, v16
	global_load_dword v36, v[26:27], off nt
	v_lshlrev_b64 v[26:27], 13, v[184:185]
	v_lshl_add_u64 v[26:27], v[18:19], 0, v[26:27]
	v_or_b32_e32 v184, 22, v16
	global_load_dword v37, v[26:27], off nt
	v_lshlrev_b64 v[26:27], 13, v[184:185]
	v_lshl_add_u64 v[26:27], v[18:19], 0, v[26:27]
	v_or_b32_e32 v184, 24, v16
	global_load_dword v38, v[26:27], off nt
	v_lshlrev_b64 v[26:27], 13, v[184:185]
	v_lshl_add_u64 v[26:27], v[18:19], 0, v[26:27]
	v_or_b32_e32 v184, 26, v16
	global_load_dword v39, v[26:27], off nt
	v_lshlrev_b64 v[26:27], 13, v[184:185]
	v_lshl_add_u64 v[26:27], v[18:19], 0, v[26:27]
	v_or_b32_e32 v184, 28, v16
	global_load_dword v40, v[26:27], off nt
	v_lshlrev_b64 v[26:27], 13, v[184:185]
	v_lshl_add_u64 v[26:27], v[18:19], 0, v[26:27]
	v_or_b32_e32 v184, 30, v16
	global_load_dword v41, v[26:27], off nt
	v_lshlrev_b64 v[26:27], 13, v[184:185]
	v_lshl_add_u64 v[26:27], v[18:19], 0, v[26:27]
	v_or_b32_e32 v184, 32, v16
	global_load_dword v42, v[26:27], off nt
	v_lshlrev_b64 v[26:27], 13, v[184:185]
	v_lshl_add_u64 v[26:27], v[18:19], 0, v[26:27]
	v_or_b32_e32 v184, 34, v16
	global_load_dword v43, v[26:27], off nt
	v_lshlrev_b64 v[26:27], 13, v[184:185]
	v_lshl_add_u64 v[26:27], v[18:19], 0, v[26:27]
	v_or_b32_e32 v184, 36, v16
	global_load_dword v44, v[26:27], off nt
	v_lshlrev_b64 v[26:27], 13, v[184:185]
	v_lshl_add_u64 v[26:27], v[18:19], 0, v[26:27]
	v_or_b32_e32 v184, 38, v16
	global_load_dword v45, v[26:27], off nt
	v_lshlrev_b64 v[26:27], 13, v[184:185]
	v_lshl_add_u64 v[26:27], v[18:19], 0, v[26:27]
	v_or_b32_e32 v184, 40, v16
	global_load_dword v46, v[26:27], off nt
	v_lshlrev_b64 v[26:27], 13, v[184:185]
	v_lshl_add_u64 v[26:27], v[18:19], 0, v[26:27]
	v_or_b32_e32 v184, 42, v16
	global_load_dword v47, v[26:27], off nt
	v_lshlrev_b64 v[26:27], 13, v[184:185]
	v_lshl_add_u64 v[26:27], v[18:19], 0, v[26:27]
	v_or_b32_e32 v184, 44, v16
	global_load_dword v48, v[26:27], off nt
	v_lshlrev_b64 v[26:27], 13, v[184:185]
	v_lshl_add_u64 v[26:27], v[18:19], 0, v[26:27]
	v_or_b32_e32 v184, 46, v16
	global_load_dword v49, v[26:27], off nt
	v_lshlrev_b64 v[26:27], 13, v[184:185]
	v_lshl_add_u64 v[26:27], v[18:19], 0, v[26:27]
	v_or_b32_e32 v184, 48, v16
	global_load_dword v50, v[26:27], off nt
	v_lshlrev_b64 v[26:27], 13, v[184:185]
	v_lshl_add_u64 v[26:27], v[18:19], 0, v[26:27]
	v_or_b32_e32 v184, 50, v16
	global_load_dword v51, v[26:27], off nt
	v_lshlrev_b64 v[26:27], 13, v[184:185]
	v_lshl_add_u64 v[26:27], v[18:19], 0, v[26:27]
	v_or_b32_e32 v184, 52, v16
	global_load_dword v52, v[26:27], off nt
	v_lshlrev_b64 v[26:27], 13, v[184:185]
	v_lshl_add_u64 v[26:27], v[18:19], 0, v[26:27]
	v_or_b32_e32 v184, 54, v16
	global_load_dword v53, v[26:27], off nt
	v_lshlrev_b64 v[26:27], 13, v[184:185]
	v_lshl_add_u64 v[26:27], v[18:19], 0, v[26:27]
	v_or_b32_e32 v184, 56, v16
	global_load_dword v54, v[26:27], off nt
	v_lshlrev_b64 v[26:27], 13, v[184:185]
	v_lshl_add_u64 v[26:27], v[18:19], 0, v[26:27]
	v_or_b32_e32 v184, 58, v16
	global_load_dword v55, v[26:27], off nt
	v_lshlrev_b64 v[26:27], 13, v[184:185]
	v_lshl_add_u64 v[26:27], v[18:19], 0, v[26:27]
	v_or_b32_e32 v184, 60, v16
	global_load_dword v56, v[26:27], off nt
	v_lshlrev_b64 v[26:27], 13, v[184:185]
	v_or_b32_e32 v184, 62, v16
	v_lshlrev_b64 v[16:17], 13, v[184:185]
	v_lshl_add_u64 v[26:27], v[18:19], 0, v[26:27]
	v_lshl_add_u64 v[16:17], v[18:19], 0, v[16:17]
	global_load_dword v26, v[26:27], off nt
	s_nop 0
	global_load_dword v16, v[16:17], off nt
	s_waitcnt vmcnt(30)
; #define LAS __attribute__((address_space(3)))
; #define LDS_WAIT() asm volatile("s_waitcnt lgkmcnt(0)" ::: "memory")
; __device__ __forceinline__ unsigned pk2(float lo, float hi) { return cvt_pk_bf16(lo, hi); }
; __device__ __forceinline__ void transpose_item(const float* W, int ldw, int k0, int n0, bf16* WT, int Kdst, int dst_row0, LAS float* scr, int lane) {
;     ...
;     for (int i = 0; i < 32; ++i) { const int kk = 2 * i + (lane >> 5); scr[kk * 33 + (lane & 31)] = tv[i]; }
;     LDS_WAIT(); asm volatile("" ::: "memory");
;     const int c = lane & 7;
; #pragma unroll
;     for (int j = 0; j < 4; ++j) { const int n = (lane >> 3) + 8 * j; const LAS float* s = scr + (8 * c) * 33 + n;
;         v4u o; o.x = pk2(s[0 * 33], s[1 * 33]); o.y = pk2(s[2 * 33], s[3 * 33]); o.z = pk2(s[4 * 33], s[5 * 33]); o.w = pk2(s[6 * 33], s[7 * 33]);
;         *(v4u*)(WT + (size_t)(dst_row0 + n) * Kdst + k0 + 8 * c) = o; }
;     LDS_WAIT(); asm volatile("" ::: "memory");
	ds_write2_b32 v20, v15, v28 offset1:66
	s_waitcnt vmcnt(28)
	ds_write2_b32 v20, v29, v30 offset0:132 offset1:198
	v_add_u32_e32 v15, 0x400, v20
	s_waitcnt vmcnt(26)
	ds_write2_b32 v15, v31, v32 offset0:8 offset1:74
	s_waitcnt vmcnt(24)
	ds_write2_b32 v15, v33, v34 offset0:140 offset1:206
	v_add_u32_e32 v15, 0x800, v20
	s_waitcnt vmcnt(22)
	ds_write2_b32 v15, v35, v36 offset0:16 offset1:82
	s_waitcnt vmcnt(20)
	ds_write2_b32 v15, v37, v38 offset0:148 offset1:214
	v_add_u32_e32 v15, 0xc00, v20
	s_waitcnt vmcnt(18)
	ds_write2_b32 v15, v39, v40 offset0:24 offset1:90
	s_waitcnt vmcnt(16)
	ds_write2_b32 v15, v41, v42 offset0:156 offset1:222
	v_add_u32_e32 v15, 0x1000, v20
	s_waitcnt vmcnt(14)
	ds_write2_b32 v15, v43, v44 offset0:32 offset1:98
	s_waitcnt vmcnt(12)
	ds_write2_b32 v15, v45, v46 offset0:164 offset1:230
	v_add_u32_e32 v15, 0x1400, v20
	s_waitcnt vmcnt(10)
	ds_write2_b32 v15, v47, v48 offset0:40 offset1:106
	s_waitcnt vmcnt(8)
	ds_write2_b32 v15, v49, v50 offset0:172 offset1:238
	v_add_u32_e32 v15, 0x1800, v20
	s_waitcnt vmcnt(6)
	ds_write2_b32 v15, v51, v52 offset0:48 offset1:114
	s_waitcnt vmcnt(4)
	ds_write2_b32 v15, v53, v54 offset0:180 offset1:246
	v_add_u32_e32 v15, 0x1c00, v20
	s_waitcnt vmcnt(2)
	ds_write2_b32 v15, v55, v56 offset0:56 offset1:122
	s_waitcnt vmcnt(0)
	ds_write2_b32 v15, v26, v16 offset0:188 offset1:254
	s_waitcnt lgkmcnt(0)
	ds_read2_b32 v[28:29], v22 offset0:33 offset1:41
	ds_read2_b32 v[30:31], v22 offset1:8
	ds_read2_b32 v[32:33], v22 offset0:66 offset1:74
	ds_read2_b32 v[34:35], v22 offset0:99 offset1:107
	ds_read2_b32 v[36:37], v22 offset0:132 offset1:140
	ds_read2_b32 v[38:39], v22 offset0:165 offset1:173
	ds_read2_b32 v[40:41], v22 offset0:198 offset1:206
	ds_read2_b32 v[42:43], v22 offset0:231 offset1:239
	v_or_b32_e32 v15, s16, v21
	v_lshl_add_u64 v[26:27], s[82:83], 1, v[8:9]
	v_lshlrev_b32_e32 v184, 10, v15
	v_or_b32_e32 v15, s16, v23
	s_waitcnt lgkmcnt(6)
	v_cvt_pk_bf16_f32 v16, v30, v28
	s_waitcnt lgkmcnt(4)
	v_cvt_pk_bf16_f32 v17, v32, v34
	s_waitcnt lgkmcnt(2)
	v_cvt_pk_bf16_f32 v18, v36, v38
	s_waitcnt lgkmcnt(0)
	v_cvt_pk_bf16_f32 v19, v40, v42
	v_lshl_add_u64 v[44:45], v[26:27], 0, v[184:185]
	v_lshlrev_b32_e32 v184, 10, v15
	global_store_dwordx4 v[44:45], v[16:19], off
	v_or_b32_e32 v15, s16, v24
	s_nop 0
	v_cvt_pk_bf16_f32 v16, v31, v29
	v_cvt_pk_bf16_f32 v17, v33, v35
	v_cvt_pk_bf16_f32 v18, v37, v39
	v_cvt_pk_bf16_f32 v19, v41, v43
	v_lshl_add_u64 v[28:29], v[26:27], 0, v[184:185]
	global_store_dwordx4 v[28:29], v[16:19], off
	ds_read2_b32 v[28:29], v22 offset0:49 offset1:57
	ds_read2_b32 v[30:31], v22 offset0:16 offset1:24
	ds_read2_b32 v[32:33], v22 offset0:82 offset1:90
	ds_read2_b32 v[34:35], v22 offset0:115 offset1:123
	ds_read2_b32 v[36:37], v22 offset0:148 offset1:156
	ds_read2_b32 v[38:39], v22 offset0:181 offset1:189
	ds_read2_b32 v[40:41], v22 offset0:214 offset1:222
	ds_read2_b32 v[42:43], v22 offset0:247 offset1:255
	v_lshlrev_b32_e32 v184, 10, v15
	v_or_b32_e32 v15, s16, v25
	s_waitcnt lgkmcnt(6)
	v_cvt_pk_bf16_f32 v16, v30, v28
	s_waitcnt lgkmcnt(4)
	v_cvt_pk_bf16_f32 v17, v32, v34
	s_waitcnt lgkmcnt(2)
	v_cvt_pk_bf16_f32 v18, v36, v38
	s_waitcnt lgkmcnt(0)
	v_cvt_pk_bf16_f32 v19, v40, v42
	v_lshl_add_u64 v[44:45], v[26:27], 0, v[184:185]
	v_lshlrev_b32_e32 v184, 10, v15
	global_store_dwordx4 v[44:45], v[16:19], off
	v_lshl_add_u64 v[26:27], v[26:27], 0, v[184:185]
	s_nop 0
	v_cvt_pk_bf16_f32 v16, v31, v29
	v_cvt_pk_bf16_f32 v17, v33, v35
	v_cvt_pk_bf16_f32 v18, v37, v39
	v_cvt_pk_bf16_f32 v19, v41, v43
	global_store_dwordx4 v[26:27], v[16:19], off
	s_waitcnt lgkmcnt(0)

; #define LAS __attribute__((address_space(3)))
; __device__ __forceinline__ void transpose_item(const float* W, int ldw, int k0, int n0, bf16* WT, int Kdst, int dst_row0, LAS float* scr, int lane) {
;     float tv[32];
; #pragma unroll
;     for (int i = 0; i < 32; ++i) { const int kk = 2 * i + (lane >> 5); tv[i] = W[(size_t)(k0 + kk) * ldw + n0 + (lane & 31)]; }
; __device__ __forceinline__ void phase_wconv(const Frame& F, const Args& a, int l, unsigned char* wt, unsigned char* wth, int part) {
;     ...
;         if (r < I_IN) {
;             const float* W = a.in[F.z + 7] + (size_t)l * D * 15744;
;             const int kb = r / 492, nb = r % 492, n0 = 32 * nb;
;             if (!(((n0 >= 7680 && n0 < 9600) ? 1 : 2) & part)) continue;
;             bf16* dst; int row;
;             if (n0 < 4608) { dst = (bf16*)(wth + WO_ATT); row = n0; }
;             else if (n0 < 7680) { dst = (bf16*)(wth + WO_RET); row = n0 - 4608; }
;             else if (n0 < 9600) { dst = (bf16*)(wth + WO_CF); row = n0 - 7680; }
;             else { dst = (bf16*)(wth + WO_GATE); row = n0 - 9600; }
;             transpose_item(W, 15744, 64 * kb, n0, dst, D, row, scr, F.lane);
.LBB0_729:
	v_readlane_b32 s20, v254, 52
	v_readlane_b32 s21, v254, 53
	s_waitcnt lgkmcnt(0)
	s_add_u32 s20, s18, s20
	s_addc_u32 s19, s19, s21
	s_lshl_b32 s18, s34, 6
	s_and_b32 s18, s18, 0x3fc0
	s_lshl_b32 s21, s35, 2
	s_add_u32 s20, s20, s21
	v_or_b32_e32 v15, s18, v1
	s_addc_u32 s21, s19, 0
	v_lshlrev_b32_e32 v184, 2, v0
	v_lshl_add_u64 v[16:17], s[20:21], 0, v[184:185]
	v_mul_u32_u24_e32 v184, 0xf600, v15
	v_lshl_add_u64 v[16:17], v[16:17], 0, v[184:185]
	s_mov_b32 s19, 0x1e000
	v_add_co_u32_e32 v18, vcc, s19, v16
	s_mov_b32 s19, 0x3d000
	s_nop 0
	v_addc_co_u32_e32 v19, vcc, 0, v17, vcc
	global_load_dword v26, v[18:19], off offset:3072 nt
	v_add_co_u32_e32 v18, vcc, s19, v16
	s_mov_b32 s19, 0x5c000
	s_nop 0
	v_addc_co_u32_e32 v19, vcc, 0, v17, vcc
	global_load_dword v27, v[18:19], off offset:2048 nt
	v_add_co_u32_e32 v18, vcc, s19, v16
	s_mov_b32 s19, 0x7b000
	s_nop 0
	v_addc_co_u32_e32 v19, vcc, 0, v17, vcc
	global_load_dword v28, v[18:19], off offset:1024 nt
	v_add_co_u32_e32 v18, vcc, s19, v16
	s_mov_b32 s19, 0x99000
	s_nop 0
	v_addc_co_u32_e32 v19, vcc, 0, v17, vcc
	global_load_dword v15, v[16:17], off nt
	global_load_dword v29, v[18:19], off nt
	v_add_co_u32_e32 v18, vcc, s19, v16
	s_mov_b32 s19, 0xb8000
	s_nop 0
	v_addc_co_u32_e32 v19, vcc, 0, v17, vcc
	global_load_dword v30, v[18:19], off offset:3072 nt
	v_add_co_u32_e32 v18, vcc, s19, v16
	s_mov_b32 s19, 0xd7000
	s_nop 0
	v_addc_co_u32_e32 v19, vcc, 0, v17, vcc
	global_load_dword v31, v[18:19], off offset:2048 nt
	v_add_co_u32_e32 v18, vcc, s19, v16
	s_mov_b32 s19, 0xf6000
	s_nop 0
	v_addc_co_u32_e32 v19, vcc, 0, v17, vcc
	global_load_dword v32, v[18:19], off offset:1024 nt
	v_add_co_u32_e32 v18, vcc, s19, v16
	s_mov_b32 s19, 0x114000
	s_nop 0
	v_addc_co_u32_e32 v19, vcc, 0, v17, vcc
	global_load_dword v33, v[18:19], off nt
	v_add_co_u32_e32 v18, vcc, s19, v16
	s_mov_b32 s19, 0x133000
	s_nop 0
	v_addc_co_u32_e32 v19, vcc, 0, v17, vcc
	global_load_dword v34, v[18:19], off offset:3072 nt
	v_add_co_u32_e32 v18, vcc, s19, v16
	s_mov_b32 s19, 0x152000
	s_nop 0
	v_addc_co_u32_e32 v19, vcc, 0, v17, vcc
	global_load_dword v35, v[18:19], off offset:2048 nt
	v_add_co_u32_e32 v18, vcc, s19, v16
	s_mov_b32 s19, 0x171000
	s_nop 0
	v_addc_co_u32_e32 v19, vcc, 0, v17, vcc
	global_load_dword v36, v[18:19], off offset:1024 nt
	v_add_co_u32_e32 v18, vcc, s19, v16
	s_mov_b32 s19, 0x18f000
	s_nop 0
	v_addc_co_u32_e32 v19, vcc, 0, v17, vcc
	global_load_dword v37, v[18:19], off nt
	v_add_co_u32_e32 v18, vcc, s19, v16
	s_mov_b32 s19, 0x1ae000
	s_nop 0
	v_addc_co_u32_e32 v19, vcc, 0, v17, vcc
	global_load_dword v38, v[18:19], off offset:3072 nt
	v_add_co_u32_e32 v18, vcc, s19, v16
	s_mov_b32 s19, 0x1cd000
	s_nop 0
	v_addc_co_u32_e32 v19, vcc, 0, v17, vcc
	global_load_dword v39, v[18:19], off offset:2048 nt
	v_add_co_u32_e32 v18, vcc, s19, v16
	s_mov_b32 s19, 0x1ec000
	s_nop 0
	v_addc_co_u32_e32 v19, vcc, 0, v17, vcc
	global_load_dword v40, v[18:19], off offset:1024 nt
	v_add_co_u32_e32 v18, vcc, s19, v16
	s_mov_b32 s19, 0x20a000
	s_nop 0
	v_addc_co_u32_e32 v19, vcc, 0, v17, vcc
	global_load_dword v41, v[18:19], off nt
	v_add_co_u32_e32 v18, vcc, s19, v16
	s_mov_b32 s19, 0x229000
	s_nop 0
	v_addc_co_u32_e32 v19, vcc, 0, v17, vcc
	global_load_dword v42, v[18:19], off offset:3072 nt
	v_add_co_u32_e32 v18, vcc, s19, v16
	s_mov_b32 s19, 0x248000
	s_nop 0
	v_addc_co_u32_e32 v19, vcc, 0, v17, vcc
	global_load_dword v43, v[18:19], off offset:2048 nt
	v_add_co_u32_e32 v18, vcc, s19, v16
	s_mov_b32 s19, 0x267000
	s_nop 0
	v_addc_co_u32_e32 v19, vcc, 0, v17, vcc
	global_load_dword v44, v[18:19], off offset:1024 nt
	v_add_co_u32_e32 v18, vcc, s19, v16
	s_mov_b32 s19, 0x285000
	s_nop 0
	v_addc_co_u32_e32 v19, vcc, 0, v17, vcc
	global_load_dword v45, v[18:19], off nt
	v_add_co_u32_e32 v18, vcc, s19, v16
	s_mov_b32 s19, 0x2a4000
	s_nop 0
	v_addc_co_u32_e32 v19, vcc, 0, v17, vcc
	global_load_dword v46, v[18:19], off offset:3072 nt
	v_add_co_u32_e32 v18, vcc, s19, v16
	s_mov_b32 s19, 0x2c3000
	s_nop 0
	v_addc_co_u32_e32 v19, vcc, 0, v17, vcc
	global_load_dword v47, v[18:19], off offset:2048 nt
	v_add_co_u32_e32 v18, vcc, s19, v16
	s_mov_b32 s19, 0x2e2000
	s_nop 0
	v_addc_co_u32_e32 v19, vcc, 0, v17, vcc
	global_load_dword v48, v[18:19], off offset:1024 nt
	v_add_co_u32_e32 v18, vcc, s19, v16
	s_mov_b32 s19, 0x300000
	s_nop 0
	v_addc_co_u32_e32 v19, vcc, 0, v17, vcc
	global_load_dword v49, v[18:19], off nt
	v_add_co_u32_e32 v18, vcc, s19, v16
	s_mov_b32 s19, 0x31f000
	s_nop 0
	v_addc_co_u32_e32 v19, vcc, 0, v17, vcc
	global_load_dword v50, v[18:19], off offset:3072 nt
	v_add_co_u32_e32 v18, vcc, s19, v16
	s_mov_b32 s19, 0x33e000
	s_nop 0
	v_addc_co_u32_e32 v19, vcc, 0, v17, vcc
	global_load_dword v51, v[18:19], off offset:2048 nt
	v_add_co_u32_e32 v18, vcc, s19, v16
	s_mov_b32 s19, 0x35d000
	s_nop 0
	v_addc_co_u32_e32 v19, vcc, 0, v17, vcc
	global_load_dword v52, v[18:19], off offset:1024 nt
	v_add_co_u32_e32 v18, vcc, s19, v16
	s_mov_b32 s19, 0x37b000
	s_nop 0
	v_addc_co_u32_e32 v19, vcc, 0, v17, vcc
	global_load_dword v53, v[18:19], off nt
	v_add_co_u32_e32 v18, vcc, s19, v16
	s_mov_b32 s19, 0x39a000
	s_nop 0
	v_addc_co_u32_e32 v19, vcc, 0, v17, vcc
	global_load_dword v54, v[18:19], off offset:3072 nt
	v_add_co_u32_e32 v18, vcc, s19, v16
	s_mov_b32 s19, 0x3b9000
	s_nop 0
	v_addc_co_u32_e32 v19, vcc, 0, v17, vcc
	v_add_co_u32_e32 v16, vcc, s19, v16
	global_load_dword v18, v[18:19], off offset:2048 nt
	s_nop 0
	v_addc_co_u32_e32 v17, vcc, 0, v17, vcc
	global_load_dword v16, v[16:17], off offset:1024 nt
	s_waitcnt vmcnt(28)
; #define LAS __attribute__((address_space(3)))
; #define LDS_WAIT() asm volatile("s_waitcnt lgkmcnt(0)" ::: "memory")
; __device__ __forceinline__ unsigned pk2(float lo, float hi) { return cvt_pk_bf16(lo, hi); }
; __device__ __forceinline__ void transpose_item(const float* W, int ldw, int k0, int n0, bf16* WT, int Kdst, int dst_row0, LAS float* scr, int lane) {
;     ...
;     for (int i = 0; i < 32; ++i) { const int kk = 2 * i + (lane >> 5); scr[kk * 33 + (lane & 31)] = tv[i]; }
;     LDS_WAIT(); asm volatile("" ::: "memory");
;     const int c = lane & 7;
; #pragma unroll
;     for (int j = 0; j < 4; ++j) { const int n = (lane >> 3) + 8 * j; const LAS float* s = scr + (8 * c) * 33 + n;
;         v4u o; o.x = pk2(s[0 * 33], s[1 * 33]); o.y = pk2(s[2 * 33], s[3 * 33]); o.z = pk2(s[4 * 33], s[5 * 33]); o.w = pk2(s[6 * 33], s[7 * 33]);
;         *(v4u*)(WT + (size_t)(dst_row0 + n) * Kdst + k0 + 8 * c) = o; }
;     LDS_WAIT(); asm volatile("" ::: "memory");
; __device__ __forceinline__ void phase_wconv(const Frame& F, const Args& a, int l, unsigned char* wt, unsigned char* wth, int part) {
;     ...
;             if (n0 < 4608) { dst = (bf16*)(wth + WO_ATT); row = n0; }
;             else if (n0 < 7680) { dst = (bf16*)(wth + WO_RET); row = n0 - 4608; }
;             else if (n0 < 9600) { dst = (bf16*)(wth + WO_CF); row = n0 - 7680; }
;             else { dst = (bf16*)(wth + WO_GATE); row = n0 - 9600; }
;             transpose_item(W, 15744, 64 * kb, n0, dst, D, row, scr, F.lane);
	ds_write2_b32 v20, v15, v26 offset1:66
	ds_write2_b32 v20, v27, v28 offset0:132 offset1:198
	v_add_u32_e32 v15, 0x400, v20
	s_waitcnt vmcnt(26)
	ds_write2_b32 v15, v29, v30 offset0:8 offset1:74
	s_waitcnt vmcnt(24)
	ds_write2_b32 v15, v31, v32 offset0:140 offset1:206
	v_add_u32_e32 v15, 0x800, v20
	s_waitcnt vmcnt(22)
	ds_write2_b32 v15, v33, v34 offset0:16 offset1:82
	s_waitcnt vmcnt(20)
	ds_write2_b32 v15, v35, v36 offset0:148 offset1:214
	v_add_u32_e32 v15, 0xc00, v20
	s_waitcnt vmcnt(18)
	ds_write2_b32 v15, v37, v38 offset0:24 offset1:90
	s_waitcnt vmcnt(16)
	ds_write2_b32 v15, v39, v40 offset0:156 offset1:222
	v_add_u32_e32 v15, 0x1000, v20
	s_waitcnt vmcnt(14)
	ds_write2_b32 v15, v41, v42 offset0:32 offset1:98
	s_waitcnt vmcnt(12)
	ds_write2_b32 v15, v43, v44 offset0:164 offset1:230
	v_add_u32_e32 v15, 0x1400, v20
	s_waitcnt vmcnt(10)
	ds_write2_b32 v15, v45, v46 offset0:40 offset1:106
	s_waitcnt vmcnt(8)
	ds_write2_b32 v15, v47, v48 offset0:172 offset1:238
	v_add_u32_e32 v15, 0x1800, v20
	s_waitcnt vmcnt(6)
	ds_write2_b32 v15, v49, v50 offset0:48 offset1:114
	s_waitcnt vmcnt(4)
	ds_write2_b32 v15, v51, v52 offset0:180 offset1:246
	v_add_u32_e32 v15, 0x1c00, v20
	s_waitcnt vmcnt(2)
	ds_write2_b32 v15, v53, v54 offset0:56 offset1:122
	s_waitcnt vmcnt(0)
	ds_write2_b32 v15, v18, v16 offset0:188 offset1:254
	s_waitcnt lgkmcnt(0)
	ds_read2_b32 v[28:29], v22 offset0:33 offset1:41
	ds_read2_b32 v[30:31], v22 offset1:8
	ds_read2_b32 v[32:33], v22 offset0:66 offset1:74
	ds_read2_b32 v[34:35], v22 offset0:99 offset1:107
	ds_read2_b32 v[36:37], v22 offset0:132 offset1:140
	ds_read2_b32 v[38:39], v22 offset0:165 offset1:173
	ds_read2_b32 v[40:41], v22 offset0:198 offset1:206
	ds_read2_b32 v[42:43], v22 offset0:231 offset1:239
	s_lshl_b32 s18, s18, 1
	s_add_u32 s16, s16, s18
	v_add_u32_e32 v44, s31, v21
	s_addc_u32 s17, s17, 0
	v_mov_b32_e32 v15, v185
	v_ashrrev_i32_e32 v45, 31, v44
	v_lshl_add_u64 v[26:27], s[16:17], 0, v[14:15]
	v_lshlrev_b64 v[44:45], 12, v[44:45]
	s_waitcnt lgkmcnt(6)
	v_cvt_pk_bf16_f32 v16, v30, v28
	s_waitcnt lgkmcnt(4)
	v_cvt_pk_bf16_f32 v17, v32, v34
	s_waitcnt lgkmcnt(2)
	v_cvt_pk_bf16_f32 v18, v36, v38
	s_waitcnt lgkmcnt(0)
	v_cvt_pk_bf16_f32 v19, v40, v42
	v_lshl_add_u64 v[44:45], v[26:27], 0, v[44:45]
	v_add_u32_e32 v28, s31, v23
	global_store_dwordx4 v[44:45], v[16:19], off
	v_add_u32_e32 v44, s31, v24
	v_ashrrev_i32_e32 v45, 31, v44
	v_cvt_pk_bf16_f32 v16, v31, v29
	v_ashrrev_i32_e32 v29, 31, v28
	v_lshlrev_b64 v[28:29], 12, v[28:29]
	v_cvt_pk_bf16_f32 v17, v33, v35
	v_cvt_pk_bf16_f32 v18, v37, v39
	v_cvt_pk_bf16_f32 v19, v41, v43
	v_lshl_add_u64 v[28:29], v[26:27], 0, v[28:29]
	global_store_dwordx4 v[28:29], v[16:19], off
	ds_read2_b32 v[28:29], v22 offset0:49 offset1:57
	ds_read2_b32 v[30:31], v22 offset0:16 offset1:24
	ds_read2_b32 v[32:33], v22 offset0:82 offset1:90
	ds_read2_b32 v[34:35], v22 offset0:115 offset1:123
	ds_read2_b32 v[36:37], v22 offset0:148 offset1:156
	ds_read2_b32 v[38:39], v22 offset0:181 offset1:189
	ds_read2_b32 v[40:41], v22 offset0:214 offset1:222
	ds_read2_b32 v[42:43], v22 offset0:247 offset1:255
	v_lshlrev_b64 v[44:45], 12, v[44:45]
	s_waitcnt lgkmcnt(6)
	v_cvt_pk_bf16_f32 v16, v30, v28
	s_waitcnt lgkmcnt(4)
	v_cvt_pk_bf16_f32 v17, v32, v34
	s_waitcnt lgkmcnt(2)
	v_cvt_pk_bf16_f32 v18, v36, v38
	s_waitcnt lgkmcnt(0)
	v_cvt_pk_bf16_f32 v19, v40, v42
	v_lshl_add_u64 v[44:45], v[26:27], 0, v[44:45]
	v_add_u32_e32 v28, s31, v25
	global_store_dwordx4 v[44:45], v[16:19], off
	s_nop 1
	v_cvt_pk_bf16_f32 v16, v31, v29
	v_ashrrev_i32_e32 v29, 31, v28
	v_lshlrev_b64 v[28:29], 12, v[28:29]
	v_cvt_pk_bf16_f32 v17, v33, v35
	v_cvt_pk_bf16_f32 v18, v37, v39
	v_cvt_pk_bf16_f32 v19, v41, v43
	v_lshl_add_u64 v[26:27], v[26:27], 0, v[28:29]
	global_store_dwordx4 v[26:27], v[16:19], off
	s_waitcnt lgkmcnt(0)

; #define LAS __attribute__((address_space(3)))
; __device__ __forceinline__ void transpose_item(const float* W, int ldw, int k0, int n0, bf16* WT, int Kdst, int dst_row0, LAS float* scr, int lane) {
;     float tv[32];
; #pragma unroll
;     for (int i = 0; i < 32; ++i) { const int kk = 2 * i + (lane >> 5); tv[i] = W[(size_t)(k0 + kk) * ldw + n0 + (lane & 31)]; }
; __device__ __forceinline__ void phase_wconv(const Frame& F, const Args& a, int l, unsigned char* wt, unsigned char* wth, int part) {
;     ...
;     for (int it = F.gw; it < NITEMS; it += F.NGW) {
;         int r = it;
;         if (r < I_A) {
;             const int m = r / I_FF, q = r % I_FF, f = m / 3, mm = m % 3;
;             if (!((f ? 2 : 1) & part)) continue;
;             if (mm < 2) {
;                 const float* W = a.in[F.z + (f ? 26 : 3) + mm] + (size_t)l * D * FF;
;                 const int kb = q / 176, nb = q % 176, n0 = 32 * nb;
;                 bf16* dst = (bf16*)(f ? wth + WO_UP2 : wt + WO_UP1);
;                 transpose_item(W, FF, 64 * kb, n0, dst, D, (n0 / 128) * 256 + mm * 128 + (n0 % 128), scr, F.lane);
;             } else {
;                 const float* W = a.in[F.z + (f ? 28 : 5)] + (size_t)l * FF * D;
;                 const int kb = q / 64, nb = q % 64, n0 = 32 * nb;
;                 bf16* dst = (bf16*)(f ? wth + WO_DN2 : wt + WO_DN1);
;                 transpose_item(W, D, 64 * kb, n0, dst, FF, n0, scr, F.lane);
;             }
.LBB0_731:
	s_andn2_b64 vcc, exec, s[16:17]
	s_cbranch_vccnz .LBB0_702
	s_add_i32 s16, s30, 0x41ff
	s_cmpk_lt_u32 s16, 0x83ff
	s_cbranch_scc1 .LBB0_702
	s_mul_hi_i32 s16, s30, 0x2e8ba2e9
	s_lshr_b32 s17, s16, 31
	s_ashr_i32 s16, s16, 10
	s_add_i32 s16, s16, s17
	s_mul_i32 s17, s16, 0xffffea00
	s_add_i32 s21, s30, s17
	s_mul_hi_i32 s17, s16, 0x55555556
	s_lshr_b32 s18, s17, 31
	s_add_i32 s17, s17, s18
	s_mul_i32 s17, s17, 3
	s_sub_i32 s20, s16, s17
	s_mov_b64 s[16:17], -1
	s_cmp_gt_i32 s20, 1
	v_lshlrev_b32_e32 v184, 2, v0
	v_add_u32_e32 v31, 0x400, v20
	v_add_u32_e32 v30, 0x800, v20
	v_add_u32_e32 v29, 0xc00, v20
	v_add_u32_e32 v28, 0x1000, v20
	v_add_u32_e32 v27, 0x1400, v20
	v_add_u32_e32 v26, 0x1800, v20
	v_add_u32_e32 v15, 0x1c00, v20
	s_cbranch_scc0 .LBB0_735
	s_load_dwordx2 s[16:17], s[14:15], 0xe0
	v_readlane_b32 s18, v254, 26
	v_readlane_b32 s19, v254, 27
	s_lshl_b64 s[18:19], s[18:19], 2
	s_waitcnt lgkmcnt(0)
	s_add_u32 s31, s16, s18
	s_addc_u32 s19, s17, s19
	s_bfe_u32 s16, s21, 0x60019
	s_add_i32 s16, s21, s16
	s_sext_i32_i16 s17, s16
	s_and_b32 s16, s16, 0xffc0
	s_sub_i32 s16, s21, s16
	s_sext_i32_i16 s16, s16
	s_lshl_b32 s16, s16, 5
	s_and_b32 s18, s17, 0xffffffc0
	s_ashr_i32 s17, s16, 31
	s_lshl_b64 s[34:35], s[16:17], 2
	v_or_b32_e32 v16, s18, v1
	s_add_u32 s34, s31, s34
	s_addc_u32 s35, s19, s35
	v_ashrrev_i32_e32 v17, 31, v16
	v_lshl_add_u64 v[18:19], s[34:35], 0, v[184:185]
	v_lshlrev_b64 v[32:33], 13, v[16:17]
	v_lshl_add_u64 v[32:33], v[18:19], 0, v[32:33]
	global_load_dword v34, v[32:33], off nt
	v_or_b32_e32 v32, 2, v16
	v_ashrrev_i32_e32 v33, 31, v32
	v_lshlrev_b64 v[32:33], 13, v[32:33]
	v_lshl_add_u64 v[32:33], v[18:19], 0, v[32:33]
	global_load_dword v35, v[32:33], off nt
	v_or_b32_e32 v32, 4, v16
	v_ashrrev_i32_e32 v33, 31, v32
	v_lshlrev_b64 v[32:33], 13, v[32:33]
	v_lshl_add_u64 v[32:33], v[18:19], 0, v[32:33]
	global_load_dword v36, v[32:33], off nt
	v_or_b32_e32 v32, 6, v16
	v_ashrrev_i32_e32 v33, 31, v32
	v_lshlrev_b64 v[32:33], 13, v[32:33]
	v_lshl_add_u64 v[32:33], v[18:19], 0, v[32:33]
	global_load_dword v37, v[32:33], off nt
	v_or_b32_e32 v32, 8, v16
	v_ashrrev_i32_e32 v33, 31, v32
	v_lshlrev_b64 v[32:33], 13, v[32:33]
	v_lshl_add_u64 v[32:33], v[18:19], 0, v[32:33]
	global_load_dword v38, v[32:33], off nt
	v_or_b32_e32 v32, 10, v16
	v_ashrrev_i32_e32 v33, 31, v32
	v_lshlrev_b64 v[32:33], 13, v[32:33]
	v_lshl_add_u64 v[32:33], v[18:19], 0, v[32:33]
	global_load_dword v39, v[32:33], off nt
	v_or_b32_e32 v32, 12, v16
	v_ashrrev_i32_e32 v33, 31, v32
	v_lshlrev_b64 v[32:33], 13, v[32:33]
	v_lshl_add_u64 v[32:33], v[18:19], 0, v[32:33]
	global_load_dword v40, v[32:33], off nt
	v_or_b32_e32 v32, 14, v16
	v_ashrrev_i32_e32 v33, 31, v32
	v_lshlrev_b64 v[32:33], 13, v[32:33]
	v_lshl_add_u64 v[32:33], v[18:19], 0, v[32:33]
	global_load_dword v41, v[32:33], off nt
	v_or_b32_e32 v32, 16, v16
	v_ashrrev_i32_e32 v33, 31, v32
	v_lshlrev_b64 v[32:33], 13, v[32:33]
	v_lshl_add_u64 v[32:33], v[18:19], 0, v[32:33]
	global_load_dword v42, v[32:33], off nt
	v_or_b32_e32 v32, 18, v16
	v_ashrrev_i32_e32 v33, 31, v32
	v_lshlrev_b64 v[32:33], 13, v[32:33]
	v_lshl_add_u64 v[32:33], v[18:19], 0, v[32:33]
	global_load_dword v43, v[32:33], off nt
	v_or_b32_e32 v32, 20, v16
	v_ashrrev_i32_e32 v33, 31, v32
	v_lshlrev_b64 v[32:33], 13, v[32:33]
	v_lshl_add_u64 v[32:33], v[18:19], 0, v[32:33]
	global_load_dword v44, v[32:33], off nt
	v_or_b32_e32 v32, 22, v16
	v_ashrrev_i32_e32 v33, 31, v32
	v_lshlrev_b64 v[32:33], 13, v[32:33]
	v_lshl_add_u64 v[32:33], v[18:19], 0, v[32:33]
	global_load_dword v45, v[32:33], off nt
	v_or_b32_e32 v32, 24, v16
	v_ashrrev_i32_e32 v33, 31, v32
	v_lshlrev_b64 v[32:33], 13, v[32:33]
	v_lshl_add_u64 v[32:33], v[18:19], 0, v[32:33]
	global_load_dword v46, v[32:33], off nt
	v_or_b32_e32 v32, 26, v16
	v_ashrrev_i32_e32 v33, 31, v32
	v_lshlrev_b64 v[32:33], 13, v[32:33]
	v_lshl_add_u64 v[32:33], v[18:19], 0, v[32:33]
	global_load_dword v47, v[32:33], off nt
	v_or_b32_e32 v32, 28, v16
	v_ashrrev_i32_e32 v33, 31, v32
	v_lshlrev_b64 v[32:33], 13, v[32:33]
	v_lshl_add_u64 v[32:33], v[18:19], 0, v[32:33]
	global_load_dword v48, v[32:33], off nt
	v_or_b32_e32 v32, 30, v16
	v_ashrrev_i32_e32 v33, 31, v32
	v_lshlrev_b64 v[32:33], 13, v[32:33]
	v_lshl_add_u64 v[32:33], v[18:19], 0, v[32:33]
	global_load_dword v49, v[32:33], off nt
	v_or_b32_e32 v32, 32, v16
	v_ashrrev_i32_e32 v33, 31, v32
	v_lshlrev_b64 v[32:33], 13, v[32:33]
	v_lshl_add_u64 v[32:33], v[18:19], 0, v[32:33]
	global_load_dword v50, v[32:33], off nt
	v_or_b32_e32 v32, 34, v16
	v_ashrrev_i32_e32 v33, 31, v32
	v_lshlrev_b64 v[32:33], 13, v[32:33]
	v_lshl_add_u64 v[32:33], v[18:19], 0, v[32:33]
	global_load_dword v51, v[32:33], off nt
	v_or_b32_e32 v32, 36, v16
	v_ashrrev_i32_e32 v33, 31, v32
	v_lshlrev_b64 v[32:33], 13, v[32:33]
	v_lshl_add_u64 v[32:33], v[18:19], 0, v[32:33]
	global_load_dword v52, v[32:33], off nt
	v_or_b32_e32 v32, 38, v16
	v_ashrrev_i32_e32 v33, 31, v32
	v_lshlrev_b64 v[32:33], 13, v[32:33]
	v_lshl_add_u64 v[32:33], v[18:19], 0, v[32:33]
	global_load_dword v53, v[32:33], off nt
	v_or_b32_e32 v32, 40, v16
	v_ashrrev_i32_e32 v33, 31, v32
	v_lshlrev_b64 v[32:33], 13, v[32:33]
	v_lshl_add_u64 v[32:33], v[18:19], 0, v[32:33]
	global_load_dword v54, v[32:33], off nt
	v_or_b32_e32 v32, 42, v16
	v_ashrrev_i32_e32 v33, 31, v32
	v_lshlrev_b64 v[32:33], 13, v[32:33]
	v_lshl_add_u64 v[32:33], v[18:19], 0, v[32:33]
	global_load_dword v55, v[32:33], off nt
	v_or_b32_e32 v32, 44, v16
	v_ashrrev_i32_e32 v33, 31, v32
	v_lshlrev_b64 v[32:33], 13, v[32:33]
	v_lshl_add_u64 v[32:33], v[18:19], 0, v[32:33]
	global_load_dword v56, v[32:33], off nt
; #define LAS __attribute__((address_space(3)))
; #define LDS_WAIT() asm volatile("s_waitcnt lgkmcnt(0)" ::: "memory")
; __device__ __forceinline__ unsigned pk2(float lo, float hi) { return cvt_pk_bf16(lo, hi); }
; __device__ __forceinline__ void transpose_item(const float* W, int ldw, int k0, int n0, bf16* WT, int Kdst, int dst_row0, LAS float* scr, int lane) {
;     float tv[32];
; #pragma unroll
;     for (int i = 0; i < 32; ++i) { const int kk = 2 * i + (lane >> 5); tv[i] = W[(size_t)(k0 + kk) * ldw + n0 + (lane & 31)]; }
; #pragma unroll
;     for (int i = 0; i < 32; ++i) { const int kk = 2 * i + (lane >> 5); scr[kk * 33 + (lane & 31)] = tv[i]; }
;     LDS_WAIT(); asm volatile("" ::: "memory");
;     const int c = lane & 7;
; #pragma unroll
;     for (int j = 0; j < 4; ++j) { const int n = (lane >> 3) + 8 * j; const LAS float* s = scr + (8 * c) * 33 + n;
;         v4u o; o.x = pk2(s[0 * 33], s[1 * 33]); o.y = pk2(s[2 * 33], s[3 * 33]); o.z = pk2(s[4 * 33], s[5 * 33]); o.w = pk2(s[6 * 33], s[7 * 33]);
;         *(v4u*)(WT + (size_t)(dst_row0 + n) * Kdst + k0 + 8 * c) = o; }
;     LDS_WAIT(); asm volatile("" ::: "memory");
; __device__ __forceinline__ void phase_wconv(const Frame& F, const Args& a, int l, unsigned char* wt, unsigned char* wth, int part) {
;     ...
;             } else {
;                 const float* W = a.in[F.z + (f ? 28 : 5)] + (size_t)l * FF * D;
;                 const int kb = q / 64, nb = q % 64, n0 = 32 * nb;
;                 bf16* dst = (bf16*)(f ? wth + WO_DN2 : wt + WO_DN1);
;                 transpose_item(W, D, 64 * kb, n0, dst, FF, n0, scr, F.lane);
	v_or_b32_e32 v32, 46, v16
	v_ashrrev_i32_e32 v33, 31, v32
	v_lshlrev_b64 v[32:33], 13, v[32:33]
	v_lshl_add_u64 v[32:33], v[18:19], 0, v[32:33]
	global_load_dword v57, v[32:33], off nt
	v_or_b32_e32 v32, 48, v16
	v_ashrrev_i32_e32 v33, 31, v32
	v_lshlrev_b64 v[32:33], 13, v[32:33]
	v_lshl_add_u64 v[32:33], v[18:19], 0, v[32:33]
	global_load_dword v58, v[32:33], off nt
	v_or_b32_e32 v32, 50, v16
	v_ashrrev_i32_e32 v33, 31, v32
	v_lshlrev_b64 v[32:33], 13, v[32:33]
	v_lshl_add_u64 v[32:33], v[18:19], 0, v[32:33]
	global_load_dword v59, v[32:33], off nt
	v_or_b32_e32 v32, 52, v16
	v_ashrrev_i32_e32 v33, 31, v32
	v_lshlrev_b64 v[32:33], 13, v[32:33]
	v_lshl_add_u64 v[32:33], v[18:19], 0, v[32:33]
	global_load_dword v60, v[32:33], off nt
	v_or_b32_e32 v32, 54, v16
	v_ashrrev_i32_e32 v33, 31, v32
	v_lshlrev_b64 v[32:33], 13, v[32:33]
	v_lshl_add_u64 v[32:33], v[18:19], 0, v[32:33]
	global_load_dword v61, v[32:33], off nt
	v_or_b32_e32 v32, 56, v16
	v_ashrrev_i32_e32 v33, 31, v32
	v_lshlrev_b64 v[32:33], 13, v[32:33]
	v_lshl_add_u64 v[32:33], v[18:19], 0, v[32:33]
	global_load_dword v62, v[32:33], off nt
	v_or_b32_e32 v32, 58, v16
	v_ashrrev_i32_e32 v33, 31, v32
	v_lshlrev_b64 v[32:33], 13, v[32:33]
	v_lshl_add_u64 v[32:33], v[18:19], 0, v[32:33]
	global_load_dword v63, v[32:33], off nt
	v_or_b32_e32 v32, 60, v16
	v_or_b32_e32 v16, 62, v16
	v_ashrrev_i32_e32 v33, 31, v32
	v_ashrrev_i32_e32 v17, 31, v16
	v_lshlrev_b64 v[32:33], 13, v[32:33]
	v_lshlrev_b64 v[16:17], 13, v[16:17]
	v_lshl_add_u64 v[32:33], v[18:19], 0, v[32:33]
	v_lshl_add_u64 v[16:17], v[18:19], 0, v[16:17]
	global_load_dword v32, v[32:33], off nt
	s_ashr_i32 s19, s18, 31
	global_load_dword v16, v[16:17], off nt
	s_waitcnt vmcnt(30)
	ds_write2_b32 v20, v34, v35 offset1:66
	s_waitcnt vmcnt(28)
	ds_write2_b32 v20, v36, v37 offset0:132 offset1:198
	s_waitcnt vmcnt(26)
	ds_write2_b32 v31, v38, v39 offset0:8 offset1:74
	s_waitcnt vmcnt(24)
	ds_write2_b32 v31, v40, v41 offset0:140 offset1:206
	s_waitcnt vmcnt(22)
	ds_write2_b32 v30, v42, v43 offset0:16 offset1:82
	s_waitcnt vmcnt(20)
	ds_write2_b32 v30, v44, v45 offset0:148 offset1:214
	s_waitcnt vmcnt(18)
	ds_write2_b32 v29, v46, v47 offset0:24 offset1:90
	s_waitcnt vmcnt(16)
	ds_write2_b32 v29, v48, v49 offset0:156 offset1:222
	s_waitcnt vmcnt(14)
	ds_write2_b32 v28, v50, v51 offset0:32 offset1:98
	s_waitcnt vmcnt(12)
	ds_write2_b32 v28, v52, v53 offset0:164 offset1:230
	s_waitcnt vmcnt(10)
	ds_write2_b32 v27, v54, v55 offset0:40 offset1:106
	s_waitcnt vmcnt(8)
	ds_write2_b32 v27, v56, v57 offset0:172 offset1:238
	s_waitcnt vmcnt(6)
	ds_write2_b32 v26, v58, v59 offset0:48 offset1:114
	s_waitcnt vmcnt(4)
	ds_write2_b32 v26, v60, v61 offset0:180 offset1:246
	s_waitcnt vmcnt(2)
	ds_write2_b32 v15, v62, v63 offset0:56 offset1:122
	s_waitcnt vmcnt(0)
	ds_write2_b32 v15, v32, v16 offset0:188 offset1:254
	s_waitcnt lgkmcnt(0)
	ds_read2_b32 v[34:35], v22 offset0:33 offset1:41
	ds_read2_b32 v[36:37], v22 offset1:8
	ds_read2_b32 v[38:39], v22 offset0:66 offset1:74
	ds_read2_b32 v[40:41], v22 offset0:99 offset1:107
	ds_read2_b32 v[42:43], v22 offset0:132 offset1:140
	ds_read2_b32 v[44:45], v22 offset0:165 offset1:173
	ds_read2_b32 v[46:47], v22 offset0:198 offset1:206
	ds_read2_b32 v[48:49], v22 offset0:231 offset1:239
	v_lshl_add_u64 v[32:33], s[18:19], 1, v[10:11]
	s_waitcnt lgkmcnt(6)
	v_cvt_pk_bf16_f32 v16, v36, v34
	v_or_b32_e32 v34, s16, v21
	v_mul_i32_i24_e32 v50, 0x2c00, v34
	v_ashrrev_i32_e32 v51, 31, v50
	v_or_b32_e32 v34, s16, v23
	s_waitcnt lgkmcnt(4)
	v_cvt_pk_bf16_f32 v17, v38, v40
	s_waitcnt lgkmcnt(2)
	v_cvt_pk_bf16_f32 v18, v42, v44
	s_waitcnt lgkmcnt(0)
	v_cvt_pk_bf16_f32 v19, v46, v48
	v_lshl_add_u64 v[50:51], v[32:33], 0, v[50:51]
	v_mul_i32_i24_e32 v34, 0x2c00, v34
	global_store_dwordx4 v[50:51], v[16:19], off
	s_nop 1
	v_cvt_pk_bf16_f32 v16, v37, v35
	v_ashrrev_i32_e32 v35, 31, v34
	v_cvt_pk_bf16_f32 v17, v39, v41
	v_cvt_pk_bf16_f32 v18, v43, v45
	v_cvt_pk_bf16_f32 v19, v47, v49
	v_lshl_add_u64 v[34:35], v[32:33], 0, v[34:35]
	global_store_dwordx4 v[34:35], v[16:19], off
	ds_read2_b32 v[34:35], v22 offset0:16 offset1:24
	ds_read2_b32 v[36:37], v22 offset0:49 offset1:57
	ds_read2_b32 v[38:39], v22 offset0:82 offset1:90
	ds_read2_b32 v[40:41], v22 offset0:115 offset1:123
	ds_read2_b32 v[42:43], v22 offset0:148 offset1:156
	ds_read2_b32 v[44:45], v22 offset0:181 offset1:189
	ds_read2_b32 v[46:47], v22 offset0:214 offset1:222
	ds_read2_b32 v[48:49], v22 offset0:247 offset1:255
	s_waitcnt lgkmcnt(6)
	v_cvt_pk_bf16_f32 v16, v34, v36
	v_or_b32_e32 v34, s16, v24
	v_mul_i32_i24_e32 v50, 0x2c00, v34
	v_ashrrev_i32_e32 v51, 31, v50
	v_or_b32_e32 v34, s16, v25
	s_waitcnt lgkmcnt(4)
	v_cvt_pk_bf16_f32 v17, v38, v40
	s_waitcnt lgkmcnt(2)
	v_cvt_pk_bf16_f32 v18, v42, v44
	s_waitcnt lgkmcnt(0)
	v_cvt_pk_bf16_f32 v19, v46, v48
	v_lshl_add_u64 v[50:51], v[32:33], 0, v[50:51]
	v_mul_i32_i24_e32 v34, 0x2c00, v34
	global_store_dwordx4 v[50:51], v[16:19], off
	s_mov_b64 s[16:17], 0
	s_nop 0
	v_cvt_pk_bf16_f32 v16, v35, v37
	v_ashrrev_i32_e32 v35, 31, v34
	v_cvt_pk_bf16_f32 v17, v39, v41
	v_cvt_pk_bf16_f32 v18, v43, v45
	v_cvt_pk_bf16_f32 v19, v47, v49
	v_lshl_add_u64 v[32:33], v[32:33], 0, v[34:35]
	global_store_dwordx4 v[32:33], v[16:19], off
	s_waitcnt lgkmcnt(0)
; #define LAS __attribute__((address_space(3)))
; __device__ __forceinline__ void transpose_item(const float* W, int ldw, int k0, int n0, bf16* WT, int Kdst, int dst_row0, LAS float* scr, int lane) {
;     float tv[32];
; #pragma unroll
;     for (int i = 0; i < 32; ++i) { const int kk = 2 * i + (lane >> 5); tv[i] = W[(size_t)(k0 + kk) * ldw + n0 + (lane & 31)]; }
; __device__ __forceinline__ void phase_wconv(const Frame& F, const Args& a, int l, unsigned char* wt, unsigned char* wth, int part) {
;     ...
;             if (mm < 2) {
;                 const float* W = a.in[F.z + (f ? 26 : 3) + mm] + (size_t)l * D * FF;
;                 const int kb = q / 176, nb = q % 176, n0 = 32 * nb;
;                 bf16* dst = (bf16*)(f ? wth + WO_UP2 : wt + WO_UP1);
;                 transpose_item(W, FF, 64 * kb, n0, dst, D, (n0 / 128) * 256 + mm * 128 + (n0 % 128), scr, F.lane);
.LBB0_735:
	s_andn2_b64 vcc, exec, s[16:17]
	s_cbranch_vccnz .LBB0_702
	s_add_i32 s16, s27, s20
	s_ashr_i32 s17, s16, 31
	s_lshl_b64 s[16:17], s[16:17], 3
	v_readlane_b32 s18, v254, 1
	v_readlane_b32 s19, v254, 2
	s_add_u32 s16, s18, s16
	s_addc_u32 s17, s19, s17
	s_load_dwordx2 s[16:17], s[16:17], 0x0
	v_readlane_b32 s18, v254, 26
	v_readlane_b32 s19, v254, 27
	s_lshl_b64 s[18:19], s[18:19], 2
	s_waitcnt lgkmcnt(0)
	s_add_u32 s31, s16, s18
	s_mul_i32 s16, s21, 0xba3
	s_addc_u32 s17, s17, s19
	s_lshr_b32 s18, s16, 31
	s_ashr_i32 s16, s16, 19
	s_add_i32 s16, s16, s18
	s_mul_i32 s18, s16, 0xb0
	s_sub_i32 s18, s21, s18
	s_sext_i32_i16 s19, s18
	s_bfe_u32 s21, s19, 0x2001d
	s_lshl_b32 s34, s19, 5
	s_add_i32 s18, s18, s21
	s_bfe_u32 s19, s19, 0x70013
	s_sext_i32_i16 s18, s18
	s_add_i32 s19, s34, s19
	s_lshl_b32 s18, s18, 6
	s_and_b32 s19, s19, 0xff80
	s_and_b32 s18, s18, 0xffffff00
	s_lshl_b32 s20, s20, 7
	s_sub_i32 s19, s34, s19
	s_add_i32 s18, s18, s20
	s_sext_i32_i16 s19, s19
	s_ashr_i32 s35, s34, 31
	s_lshl_b32 s16, s16, 6
	s_add_i32 s18, s18, s19
	s_lshl_b64 s[20:21], s[34:35], 2
	v_or_b32_e32 v18, s16, v1
	s_add_u32 s20, s31, s20
	s_addc_u32 s21, s17, s21
	v_mul_i32_i24_e32 v18, 0x5800, v18
	v_lshl_add_u64 v[16:17], s[20:21], 0, v[184:185]
	v_ashrrev_i32_e32 v19, 31, v18
	v_lshl_add_u64 v[16:17], v[16:17], 0, v[18:19]
	s_mov_b32 s17, 0xb000
	v_add_co_u32_e32 v18, vcc, s17, v16
	s_mov_b32 s17, 0x16000
	s_nop 0
	v_addc_co_u32_e32 v19, vcc, 0, v17, vcc
	global_load_dword v32, v[16:17], off nt
	global_load_dword v33, v[18:19], off nt
	v_add_co_u32_e32 v18, vcc, s17, v16
	s_mov_b32 s17, 0x21000
	s_nop 0
	v_addc_co_u32_e32 v19, vcc, 0, v17, vcc
	global_load_dword v34, v[18:19], off nt
	v_add_co_u32_e32 v18, vcc, s17, v16
	s_mov_b32 s17, 0x2c000
	s_nop 0
	v_addc_co_u32_e32 v19, vcc, 0, v17, vcc
	global_load_dword v35, v[18:19], off nt
	v_add_co_u32_e32 v18, vcc, s17, v16
	s_mov_b32 s17, 0x37000
	s_nop 0
	v_addc_co_u32_e32 v19, vcc, 0, v17, vcc
	global_load_dword v36, v[18:19], off nt
	v_add_co_u32_e32 v18, vcc, s17, v16
	s_mov_b32 s17, 0x42000
	s_nop 0
	v_addc_co_u32_e32 v19, vcc, 0, v17, vcc
	global_load_dword v37, v[18:19], off nt
	v_add_co_u32_e32 v18, vcc, s17, v16
	s_mov_b32 s17, 0x4d000
	s_nop 0
	v_addc_co_u32_e32 v19, vcc, 0, v17, vcc
	global_load_dword v38, v[18:19], off nt
	v_add_co_u32_e32 v18, vcc, s17, v16
	s_mov_b32 s17, 0x58000
	s_nop 0
	v_addc_co_u32_e32 v19, vcc, 0, v17, vcc
	global_load_dword v39, v[18:19], off nt
	v_add_co_u32_e32 v18, vcc, s17, v16
	s_mov_b32 s17, 0x63000
	s_nop 0
	v_addc_co_u32_e32 v19, vcc, 0, v17, vcc
	global_load_dword v40, v[18:19], off nt
	v_add_co_u32_e32 v18, vcc, s17, v16
	s_mov_b32 s17, 0x6e000
	s_nop 0
	v_addc_co_u32_e32 v19, vcc, 0, v17, vcc
	global_load_dword v41, v[18:19], off nt
	v_add_co_u32_e32 v18, vcc, s17, v16
	s_mov_b32 s17, 0x79000
	s_nop 0
	v_addc_co_u32_e32 v19, vcc, 0, v17, vcc
	global_load_dword v42, v[18:19], off nt
	v_add_co_u32_e32 v18, vcc, s17, v16
	s_mov_b32 s17, 0x84000
	s_nop 0
	v_addc_co_u32_e32 v19, vcc, 0, v17, vcc
	global_load_dword v43, v[18:19], off nt
	v_add_co_u32_e32 v18, vcc, s17, v16
	s_mov_b32 s17, 0x8f000
	s_nop 0
	v_addc_co_u32_e32 v19, vcc, 0, v17, vcc
	global_load_dword v44, v[18:19], off nt
	v_add_co_u32_e32 v18, vcc, s17, v16
	s_mov_b32 s17, 0x9a000
	s_nop 0
	v_addc_co_u32_e32 v19, vcc, 0, v17, vcc
	global_load_dword v45, v[18:19], off nt
	v_add_co_u32_e32 v18, vcc, s17, v16
	s_mov_b32 s17, 0xa5000
	s_nop 0
	v_addc_co_u32_e32 v19, vcc, 0, v17, vcc
	global_load_dword v46, v[18:19], off nt
	v_add_co_u32_e32 v18, vcc, s17, v16
	s_mov_b32 s17, 0xb0000
	s_nop 0
	v_addc_co_u32_e32 v19, vcc, 0, v17, vcc
	global_load_dword v47, v[18:19], off nt
	v_add_co_u32_e32 v18, vcc, s17, v16
	s_mov_b32 s17, 0xbb000
	s_nop 0
	v_addc_co_u32_e32 v19, vcc, 0, v17, vcc
	global_load_dword v48, v[18:19], off nt
	v_add_co_u32_e32 v18, vcc, s17, v16
	s_mov_b32 s17, 0xc6000
	s_nop 0
	v_addc_co_u32_e32 v19, vcc, 0, v17, vcc
	global_load_dword v49, v[18:19], off nt
	v_add_co_u32_e32 v18, vcc, s17, v16
	s_mov_b32 s17, 0xd1000
	s_nop 0
	v_addc_co_u32_e32 v19, vcc, 0, v17, vcc
	global_load_dword v50, v[18:19], off nt
	v_add_co_u32_e32 v18, vcc, s17, v16
	s_mov_b32 s17, 0xdc000
	s_nop 0
	v_addc_co_u32_e32 v19, vcc, 0, v17, vcc
	global_load_dword v51, v[18:19], off nt
	v_add_co_u32_e32 v18, vcc, s17, v16
	s_mov_b32 s17, 0xe7000
	s_nop 0
	v_addc_co_u32_e32 v19, vcc, 0, v17, vcc
	global_load_dword v52, v[18:19], off nt
	v_add_co_u32_e32 v18, vcc, s17, v16
	s_mov_b32 s17, 0xf2000
	s_nop 0
	v_addc_co_u32_e32 v19, vcc, 0, v17, vcc
	global_load_dword v53, v[18:19], off nt
	v_add_co_u32_e32 v18, vcc, s17, v16
	s_mov_b32 s17, 0xfd000
	s_nop 0
	v_addc_co_u32_e32 v19, vcc, 0, v17, vcc
	global_load_dword v54, v[18:19], off nt
	v_add_co_u32_e32 v18, vcc, s17, v16
	s_mov_b32 s17, 0x108000
	s_nop 0
	v_addc_co_u32_e32 v19, vcc, 0, v17, vcc
	global_load_dword v55, v[18:19], off nt
	v_add_co_u32_e32 v18, vcc, s17, v16
	s_mov_b32 s17, 0x113000
	s_nop 0
	v_addc_co_u32_e32 v19, vcc, 0, v17, vcc
	global_load_dword v56, v[18:19], off nt
	v_add_co_u32_e32 v18, vcc, s17, v16
	s_mov_b32 s17, 0x11e000
	s_nop 0
	v_addc_co_u32_e32 v19, vcc, 0, v17, vcc
	global_load_dword v57, v[18:19], off nt
	v_add_co_u32_e32 v18, vcc, s17, v16
	s_mov_b32 s17, 0x129000
	s_nop 0
	v_addc_co_u32_e32 v19, vcc, 0, v17, vcc
	global_load_dword v58, v[18:19], off nt
	v_add_co_u32_e32 v18, vcc, s17, v16
	s_mov_b32 s17, 0x134000
	s_nop 0
	v_addc_co_u32_e32 v19, vcc, 0, v17, vcc
	global_load_dword v59, v[18:19], off nt
	v_add_co_u32_e32 v18, vcc, s17, v16
	s_mov_b32 s17, 0x13f000
	s_nop 0
	v_addc_co_u32_e32 v19, vcc, 0, v17, vcc
	global_load_dword v60, v[18:19], off nt
	v_add_co_u32_e32 v18, vcc, s17, v16
	s_mov_b32 s17, 0x14a000
	s_nop 0
	v_addc_co_u32_e32 v19, vcc, 0, v17, vcc
	global_load_dword v61, v[18:19], off nt
	v_add_co_u32_e32 v18, vcc, s17, v16
	s_mov_b32 s17, 0x155000
	s_nop 0
	v_addc_co_u32_e32 v19, vcc, 0, v17, vcc
	v_add_co_u32_e32 v16, vcc, s17, v16
	global_load_dword v18, v[18:19], off nt
	s_nop 0
	v_addc_co_u32_e32 v17, vcc, 0, v17, vcc
	global_load_dword v16, v[16:17], off nt
	s_waitcnt vmcnt(30)
; #define LAS __attribute__((address_space(3)))
; #define LDS_WAIT() asm volatile("s_waitcnt lgkmcnt(0)" ::: "memory")
; __device__ __forceinline__ unsigned pk2(float lo, float hi) { return cvt_pk_bf16(lo, hi); }
; __device__ __forceinline__ void transpose_item(const float* W, int ldw, int k0, int n0, bf16* WT, int Kdst, int dst_row0, LAS float* scr, int lane) {
;     ...
;     for (int i = 0; i < 32; ++i) { const int kk = 2 * i + (lane >> 5); scr[kk * 33 + (lane & 31)] = tv[i]; }
;     LDS_WAIT(); asm volatile("" ::: "memory");
;     const int c = lane & 7;
; #pragma unroll
;     for (int j = 0; j < 4; ++j) { const int n = (lane >> 3) + 8 * j; const LAS float* s = scr + (8 * c) * 33 + n;
;         v4u o; o.x = pk2(s[0 * 33], s[1 * 33]); o.y = pk2(s[2 * 33], s[3 * 33]); o.z = pk2(s[4 * 33], s[5 * 33]); o.w = pk2(s[6 * 33], s[7 * 33]);
;         *(v4u*)(WT + (size_t)(dst_row0 + n) * Kdst + k0 + 8 * c) = o; }
;     LDS_WAIT(); asm volatile("" ::: "memory");
	ds_write2_b32 v20, v32, v33 offset1:66
	s_waitcnt vmcnt(28)
	ds_write2_b32 v20, v34, v35 offset0:132 offset1:198
	s_waitcnt vmcnt(26)
	ds_write2_b32 v31, v36, v37 offset0:8 offset1:74
	s_waitcnt vmcnt(24)
	ds_write2_b32 v31, v38, v39 offset0:140 offset1:206
	s_waitcnt vmcnt(22)
	ds_write2_b32 v30, v40, v41 offset0:16 offset1:82
	s_waitcnt vmcnt(20)
	ds_write2_b32 v30, v42, v43 offset0:148 offset1:214
	s_waitcnt vmcnt(18)
	ds_write2_b32 v29, v44, v45 offset0:24 offset1:90
	s_waitcnt vmcnt(16)
	ds_write2_b32 v29, v46, v47 offset0:156 offset1:222
	s_waitcnt vmcnt(14)
	ds_write2_b32 v28, v48, v49 offset0:32 offset1:98
	s_waitcnt vmcnt(12)
	ds_write2_b32 v28, v50, v51 offset0:164 offset1:230
	s_waitcnt vmcnt(10)
	ds_write2_b32 v27, v52, v53 offset0:40 offset1:106
	s_waitcnt vmcnt(8)
	ds_write2_b32 v27, v54, v55 offset0:172 offset1:238
	s_waitcnt vmcnt(6)
	ds_write2_b32 v26, v56, v57 offset0:48 offset1:114
	s_waitcnt vmcnt(4)
	ds_write2_b32 v26, v58, v59 offset0:180 offset1:246
	s_waitcnt vmcnt(2)
	ds_write2_b32 v15, v60, v61 offset0:56 offset1:122
	s_waitcnt vmcnt(0)
	ds_write2_b32 v15, v18, v16 offset0:188 offset1:254
	s_waitcnt lgkmcnt(0)
	ds_read2_b32 v[28:29], v22 offset0:33 offset1:41
	ds_read2_b32 v[30:31], v22 offset1:8
	ds_read2_b32 v[32:33], v22 offset0:66 offset1:74
	ds_read2_b32 v[34:35], v22 offset0:99 offset1:107
	ds_read2_b32 v[36:37], v22 offset0:132 offset1:140
	ds_read2_b32 v[38:39], v22 offset0:165 offset1:173
	ds_read2_b32 v[40:41], v22 offset0:198 offset1:206
	ds_read2_b32 v[42:43], v22 offset0:231 offset1:239
	v_or_b32_e32 v44, s18, v21
	s_ashr_i32 s17, s16, 31
	v_ashrrev_i32_e32 v45, 31, v44
	v_lshl_add_u64 v[26:27], s[16:17], 1, v[12:13]
	v_lshlrev_b64 v[44:45], 12, v[44:45]
	s_waitcnt lgkmcnt(6)
	v_cvt_pk_bf16_f32 v16, v30, v28
	s_waitcnt lgkmcnt(4)
	v_cvt_pk_bf16_f32 v17, v32, v34
	s_waitcnt lgkmcnt(2)
	v_cvt_pk_bf16_f32 v18, v36, v38
	s_waitcnt lgkmcnt(0)
	v_cvt_pk_bf16_f32 v19, v40, v42
	v_lshl_add_u64 v[44:45], v[26:27], 0, v[44:45]
	v_or_b32_e32 v28, s18, v23
	global_store_dwordx4 v[44:45], v[16:19], off
	v_or_b32_e32 v44, s18, v24
	v_ashrrev_i32_e32 v45, 31, v44
	v_cvt_pk_bf16_f32 v16, v31, v29
	v_ashrrev_i32_e32 v29, 31, v28
	v_lshlrev_b64 v[28:29], 12, v[28:29]
	v_cvt_pk_bf16_f32 v17, v33, v35
	v_cvt_pk_bf16_f32 v18, v37, v39
	v_cvt_pk_bf16_f32 v19, v41, v43
	v_lshl_add_u64 v[28:29], v[26:27], 0, v[28:29]
	global_store_dwordx4 v[28:29], v[16:19], off
	ds_read2_b32 v[28:29], v22 offset0:49 offset1:57
	ds_read2_b32 v[30:31], v22 offset0:16 offset1:24
	ds_read2_b32 v[32:33], v22 offset0:82 offset1:90
	ds_read2_b32 v[34:35], v22 offset0:115 offset1:123
	ds_read2_b32 v[36:37], v22 offset0:148 offset1:156
	ds_read2_b32 v[38:39], v22 offset0:181 offset1:189
	ds_read2_b32 v[40:41], v22 offset0:214 offset1:222
	ds_read2_b32 v[42:43], v22 offset0:247 offset1:255
	v_lshlrev_b64 v[44:45], 12, v[44:45]
	s_waitcnt lgkmcnt(6)
	v_cvt_pk_bf16_f32 v16, v30, v28
	s_waitcnt lgkmcnt(4)
	v_cvt_pk_bf16_f32 v17, v32, v34
	s_waitcnt lgkmcnt(2)
	v_cvt_pk_bf16_f32 v18, v36, v38
	s_waitcnt lgkmcnt(0)
	v_cvt_pk_bf16_f32 v19, v40, v42
	v_lshl_add_u64 v[44:45], v[26:27], 0, v[44:45]
	v_or_b32_e32 v28, s18, v25
	global_store_dwordx4 v[44:45], v[16:19], off
	s_nop 1
	v_cvt_pk_bf16_f32 v16, v31, v29
	v_ashrrev_i32_e32 v29, 31, v28
	v_lshlrev_b64 v[28:29], 12, v[28:29]
	v_cvt_pk_bf16_f32 v17, v33, v35
	v_cvt_pk_bf16_f32 v18, v37, v39
	v_cvt_pk_bf16_f32 v19, v41, v43
	v_lshl_add_u64 v[26:27], v[26:27], 0, v[28:29]
	global_store_dwordx4 v[26:27], v[16:19], off
	s_waitcnt lgkmcnt(0)
	s_branch .LBB0_702

; #define LAS __attribute__((address_space(3)))
; __device__ __forceinline__ void transpose_item(const float* W, int ldw, int k0, int n0, bf16* WT, int Kdst, int dst_row0, LAS float* scr, int lane) {
;     float tv[32];
; #pragma unroll
;     for (int i = 0; i < 32; ++i) { const int kk = 2 * i + (lane >> 5); tv[i] = W[(size_t)(k0 + kk) * ldw + n0 + (lane & 31)]; }
; __device__ __forceinline__ void phase_wconv(const Frame& F, const Args& a, int l, unsigned char* wt, unsigned char* wth, int part) {
;     ...
;         if (r < I_IN) {
;             const float* W = a.in[F.z + 7] + (size_t)l * D * 15744;
;             const int kb = r / 492, nb = r % 492, n0 = 32 * nb;
;             if (!(((n0 >= 7680 && n0 < 9600) ? 1 : 2) & part)) continue;
;             bf16* dst; int row;
;             if (n0 < 4608) { dst = (bf16*)(wth + WO_ATT); row = n0; }
;             else if (n0 < 7680) { dst = (bf16*)(wth + WO_RET); row = n0 - 4608; }
;             else if (n0 < 9600) { dst = (bf16*)(wth + WO_CF); row = n0 - 7680; }
;             else { dst = (bf16*)(wth + WO_GATE); row = n0 - 9600; }
;             transpose_item(W, 15744, 64 * kb, n0, dst, D, row, scr, F.lane);
.LBB0_744:
	s_cmp_gt_i32 s23, 0x83ff
	s_mov_b64 s[6:7], -1
	s_cbranch_scc0 .LBB0_749
	s_mov_b64 s[6:7], 0
	s_cmpk_gt_u32 s23, 0xc17f
	s_mov_b64 s[8:9], 0
	s_cbranch_scc1 .LBB0_749
	s_add_i32 s8, s23, 0x7c00
	s_bfe_u32 s9, s8, 0xe0002
	s_mulk_i32 s9, 0x429b
	s_lshr_b32 s12, s9, 21
	s_mul_i32 s9, s12, 0x1ec
	s_sub_i32 s8, s8, s9
	s_add_i32 s9, s8, 0xfed4
	s_and_b32 s9, s9, 0xffff
	s_cmpk_lt_u32 s9, 0xffc4
	s_cbranch_scc1 .LBB0_748
	s_and_b32 s9, 0xffff, s8
	s_lshl_b32 s8, s8, 5
	s_and_b32 s13, s8, 0xffe0
	s_cmpk_lt_u32 s9, 0x12c
	s_load_dwordx2 s[14:15], s[4:5], 0x38
	s_mov_b32 s9, 0xa400000
	s_movk_i32 s8, 0xe200
	s_cselect_b32 s9, s9, 0xac00000
	s_cselect_b32 s8, s8, 0xffffda80
	s_add_u32 s9, s50, s9
	s_addc_u32 s11, s51, 0
	s_lshl_b32 s12, s12, 6
	s_add_i32 s8, s8, s13
	s_and_b32 s12, s12, 0x3fc0
	s_lshl_b32 s13, s13, 2
	s_waitcnt lgkmcnt(0)
	s_add_u32 s14, s14, s13
	v_or_b32_e32 v7, s12, v1
	s_addc_u32 s15, s15, 0
	v_lshlrev_b32_e32 v184, 2, v0
	v_lshl_add_u64 v[8:9], s[14:15], 0, v[184:185]
	v_mul_u32_u24_e32 v184, 0xf600, v7
	v_lshl_add_u64 v[8:9], v[8:9], 0, v[184:185]
	s_mov_b32 s13, 0x7b00000
	v_add_co_u32_e32 v10, vcc, s13, v8
	s_mov_b32 s13, 0x7b1e000
	s_nop 0
	v_addc_co_u32_e32 v11, vcc, 0, v9, vcc
	global_load_dword v7, v[10:11], off nt
	v_add_co_u32_e32 v10, vcc, s13, v8
	s_mov_b32 s13, 0x7b3d000
	s_nop 0
	v_addc_co_u32_e32 v11, vcc, 0, v9, vcc
	global_load_dword v18, v[10:11], off offset:3072 nt
	v_add_co_u32_e32 v10, vcc, s13, v8
	s_mov_b32 s13, 0x7b5c000
	s_nop 0
	v_addc_co_u32_e32 v11, vcc, 0, v9, vcc
	global_load_dword v19, v[10:11], off offset:2048 nt
	v_add_co_u32_e32 v10, vcc, s13, v8
	s_mov_b32 s13, 0x7b7b000
	s_nop 0
	v_addc_co_u32_e32 v11, vcc, 0, v9, vcc
	global_load_dword v20, v[10:11], off offset:1024 nt
	v_add_co_u32_e32 v10, vcc, s13, v8
	s_mov_b32 s13, 0x7b99000
	s_nop 0
	v_addc_co_u32_e32 v11, vcc, 0, v9, vcc
	global_load_dword v21, v[10:11], off nt
	v_add_co_u32_e32 v10, vcc, s13, v8
	s_mov_b32 s13, 0x7bb8000
	s_nop 0
	v_addc_co_u32_e32 v11, vcc, 0, v9, vcc
	global_load_dword v22, v[10:11], off offset:3072 nt
	v_add_co_u32_e32 v10, vcc, s13, v8
	s_mov_b32 s13, 0x7bd7000
	s_nop 0
	v_addc_co_u32_e32 v11, vcc, 0, v9, vcc
	global_load_dword v23, v[10:11], off offset:2048 nt
	v_add_co_u32_e32 v10, vcc, s13, v8
	s_mov_b32 s13, 0x7bf6000
	s_nop 0
	v_addc_co_u32_e32 v11, vcc, 0, v9, vcc
	global_load_dword v24, v[10:11], off offset:1024 nt
	v_add_co_u32_e32 v10, vcc, s13, v8
	s_mov_b32 s13, 0x7c14000
	s_nop 0
	v_addc_co_u32_e32 v11, vcc, 0, v9, vcc
	global_load_dword v25, v[10:11], off nt
	v_add_co_u32_e32 v10, vcc, s13, v8
	s_mov_b32 s13, 0x7c33000
	s_nop 0
	v_addc_co_u32_e32 v11, vcc, 0, v9, vcc
	global_load_dword v26, v[10:11], off offset:3072 nt
	v_add_co_u32_e32 v10, vcc, s13, v8
	s_mov_b32 s13, 0x7c52000
	s_nop 0
	v_addc_co_u32_e32 v11, vcc, 0, v9, vcc
	global_load_dword v27, v[10:11], off offset:2048 nt
	v_add_co_u32_e32 v10, vcc, s13, v8
	s_mov_b32 s13, 0x7c71000
	s_nop 0
	v_addc_co_u32_e32 v11, vcc, 0, v9, vcc
	global_load_dword v28, v[10:11], off offset:1024 nt
	v_add_co_u32_e32 v10, vcc, s13, v8
	s_mov_b32 s13, 0x7c8f000
	s_nop 0
	v_addc_co_u32_e32 v11, vcc, 0, v9, vcc
	global_load_dword v29, v[10:11], off nt
	v_add_co_u32_e32 v10, vcc, s13, v8
	s_mov_b32 s13, 0x7cae000
	s_nop 0
	v_addc_co_u32_e32 v11, vcc, 0, v9, vcc
	global_load_dword v30, v[10:11], off offset:3072 nt
	v_add_co_u32_e32 v10, vcc, s13, v8
	s_mov_b32 s13, 0x7ccd000
	s_nop 0
	v_addc_co_u32_e32 v11, vcc, 0, v9, vcc
	global_load_dword v31, v[10:11], off offset:2048 nt
	v_add_co_u32_e32 v10, vcc, s13, v8
	s_mov_b32 s13, 0x7cec000
	s_nop 0
	v_addc_co_u32_e32 v11, vcc, 0, v9, vcc
	global_load_dword v32, v[10:11], off offset:1024 nt
	v_add_co_u32_e32 v10, vcc, s13, v8
	s_mov_b32 s13, 0x7d0a000
	s_nop 0
	v_addc_co_u32_e32 v11, vcc, 0, v9, vcc
	global_load_dword v33, v[10:11], off nt
	v_add_co_u32_e32 v10, vcc, s13, v8
	s_mov_b32 s13, 0x7d29000
	s_nop 0
	v_addc_co_u32_e32 v11, vcc, 0, v9, vcc
	global_load_dword v34, v[10:11], off offset:3072 nt
	v_add_co_u32_e32 v10, vcc, s13, v8
	s_mov_b32 s13, 0x7d48000
	s_nop 0
	v_addc_co_u32_e32 v11, vcc, 0, v9, vcc
	global_load_dword v35, v[10:11], off offset:2048 nt
	v_add_co_u32_e32 v10, vcc, s13, v8
	s_mov_b32 s13, 0x7d67000
	s_nop 0
	v_addc_co_u32_e32 v11, vcc, 0, v9, vcc
	global_load_dword v36, v[10:11], off offset:1024 nt
	v_add_co_u32_e32 v10, vcc, s13, v8
	s_mov_b32 s13, 0x7d85000
	s_nop 0
	v_addc_co_u32_e32 v11, vcc, 0, v9, vcc
	global_load_dword v37, v[10:11], off nt
	v_add_co_u32_e32 v10, vcc, s13, v8
	s_mov_b32 s13, 0x7da4000
	s_nop 0
	v_addc_co_u32_e32 v11, vcc, 0, v9, vcc
	global_load_dword v38, v[10:11], off offset:3072 nt
	v_add_co_u32_e32 v10, vcc, s13, v8
	s_mov_b32 s13, 0x7dc3000
	s_nop 0
	v_addc_co_u32_e32 v11, vcc, 0, v9, vcc
	global_load_dword v39, v[10:11], off offset:2048 nt
	v_add_co_u32_e32 v10, vcc, s13, v8
	s_mov_b32 s13, 0x7de2000
	s_nop 0
	v_addc_co_u32_e32 v11, vcc, 0, v9, vcc
	global_load_dword v40, v[10:11], off offset:1024 nt
	v_add_co_u32_e32 v10, vcc, s13, v8
	s_mov_b32 s13, 0x7e00000
	s_nop 0
	v_addc_co_u32_e32 v11, vcc, 0, v9, vcc
	global_load_dword v41, v[10:11], off nt
	v_add_co_u32_e32 v10, vcc, s13, v8
	s_mov_b32 s13, 0x7e1f000
	s_nop 0
	v_addc_co_u32_e32 v11, vcc, 0, v9, vcc
	global_load_dword v42, v[10:11], off offset:3072 nt
	v_add_co_u32_e32 v10, vcc, s13, v8
	s_mov_b32 s13, 0x7e3e000
	s_nop 0
	v_addc_co_u32_e32 v11, vcc, 0, v9, vcc
	global_load_dword v43, v[10:11], off offset:2048 nt
	v_add_co_u32_e32 v10, vcc, s13, v8
	s_mov_b32 s13, 0x7e5d000
	s_nop 0
	v_addc_co_u32_e32 v11, vcc, 0, v9, vcc
	global_load_dword v44, v[10:11], off offset:1024 nt
	v_add_co_u32_e32 v10, vcc, s13, v8
	s_mov_b32 s13, 0x7e7b000
	s_nop 0
	v_addc_co_u32_e32 v11, vcc, 0, v9, vcc
	global_load_dword v45, v[10:11], off nt
	v_add_co_u32_e32 v10, vcc, s13, v8
	s_mov_b32 s13, 0x7e9a000
	s_nop 0
	v_addc_co_u32_e32 v11, vcc, 0, v9, vcc
	global_load_dword v46, v[10:11], off offset:3072 nt
	v_add_co_u32_e32 v10, vcc, s13, v8
	s_mov_b32 s13, 0x7eb9000
	s_nop 0
	v_addc_co_u32_e32 v11, vcc, 0, v9, vcc
	v_add_co_u32_e32 v8, vcc, s13, v8
	global_load_dword v10, v[10:11], off offset:2048 nt
	s_nop 0
	v_addc_co_u32_e32 v9, vcc, 0, v9, vcc
	global_load_dword v8, v[8:9], off offset:1024 nt
	s_waitcnt vmcnt(30)
; #define LAS __attribute__((address_space(3)))
; #define LDS_WAIT() asm volatile("s_waitcnt lgkmcnt(0)" ::: "memory")
; __device__ __forceinline__ unsigned pk2(float lo, float hi) { return cvt_pk_bf16(lo, hi); }
; __device__ __forceinline__ void transpose_item(const float* W, int ldw, int k0, int n0, bf16* WT, int Kdst, int dst_row0, LAS float* scr, int lane) {
;     ...
;     for (int i = 0; i < 32; ++i) { const int kk = 2 * i + (lane >> 5); scr[kk * 33 + (lane & 31)] = tv[i]; }
;     LDS_WAIT(); asm volatile("" ::: "memory");
;     const int c = lane & 7;
; #pragma unroll
;     for (int j = 0; j < 4; ++j) { const int n = (lane >> 3) + 8 * j; const LAS float* s = scr + (8 * c) * 33 + n;
;         v4u o; o.x = pk2(s[0 * 33], s[1 * 33]); o.y = pk2(s[2 * 33], s[3 * 33]); o.z = pk2(s[4 * 33], s[5 * 33]); o.w = pk2(s[6 * 33], s[7 * 33]);
;         *(v4u*)(WT + (size_t)(dst_row0 + n) * Kdst + k0 + 8 * c) = o; }
;     LDS_WAIT(); asm volatile("" ::: "memory");
	ds_write2_b32 v12, v7, v18 offset1:66
	s_waitcnt vmcnt(28)
	ds_write2_b32 v12, v19, v20 offset0:132 offset1:198
	v_add_u32_e32 v7, 0x400, v12
	s_waitcnt vmcnt(26)
	ds_write2_b32 v7, v21, v22 offset0:8 offset1:74
	s_waitcnt vmcnt(24)
	ds_write2_b32 v7, v23, v24 offset0:140 offset1:206
	v_add_u32_e32 v7, 0x800, v12
	s_waitcnt vmcnt(22)
	ds_write2_b32 v7, v25, v26 offset0:16 offset1:82
	s_waitcnt vmcnt(20)
	ds_write2_b32 v7, v27, v28 offset0:148 offset1:214
	v_add_u32_e32 v7, 0xc00, v12
	s_waitcnt vmcnt(18)
	ds_write2_b32 v7, v29, v30 offset0:24 offset1:90
	s_waitcnt vmcnt(16)
	ds_write2_b32 v7, v31, v32 offset0:156 offset1:222
	v_add_u32_e32 v7, 0x1000, v12
	s_waitcnt vmcnt(14)
	ds_write2_b32 v7, v33, v34 offset0:32 offset1:98
	s_waitcnt vmcnt(12)
	ds_write2_b32 v7, v35, v36 offset0:164 offset1:230
	v_add_u32_e32 v7, 0x1400, v12
	s_waitcnt vmcnt(10)
	ds_write2_b32 v7, v37, v38 offset0:40 offset1:106
	s_waitcnt vmcnt(8)
	ds_write2_b32 v7, v39, v40 offset0:172 offset1:238
	v_add_u32_e32 v7, 0x1800, v12
	s_waitcnt vmcnt(6)
	ds_write2_b32 v7, v41, v42 offset0:48 offset1:114
	s_waitcnt vmcnt(4)
	ds_write2_b32 v7, v43, v44 offset0:180 offset1:246
	v_add_u32_e32 v7, 0x1c00, v12
	s_waitcnt vmcnt(2)
	ds_write2_b32 v7, v45, v46 offset0:56 offset1:122
	s_waitcnt vmcnt(0)
	ds_write2_b32 v7, v10, v8 offset0:188 offset1:254
	s_waitcnt lgkmcnt(0)
	ds_read2_b32 v[20:21], v14 offset0:33 offset1:41
	ds_read2_b32 v[22:23], v14 offset1:8
	ds_read2_b32 v[24:25], v14 offset0:66 offset1:74
	ds_read2_b32 v[26:27], v14 offset0:99 offset1:107
	ds_read2_b32 v[28:29], v14 offset0:132 offset1:140
	ds_read2_b32 v[30:31], v14 offset0:165 offset1:173
	ds_read2_b32 v[32:33], v14 offset0:198 offset1:206
	ds_read2_b32 v[34:35], v14 offset0:231 offset1:239
	s_lshl_b32 s12, s12, 1
	s_add_u32 s12, s9, s12
	v_or_b32_e32 v36, s8, v13
	s_addc_u32 s13, s11, 0
	v_mov_b32_e32 v7, v185
	v_ashrrev_i32_e32 v37, 31, v36
	v_lshl_add_u64 v[18:19], s[12:13], 0, v[6:7]
	v_lshlrev_b64 v[36:37], 12, v[36:37]
	s_waitcnt lgkmcnt(6)
	v_cvt_pk_bf16_f32 v8, v22, v20
	s_waitcnt lgkmcnt(4)
	v_cvt_pk_bf16_f32 v9, v24, v26
	s_waitcnt lgkmcnt(2)
	v_cvt_pk_bf16_f32 v10, v28, v30
	s_waitcnt lgkmcnt(0)
	v_cvt_pk_bf16_f32 v11, v32, v34
	v_lshl_add_u64 v[36:37], v[18:19], 0, v[36:37]
	v_or_b32_e32 v20, s8, v15
	global_store_dwordx4 v[36:37], v[8:11], off
	v_or_b32_e32 v36, s8, v16
	v_ashrrev_i32_e32 v37, 31, v36
	v_cvt_pk_bf16_f32 v8, v23, v21
	v_ashrrev_i32_e32 v21, 31, v20
	v_lshlrev_b64 v[20:21], 12, v[20:21]
	v_cvt_pk_bf16_f32 v9, v25, v27
	v_cvt_pk_bf16_f32 v10, v29, v31
	v_cvt_pk_bf16_f32 v11, v33, v35
	v_lshl_add_u64 v[20:21], v[18:19], 0, v[20:21]
	global_store_dwordx4 v[20:21], v[8:11], off
	ds_read2_b32 v[20:21], v14 offset0:49 offset1:57
	ds_read2_b32 v[22:23], v14 offset0:16 offset1:24
	ds_read2_b32 v[24:25], v14 offset0:82 offset1:90
	ds_read2_b32 v[26:27], v14 offset0:115 offset1:123
	ds_read2_b32 v[28:29], v14 offset0:148 offset1:156
	ds_read2_b32 v[30:31], v14 offset0:181 offset1:189
	ds_read2_b32 v[32:33], v14 offset0:214 offset1:222
	ds_read2_b32 v[34:35], v14 offset0:247 offset1:255
	v_lshlrev_b64 v[36:37], 12, v[36:37]
	s_waitcnt lgkmcnt(6)
	v_cvt_pk_bf16_f32 v8, v22, v20
	s_waitcnt lgkmcnt(4)
	v_cvt_pk_bf16_f32 v9, v24, v26
	s_waitcnt lgkmcnt(2)
	v_cvt_pk_bf16_f32 v10, v28, v30
	s_waitcnt lgkmcnt(0)
	v_cvt_pk_bf16_f32 v11, v32, v34
	v_lshl_add_u64 v[36:37], v[18:19], 0, v[36:37]
	v_or_b32_e32 v20, s8, v17
	global_store_dwordx4 v[36:37], v[8:11], off
	s_nop 1
	v_cvt_pk_bf16_f32 v8, v23, v21
	v_ashrrev_i32_e32 v21, 31, v20
	v_lshlrev_b64 v[20:21], 12, v[20:21]
	v_cvt_pk_bf16_f32 v9, v25, v27
	v_cvt_pk_bf16_f32 v10, v29, v31
	v_cvt_pk_bf16_f32 v11, v33, v35
	v_lshl_add_u64 v[18:19], v[18:19], 0, v[20:21]
	global_store_dwordx4 v[18:19], v[8:11], off
	s_waitcnt lgkmcnt(0)

; #define LAS __attribute__((address_space(3)))
; __device__ __forceinline__ void transpose_item(const float* W, int ldw, int k0, int n0, bf16* WT, int Kdst, int dst_row0, LAS float* scr, int lane) {
;     float tv[32];
; #pragma unroll
;     for (int i = 0; i < 32; ++i) { const int kk = 2 * i + (lane >> 5); tv[i] = W[(size_t)(k0 + kk) * ldw + n0 + (lane & 31)]; }
; __device__ __forceinline__ void phase_wconv(const Frame& F, const Args& a, int l, unsigned char* wt, unsigned char* wth, int part) {
;     ...
;     for (int it = F.gw; it < NITEMS; it += F.NGW) {
;         int r = it;
;         if (r < I_A) {
;             const int m = r / I_FF, q = r % I_FF, f = m / 3, mm = m % 3;
;             if (!((f ? 2 : 1) & part)) continue;
;             if (mm < 2) {
;                 const float* W = a.in[F.z + (f ? 26 : 3) + mm] + (size_t)l * D * FF;
;                 const int kb = q / 176, nb = q % 176, n0 = 32 * nb;
;                 bf16* dst = (bf16*)(f ? wth + WO_UP2 : wt + WO_UP1);
;                 transpose_item(W, FF, 64 * kb, n0, dst, D, (n0 / 128) * 256 + mm * 128 + (n0 % 128), scr, F.lane);
;             } else {
;                 const float* W = a.in[F.z + (f ? 28 : 5)] + (size_t)l * FF * D;
;                 const int kb = q / 64, nb = q % 64, n0 = 32 * nb;
;                 bf16* dst = (bf16*)(f ? wth + WO_DN2 : wt + WO_DN1);
;                 transpose_item(W, D, 64 * kb, n0, dst, FF, n0, scr, F.lane);
;             }
.LBB0_749:
	s_andn2_b64 vcc, exec, s[6:7]
	s_cbranch_vccnz .LBB0_743
	s_add_i32 s6, s23, 0xffffbe00
	s_cmp_lt_u32 s6, 0xffff7c01
	s_cbranch_scc1 .LBB0_742
	s_mul_hi_i32 s6, s23, 0x2e8ba2e9
	s_lshr_b32 s7, s6, 31
	s_ashr_i32 s6, s6, 10
	s_add_i32 s6, s6, s7
	s_mul_i32 s7, s6, 0xffffea00
	s_add_i32 s12, s23, s7
	s_mul_hi_i32 s7, s6, 0x55555556
	s_lshr_b32 s8, s7, 31
	s_add_i32 s7, s7, s8
	s_mul_i32 s7, s7, 3
	s_sub_i32 s11, s6, s7
	s_mov_b64 s[6:7], -1
	s_cmp_gt_i32 s11, 1
	v_lshlrev_b32_e32 v184, 2, v0
	v_add_u32_e32 v23, 0x400, v12
	v_add_u32_e32 v22, 0x800, v12
	v_add_u32_e32 v21, 0xc00, v12
	v_add_u32_e32 v20, 0x1000, v12
	v_add_u32_e32 v19, 0x1400, v12
	v_add_u32_e32 v18, 0x1800, v12
	v_add_u32_e32 v7, 0x1c00, v12
	s_cbranch_scc0 .LBB0_753
	s_bfe_u32 s6, s12, 0x60019
	s_add_i32 s6, s12, s6
	s_sext_i32_i16 s7, s6
	s_and_b32 s6, s6, 0xffc0
	s_load_dwordx2 s[14:15], s[4:5], 0x28
	s_sub_i32 s6, s12, s6
	s_sext_i32_i16 s6, s6
	s_lshl_b32 s6, s6, 5
	s_and_b32 s8, s7, 0xffffffc0
	s_ashr_i32 s7, s6, 31
	s_lshl_b64 s[16:17], s[6:7], 2
	s_waitcnt lgkmcnt(0)
	s_add_u32 s14, s14, s16
	v_or_b32_e32 v8, s8, v1
	s_addc_u32 s15, s15, s17
	v_lshl_add_u64 v[10:11], s[14:15], 0, v[184:185]
	s_mov_b64 s[14:15], 0x2c00000
	v_ashrrev_i32_e32 v9, 31, v8
	v_lshl_add_u64 v[10:11], v[10:11], 0, s[14:15]
	v_lshlrev_b64 v[24:25], 13, v[8:9]
	v_lshl_add_u64 v[24:25], v[10:11], 0, v[24:25]
	global_load_dword v26, v[24:25], off nt
	v_or_b32_e32 v24, 2, v8
	v_ashrrev_i32_e32 v25, 31, v24
	v_lshlrev_b64 v[24:25], 13, v[24:25]
	v_lshl_add_u64 v[24:25], v[10:11], 0, v[24:25]
	global_load_dword v27, v[24:25], off nt
	v_or_b32_e32 v24, 4, v8
	v_ashrrev_i32_e32 v25, 31, v24
	v_lshlrev_b64 v[24:25], 13, v[24:25]
	v_lshl_add_u64 v[24:25], v[10:11], 0, v[24:25]
	global_load_dword v28, v[24:25], off nt
	v_or_b32_e32 v24, 6, v8
	v_ashrrev_i32_e32 v25, 31, v24
	v_lshlrev_b64 v[24:25], 13, v[24:25]
	v_lshl_add_u64 v[24:25], v[10:11], 0, v[24:25]
	global_load_dword v29, v[24:25], off nt
	v_or_b32_e32 v24, 8, v8
	v_ashrrev_i32_e32 v25, 31, v24
	v_lshlrev_b64 v[24:25], 13, v[24:25]
	v_lshl_add_u64 v[24:25], v[10:11], 0, v[24:25]
	global_load_dword v30, v[24:25], off nt
	v_or_b32_e32 v24, 10, v8
	v_ashrrev_i32_e32 v25, 31, v24
	v_lshlrev_b64 v[24:25], 13, v[24:25]
	v_lshl_add_u64 v[24:25], v[10:11], 0, v[24:25]
	global_load_dword v31, v[24:25], off nt
	v_or_b32_e32 v24, 12, v8
	v_ashrrev_i32_e32 v25, 31, v24
	v_lshlrev_b64 v[24:25], 13, v[24:25]
	v_lshl_add_u64 v[24:25], v[10:11], 0, v[24:25]
	global_load_dword v32, v[24:25], off nt
	v_or_b32_e32 v24, 14, v8
	v_ashrrev_i32_e32 v25, 31, v24
	v_lshlrev_b64 v[24:25], 13, v[24:25]
	v_lshl_add_u64 v[24:25], v[10:11], 0, v[24:25]
	global_load_dword v33, v[24:25], off nt
	v_or_b32_e32 v24, 16, v8
	v_ashrrev_i32_e32 v25, 31, v24
	v_lshlrev_b64 v[24:25], 13, v[24:25]
	v_lshl_add_u64 v[24:25], v[10:11], 0, v[24:25]
	global_load_dword v34, v[24:25], off nt
	v_or_b32_e32 v24, 18, v8
	v_ashrrev_i32_e32 v25, 31, v24
	v_lshlrev_b64 v[24:25], 13, v[24:25]
	v_lshl_add_u64 v[24:25], v[10:11], 0, v[24:25]
	global_load_dword v35, v[24:25], off nt
	v_or_b32_e32 v24, 20, v8
	v_ashrrev_i32_e32 v25, 31, v24
	v_lshlrev_b64 v[24:25], 13, v[24:25]
	v_lshl_add_u64 v[24:25], v[10:11], 0, v[24:25]
	global_load_dword v36, v[24:25], off nt
	v_or_b32_e32 v24, 22, v8
	v_ashrrev_i32_e32 v25, 31, v24
	v_lshlrev_b64 v[24:25], 13, v[24:25]
	v_lshl_add_u64 v[24:25], v[10:11], 0, v[24:25]
	global_load_dword v37, v[24:25], off nt
	v_or_b32_e32 v24, 24, v8
	v_ashrrev_i32_e32 v25, 31, v24
	v_lshlrev_b64 v[24:25], 13, v[24:25]
	v_lshl_add_u64 v[24:25], v[10:11], 0, v[24:25]
	global_load_dword v38, v[24:25], off nt
	v_or_b32_e32 v24, 26, v8
	v_ashrrev_i32_e32 v25, 31, v24
	v_lshlrev_b64 v[24:25], 13, v[24:25]
	v_lshl_add_u64 v[24:25], v[10:11], 0, v[24:25]
	global_load_dword v39, v[24:25], off nt
	v_or_b32_e32 v24, 28, v8
	v_ashrrev_i32_e32 v25, 31, v24
	v_lshlrev_b64 v[24:25], 13, v[24:25]
	v_lshl_add_u64 v[24:25], v[10:11], 0, v[24:25]
	global_load_dword v40, v[24:25], off nt
	v_or_b32_e32 v24, 30, v8
	v_ashrrev_i32_e32 v25, 31, v24
	v_lshlrev_b64 v[24:25], 13, v[24:25]
	v_lshl_add_u64 v[24:25], v[10:11], 0, v[24:25]
	global_load_dword v41, v[24:25], off nt
	v_or_b32_e32 v24, 32, v8
	v_ashrrev_i32_e32 v25, 31, v24
	v_lshlrev_b64 v[24:25], 13, v[24:25]
	v_lshl_add_u64 v[24:25], v[10:11], 0, v[24:25]
	global_load_dword v42, v[24:25], off nt
	v_or_b32_e32 v24, 34, v8
	v_ashrrev_i32_e32 v25, 31, v24
	v_lshlrev_b64 v[24:25], 13, v[24:25]
	v_lshl_add_u64 v[24:25], v[10:11], 0, v[24:25]
	global_load_dword v43, v[24:25], off nt
	v_or_b32_e32 v24, 36, v8
	v_ashrrev_i32_e32 v25, 31, v24
	v_lshlrev_b64 v[24:25], 13, v[24:25]
	v_lshl_add_u64 v[24:25], v[10:11], 0, v[24:25]
	global_load_dword v44, v[24:25], off nt
	v_or_b32_e32 v24, 38, v8
	v_ashrrev_i32_e32 v25, 31, v24
	v_lshlrev_b64 v[24:25], 13, v[24:25]
	v_lshl_add_u64 v[24:25], v[10:11], 0, v[24:25]
	global_load_dword v45, v[24:25], off nt
	v_or_b32_e32 v24, 40, v8
	v_ashrrev_i32_e32 v25, 31, v24
	v_lshlrev_b64 v[24:25], 13, v[24:25]
	v_lshl_add_u64 v[24:25], v[10:11], 0, v[24:25]
	global_load_dword v46, v[24:25], off nt
	v_or_b32_e32 v24, 42, v8
	v_ashrrev_i32_e32 v25, 31, v24
	v_lshlrev_b64 v[24:25], 13, v[24:25]
	v_lshl_add_u64 v[24:25], v[10:11], 0, v[24:25]
	global_load_dword v47, v[24:25], off nt
	v_or_b32_e32 v24, 44, v8
	v_ashrrev_i32_e32 v25, 31, v24
	v_lshlrev_b64 v[24:25], 13, v[24:25]
	v_lshl_add_u64 v[24:25], v[10:11], 0, v[24:25]
	global_load_dword v48, v[24:25], off nt
	v_or_b32_e32 v24, 46, v8
	v_ashrrev_i32_e32 v25, 31, v24
	v_lshlrev_b64 v[24:25], 13, v[24:25]
	v_lshl_add_u64 v[24:25], v[10:11], 0, v[24:25]
; #define LAS __attribute__((address_space(3)))
; #define LDS_WAIT() asm volatile("s_waitcnt lgkmcnt(0)" ::: "memory")
; __device__ __forceinline__ unsigned pk2(float lo, float hi) { return cvt_pk_bf16(lo, hi); }
; __device__ __forceinline__ void transpose_item(const float* W, int ldw, int k0, int n0, bf16* WT, int Kdst, int dst_row0, LAS float* scr, int lane) {
;     float tv[32];
; #pragma unroll
;     for (int i = 0; i < 32; ++i) { const int kk = 2 * i + (lane >> 5); tv[i] = W[(size_t)(k0 + kk) * ldw + n0 + (lane & 31)]; }
; #pragma unroll
;     for (int i = 0; i < 32; ++i) { const int kk = 2 * i + (lane >> 5); scr[kk * 33 + (lane & 31)] = tv[i]; }
;     LDS_WAIT(); asm volatile("" ::: "memory");
;     const int c = lane & 7;
; #pragma unroll
;     for (int j = 0; j < 4; ++j) { const int n = (lane >> 3) + 8 * j; const LAS float* s = scr + (8 * c) * 33 + n;
;         v4u o; o.x = pk2(s[0 * 33], s[1 * 33]); o.y = pk2(s[2 * 33], s[3 * 33]); o.z = pk2(s[4 * 33], s[5 * 33]); o.w = pk2(s[6 * 33], s[7 * 33]);
;         *(v4u*)(WT + (size_t)(dst_row0 + n) * Kdst + k0 + 8 * c) = o; }
;     LDS_WAIT(); asm volatile("" ::: "memory");
; __device__ __forceinline__ void phase_wconv(const Frame& F, const Args& a, int l, unsigned char* wt, unsigned char* wth, int part) {
;     ...
;             } else {
;                 const float* W = a.in[F.z + (f ? 28 : 5)] + (size_t)l * FF * D;
;                 const int kb = q / 64, nb = q % 64, n0 = 32 * nb;
;                 bf16* dst = (bf16*)(f ? wth + WO_DN2 : wt + WO_DN1);
;                 transpose_item(W, D, 64 * kb, n0, dst, FF, n0, scr, F.lane);
	global_load_dword v49, v[24:25], off nt
	v_or_b32_e32 v24, 48, v8
	v_ashrrev_i32_e32 v25, 31, v24
	v_lshlrev_b64 v[24:25], 13, v[24:25]
	v_lshl_add_u64 v[24:25], v[10:11], 0, v[24:25]
	global_load_dword v50, v[24:25], off nt
	v_or_b32_e32 v24, 50, v8
	v_ashrrev_i32_e32 v25, 31, v24
	v_lshlrev_b64 v[24:25], 13, v[24:25]
	v_lshl_add_u64 v[24:25], v[10:11], 0, v[24:25]
	global_load_dword v51, v[24:25], off nt
	v_or_b32_e32 v24, 52, v8
	v_ashrrev_i32_e32 v25, 31, v24
	v_lshlrev_b64 v[24:25], 13, v[24:25]
	v_lshl_add_u64 v[24:25], v[10:11], 0, v[24:25]
	global_load_dword v52, v[24:25], off nt
	v_or_b32_e32 v24, 54, v8
	v_ashrrev_i32_e32 v25, 31, v24
	v_lshlrev_b64 v[24:25], 13, v[24:25]
	v_lshl_add_u64 v[24:25], v[10:11], 0, v[24:25]
	global_load_dword v53, v[24:25], off nt
	v_or_b32_e32 v24, 56, v8
	v_ashrrev_i32_e32 v25, 31, v24
	v_lshlrev_b64 v[24:25], 13, v[24:25]
	v_lshl_add_u64 v[24:25], v[10:11], 0, v[24:25]
	global_load_dword v54, v[24:25], off nt
	v_or_b32_e32 v24, 58, v8
	v_ashrrev_i32_e32 v25, 31, v24
	v_lshlrev_b64 v[24:25], 13, v[24:25]
	v_lshl_add_u64 v[24:25], v[10:11], 0, v[24:25]
	global_load_dword v55, v[24:25], off nt
	v_or_b32_e32 v24, 60, v8
	v_or_b32_e32 v8, 62, v8
	v_ashrrev_i32_e32 v25, 31, v24
	v_ashrrev_i32_e32 v9, 31, v8
	v_lshlrev_b64 v[24:25], 13, v[24:25]
	v_lshlrev_b64 v[8:9], 13, v[8:9]
	v_lshl_add_u64 v[24:25], v[10:11], 0, v[24:25]
	v_lshl_add_u64 v[8:9], v[10:11], 0, v[8:9]
	global_load_dword v24, v[24:25], off nt
	s_ashr_i32 s9, s8, 31
	global_load_dword v8, v[8:9], off nt
	s_waitcnt vmcnt(30)
	ds_write2_b32 v12, v26, v27 offset1:66
	s_waitcnt vmcnt(28)
	ds_write2_b32 v12, v28, v29 offset0:132 offset1:198
	s_waitcnt vmcnt(26)
	ds_write2_b32 v23, v30, v31 offset0:8 offset1:74
	s_waitcnt vmcnt(24)
	ds_write2_b32 v23, v32, v33 offset0:140 offset1:206
	s_waitcnt vmcnt(22)
	ds_write2_b32 v22, v34, v35 offset0:16 offset1:82
	s_waitcnt vmcnt(20)
	ds_write2_b32 v22, v36, v37 offset0:148 offset1:214
	s_waitcnt vmcnt(18)
	ds_write2_b32 v21, v38, v39 offset0:24 offset1:90
	s_waitcnt vmcnt(16)
	ds_write2_b32 v21, v40, v41 offset0:156 offset1:222
	s_waitcnt vmcnt(14)
	ds_write2_b32 v20, v42, v43 offset0:32 offset1:98
	s_waitcnt vmcnt(12)
	ds_write2_b32 v20, v44, v45 offset0:164 offset1:230
	s_waitcnt vmcnt(10)
	ds_write2_b32 v19, v46, v47 offset0:40 offset1:106
	s_waitcnt vmcnt(8)
	ds_write2_b32 v19, v48, v49 offset0:172 offset1:238
	s_waitcnt vmcnt(6)
	ds_write2_b32 v18, v50, v51 offset0:48 offset1:114
	s_waitcnt vmcnt(4)
	ds_write2_b32 v18, v52, v53 offset0:180 offset1:246
	s_waitcnt vmcnt(2)
	ds_write2_b32 v7, v54, v55 offset0:56 offset1:122
	s_waitcnt vmcnt(0)
	ds_write2_b32 v7, v24, v8 offset0:188 offset1:254
	s_waitcnt lgkmcnt(0)
	ds_read2_b32 v[26:27], v14 offset0:33 offset1:41
	ds_read2_b32 v[28:29], v14 offset1:8
	ds_read2_b32 v[30:31], v14 offset0:66 offset1:74
	ds_read2_b32 v[32:33], v14 offset0:99 offset1:107
	ds_read2_b32 v[34:35], v14 offset0:132 offset1:140
	ds_read2_b32 v[36:37], v14 offset0:165 offset1:173
	ds_read2_b32 v[38:39], v14 offset0:198 offset1:206
	ds_read2_b32 v[40:41], v14 offset0:231 offset1:239
	v_lshl_add_u64 v[24:25], s[8:9], 1, v[2:3]
	s_waitcnt lgkmcnt(6)
	v_cvt_pk_bf16_f32 v8, v28, v26
	v_or_b32_e32 v26, s6, v13
	v_mul_i32_i24_e32 v42, 0x2c00, v26
	v_ashrrev_i32_e32 v43, 31, v42
	v_or_b32_e32 v26, s6, v15
	s_waitcnt lgkmcnt(4)
	v_cvt_pk_bf16_f32 v9, v30, v32
	s_waitcnt lgkmcnt(2)
	v_cvt_pk_bf16_f32 v10, v34, v36
	s_waitcnt lgkmcnt(0)
	v_cvt_pk_bf16_f32 v11, v38, v40
	v_lshl_add_u64 v[42:43], v[24:25], 0, v[42:43]
	v_mul_i32_i24_e32 v26, 0x2c00, v26
	global_store_dwordx4 v[42:43], v[8:11], off
	s_nop 1
	v_cvt_pk_bf16_f32 v8, v29, v27
	v_ashrrev_i32_e32 v27, 31, v26
	v_cvt_pk_bf16_f32 v9, v31, v33
	v_cvt_pk_bf16_f32 v10, v35, v37
	v_cvt_pk_bf16_f32 v11, v39, v41
	v_lshl_add_u64 v[26:27], v[24:25], 0, v[26:27]
	global_store_dwordx4 v[26:27], v[8:11], off
	ds_read2_b32 v[26:27], v14 offset0:16 offset1:24
	ds_read2_b32 v[28:29], v14 offset0:49 offset1:57
	ds_read2_b32 v[30:31], v14 offset0:82 offset1:90
	ds_read2_b32 v[32:33], v14 offset0:115 offset1:123
	ds_read2_b32 v[34:35], v14 offset0:148 offset1:156
	ds_read2_b32 v[36:37], v14 offset0:181 offset1:189
	ds_read2_b32 v[38:39], v14 offset0:214 offset1:222
	ds_read2_b32 v[40:41], v14 offset0:247 offset1:255
	s_waitcnt lgkmcnt(6)
	v_cvt_pk_bf16_f32 v8, v26, v28
	v_or_b32_e32 v26, s6, v16
	v_mul_i32_i24_e32 v42, 0x2c00, v26
	v_ashrrev_i32_e32 v43, 31, v42
	v_or_b32_e32 v26, s6, v17
	s_waitcnt lgkmcnt(4)
	v_cvt_pk_bf16_f32 v9, v30, v32
	s_waitcnt lgkmcnt(2)
	v_cvt_pk_bf16_f32 v10, v34, v36
	s_waitcnt lgkmcnt(0)
	v_cvt_pk_bf16_f32 v11, v38, v40
	v_lshl_add_u64 v[42:43], v[24:25], 0, v[42:43]
	v_mul_i32_i24_e32 v26, 0x2c00, v26
	global_store_dwordx4 v[42:43], v[8:11], off
	s_mov_b64 s[6:7], 0
	s_nop 0
	v_cvt_pk_bf16_f32 v8, v27, v29
	v_ashrrev_i32_e32 v27, 31, v26
	v_cvt_pk_bf16_f32 v9, v31, v33
	v_cvt_pk_bf16_f32 v10, v35, v37
	v_cvt_pk_bf16_f32 v11, v39, v41
	v_lshl_add_u64 v[24:25], v[24:25], 0, v[26:27]
	global_store_dwordx4 v[24:25], v[8:11], off
	s_waitcnt lgkmcnt(0)
; #define LAS __attribute__((address_space(3)))
; __device__ __forceinline__ void transpose_item(const float* W, int ldw, int k0, int n0, bf16* WT, int Kdst, int dst_row0, LAS float* scr, int lane) {
;     float tv[32];
; #pragma unroll
;     for (int i = 0; i < 32; ++i) { const int kk = 2 * i + (lane >> 5); tv[i] = W[(size_t)(k0 + kk) * ldw + n0 + (lane & 31)]; }
; __device__ __forceinline__ void phase_wconv(const Frame& F, const Args& a, int l, unsigned char* wt, unsigned char* wth, int part) {
;     ...
;             if (mm < 2) {
;                 const float* W = a.in[F.z + (f ? 26 : 3) + mm] + (size_t)l * D * FF;
;                 const int kb = q / 176, nb = q % 176, n0 = 32 * nb;
;                 bf16* dst = (bf16*)(f ? wth + WO_UP2 : wt + WO_UP1);
;                 transpose_item(W, FF, 64 * kb, n0, dst, D, (n0 / 128) * 256 + mm * 128 + (n0 % 128), scr, F.lane);
.LBB0_753:
	s_andn2_b64 vcc, exec, s[6:7]
	s_cbranch_vccnz .LBB0_742
	s_add_i32 s6, s10, s11
	s_ashr_i32 s7, s6, 31
	s_lshl_b64 s[6:7], s[6:7], 3
	v_readlane_b32 s8, v254, 1
	v_readlane_b32 s9, v254, 2
	s_add_u32 s6, s8, s6
	s_addc_u32 s7, s9, s7
	s_load_dwordx2 s[14:15], s[6:7], 0x0
	s_mul_i32 s6, s12, 0xba3
	s_lshr_b32 s7, s6, 31
	s_ashr_i32 s6, s6, 19
	s_add_i32 s6, s6, s7
	s_mul_i32 s7, s6, 0xb0
	s_sub_i32 s7, s12, s7
	s_sext_i32_i16 s8, s7
	s_bfe_u32 s9, s8, 0x2001d
	s_lshl_b32 s12, s8, 5
	s_add_i32 s7, s7, s9
	s_bfe_u32 s8, s8, 0x70013
	s_sext_i32_i16 s7, s7
	s_add_i32 s8, s12, s8
	s_lshl_b32 s7, s7, 6
	s_and_b32 s8, s8, 0xff80
	s_and_b32 s7, s7, 0xffffff00
	s_lshl_b32 s9, s11, 7
	s_sub_i32 s8, s12, s8
	s_add_i32 s7, s7, s9
	s_sext_i32_i16 s8, s8
	s_ashr_i32 s13, s12, 31
	s_lshl_b32 s6, s6, 6
	s_add_i32 s8, s7, s8
	s_lshl_b64 s[12:13], s[12:13], 2
	v_or_b32_e32 v10, s6, v1
	s_waitcnt lgkmcnt(0)
	s_add_u32 s12, s14, s12
	s_addc_u32 s13, s15, s13
	v_mul_i32_i24_e32 v10, 0x5800, v10
	v_lshl_add_u64 v[8:9], s[12:13], 0, v[184:185]
	v_ashrrev_i32_e32 v11, 31, v10
	v_lshl_add_u64 v[8:9], v[8:9], 0, v[10:11]
	s_mov_b32 s7, 0x2c00000
	v_add_co_u32_e32 v10, vcc, s7, v8
	s_mov_b32 s7, 0x2c0b000
	s_nop 0
	v_addc_co_u32_e32 v11, vcc, 0, v9, vcc
	global_load_dword v24, v[10:11], off nt
	v_add_co_u32_e32 v10, vcc, s7, v8
	s_mov_b32 s7, 0x2c16000
	s_nop 0
	v_addc_co_u32_e32 v11, vcc, 0, v9, vcc
	global_load_dword v25, v[10:11], off nt
	v_add_co_u32_e32 v10, vcc, s7, v8
	s_mov_b32 s7, 0x2c21000
	s_nop 0
	v_addc_co_u32_e32 v11, vcc, 0, v9, vcc
	global_load_dword v26, v[10:11], off nt
	v_add_co_u32_e32 v10, vcc, s7, v8
	s_mov_b32 s7, 0x2c2c000
	s_nop 0
	v_addc_co_u32_e32 v11, vcc, 0, v9, vcc
	global_load_dword v27, v[10:11], off nt
	v_add_co_u32_e32 v10, vcc, s7, v8
	s_mov_b32 s7, 0x2c37000
	s_nop 0
	v_addc_co_u32_e32 v11, vcc, 0, v9, vcc
	global_load_dword v28, v[10:11], off nt
	v_add_co_u32_e32 v10, vcc, s7, v8
	s_mov_b32 s7, 0x2c42000
	s_nop 0
	v_addc_co_u32_e32 v11, vcc, 0, v9, vcc
	global_load_dword v29, v[10:11], off nt
	v_add_co_u32_e32 v10, vcc, s7, v8
	s_mov_b32 s7, 0x2c4d000
	s_nop 0
	v_addc_co_u32_e32 v11, vcc, 0, v9, vcc
	global_load_dword v30, v[10:11], off nt
	v_add_co_u32_e32 v10, vcc, s7, v8
	s_mov_b32 s7, 0x2c58000
	s_nop 0
	v_addc_co_u32_e32 v11, vcc, 0, v9, vcc
	global_load_dword v31, v[10:11], off nt
	v_add_co_u32_e32 v10, vcc, s7, v8
	s_mov_b32 s7, 0x2c63000
	s_nop 0
	v_addc_co_u32_e32 v11, vcc, 0, v9, vcc
	global_load_dword v32, v[10:11], off nt
	v_add_co_u32_e32 v10, vcc, s7, v8
	s_mov_b32 s7, 0x2c6e000
	s_nop 0
	v_addc_co_u32_e32 v11, vcc, 0, v9, vcc
	global_load_dword v33, v[10:11], off nt
	v_add_co_u32_e32 v10, vcc, s7, v8
	s_mov_b32 s7, 0x2c79000
	s_nop 0
	v_addc_co_u32_e32 v11, vcc, 0, v9, vcc
	global_load_dword v34, v[10:11], off nt
	v_add_co_u32_e32 v10, vcc, s7, v8
	s_mov_b32 s7, 0x2c84000
	s_nop 0
	v_addc_co_u32_e32 v11, vcc, 0, v9, vcc
	global_load_dword v35, v[10:11], off nt
	v_add_co_u32_e32 v10, vcc, s7, v8
	s_mov_b32 s7, 0x2c8f000
	s_nop 0
	v_addc_co_u32_e32 v11, vcc, 0, v9, vcc
	global_load_dword v36, v[10:11], off nt
	v_add_co_u32_e32 v10, vcc, s7, v8
	s_mov_b32 s7, 0x2c9a000
	s_nop 0
	v_addc_co_u32_e32 v11, vcc, 0, v9, vcc
	global_load_dword v37, v[10:11], off nt
	v_add_co_u32_e32 v10, vcc, s7, v8
	s_mov_b32 s7, 0x2ca5000
	s_nop 0
	v_addc_co_u32_e32 v11, vcc, 0, v9, vcc
	global_load_dword v38, v[10:11], off nt
	v_add_co_u32_e32 v10, vcc, s7, v8
	s_mov_b32 s7, 0x2cb0000
	s_nop 0
	v_addc_co_u32_e32 v11, vcc, 0, v9, vcc
	global_load_dword v39, v[10:11], off nt
	v_add_co_u32_e32 v10, vcc, s7, v8
	s_mov_b32 s7, 0x2cbb000
	s_nop 0
	v_addc_co_u32_e32 v11, vcc, 0, v9, vcc
	global_load_dword v40, v[10:11], off nt
	v_add_co_u32_e32 v10, vcc, s7, v8
	s_mov_b32 s7, 0x2cc6000
	s_nop 0
	v_addc_co_u32_e32 v11, vcc, 0, v9, vcc
	global_load_dword v41, v[10:11], off nt
	v_add_co_u32_e32 v10, vcc, s7, v8
	s_mov_b32 s7, 0x2cd1000
	s_nop 0
	v_addc_co_u32_e32 v11, vcc, 0, v9, vcc
	global_load_dword v42, v[10:11], off nt
	v_add_co_u32_e32 v10, vcc, s7, v8
	s_mov_b32 s7, 0x2cdc000
	s_nop 0
	v_addc_co_u32_e32 v11, vcc, 0, v9, vcc
	global_load_dword v43, v[10:11], off nt
	v_add_co_u32_e32 v10, vcc, s7, v8
	s_mov_b32 s7, 0x2ce7000
	s_nop 0
	v_addc_co_u32_e32 v11, vcc, 0, v9, vcc
	global_load_dword v44, v[10:11], off nt
	v_add_co_u32_e32 v10, vcc, s7, v8
	s_mov_b32 s7, 0x2cf2000
	s_nop 0
	v_addc_co_u32_e32 v11, vcc, 0, v9, vcc
	global_load_dword v45, v[10:11], off nt
	v_add_co_u32_e32 v10, vcc, s7, v8
	s_mov_b32 s7, 0x2cfd000
	s_nop 0
	v_addc_co_u32_e32 v11, vcc, 0, v9, vcc
	global_load_dword v46, v[10:11], off nt
	v_add_co_u32_e32 v10, vcc, s7, v8
	s_mov_b32 s7, 0x2d08000
	s_nop 0
	v_addc_co_u32_e32 v11, vcc, 0, v9, vcc
	global_load_dword v47, v[10:11], off nt
	v_add_co_u32_e32 v10, vcc, s7, v8
	s_mov_b32 s7, 0x2d13000
	s_nop 0
	v_addc_co_u32_e32 v11, vcc, 0, v9, vcc
	global_load_dword v48, v[10:11], off nt
	v_add_co_u32_e32 v10, vcc, s7, v8
	s_mov_b32 s7, 0x2d1e000
	s_nop 0
	v_addc_co_u32_e32 v11, vcc, 0, v9, vcc
	global_load_dword v49, v[10:11], off nt
	v_add_co_u32_e32 v10, vcc, s7, v8
	s_mov_b32 s7, 0x2d29000
	s_nop 0
	v_addc_co_u32_e32 v11, vcc, 0, v9, vcc
	global_load_dword v50, v[10:11], off nt
	v_add_co_u32_e32 v10, vcc, s7, v8
	s_mov_b32 s7, 0x2d34000
	s_nop 0
	v_addc_co_u32_e32 v11, vcc, 0, v9, vcc
	global_load_dword v51, v[10:11], off nt
	v_add_co_u32_e32 v10, vcc, s7, v8
	s_mov_b32 s7, 0x2d3f000
	s_nop 0
	v_addc_co_u32_e32 v11, vcc, 0, v9, vcc
	global_load_dword v52, v[10:11], off nt
	v_add_co_u32_e32 v10, vcc, s7, v8
	s_mov_b32 s7, 0x2d4a000
	s_nop 0
	v_addc_co_u32_e32 v11, vcc, 0, v9, vcc
	global_load_dword v53, v[10:11], off nt
	v_add_co_u32_e32 v10, vcc, s7, v8
	s_mov_b32 s7, 0x2d55000
	s_nop 0
	v_addc_co_u32_e32 v11, vcc, 0, v9, vcc
	v_add_co_u32_e32 v8, vcc, s7, v8
	global_load_dword v10, v[10:11], off nt
	s_nop 0
	v_addc_co_u32_e32 v9, vcc, 0, v9, vcc
	global_load_dword v8, v[8:9], off nt
	s_waitcnt vmcnt(30)
; #define LAS __attribute__((address_space(3)))
; #define LDS_WAIT() asm volatile("s_waitcnt lgkmcnt(0)" ::: "memory")
; __device__ __forceinline__ unsigned pk2(float lo, float hi) { return cvt_pk_bf16(lo, hi); }
; __device__ __forceinline__ void transpose_item(const float* W, int ldw, int k0, int n0, bf16* WT, int Kdst, int dst_row0, LAS float* scr, int lane) {
;     ...
;     for (int i = 0; i < 32; ++i) { const int kk = 2 * i + (lane >> 5); scr[kk * 33 + (lane & 31)] = tv[i]; }
;     LDS_WAIT(); asm volatile("" ::: "memory");
;     const int c = lane & 7;
; #pragma unroll
;     for (int j = 0; j < 4; ++j) { const int n = (lane >> 3) + 8 * j; const LAS float* s = scr + (8 * c) * 33 + n;
;         v4u o; o.x = pk2(s[0 * 33], s[1 * 33]); o.y = pk2(s[2 * 33], s[3 * 33]); o.z = pk2(s[4 * 33], s[5 * 33]); o.w = pk2(s[6 * 33], s[7 * 33]);
;         *(v4u*)(WT + (size_t)(dst_row0 + n) * Kdst + k0 + 8 * c) = o; }
;     LDS_WAIT(); asm volatile("" ::: "memory");
	ds_write2_b32 v12, v24, v25 offset1:66
	s_waitcnt vmcnt(28)
	ds_write2_b32 v12, v26, v27 offset0:132 offset1:198
	s_waitcnt vmcnt(26)
	ds_write2_b32 v23, v28, v29 offset0:8 offset1:74
	s_waitcnt vmcnt(24)
	ds_write2_b32 v23, v30, v31 offset0:140 offset1:206
	s_waitcnt vmcnt(22)
	ds_write2_b32 v22, v32, v33 offset0:16 offset1:82
	s_waitcnt vmcnt(20)
	ds_write2_b32 v22, v34, v35 offset0:148 offset1:214
	s_waitcnt vmcnt(18)
	ds_write2_b32 v21, v36, v37 offset0:24 offset1:90
	s_waitcnt vmcnt(16)
	ds_write2_b32 v21, v38, v39 offset0:156 offset1:222
	s_waitcnt vmcnt(14)
	ds_write2_b32 v20, v40, v41 offset0:32 offset1:98
	s_waitcnt vmcnt(12)
	ds_write2_b32 v20, v42, v43 offset0:164 offset1:230
	s_waitcnt vmcnt(10)
	ds_write2_b32 v19, v44, v45 offset0:40 offset1:106
	s_waitcnt vmcnt(8)
	ds_write2_b32 v19, v46, v47 offset0:172 offset1:238
	s_waitcnt vmcnt(6)
	ds_write2_b32 v18, v48, v49 offset0:48 offset1:114
	s_waitcnt vmcnt(4)
	ds_write2_b32 v18, v50, v51 offset0:180 offset1:246
	s_waitcnt vmcnt(2)
	ds_write2_b32 v7, v52, v53 offset0:56 offset1:122
	s_waitcnt vmcnt(0)
	ds_write2_b32 v7, v10, v8 offset0:188 offset1:254
	s_waitcnt lgkmcnt(0)
	ds_read2_b32 v[20:21], v14 offset0:33 offset1:41
	ds_read2_b32 v[22:23], v14 offset1:8
	ds_read2_b32 v[24:25], v14 offset0:66 offset1:74
	ds_read2_b32 v[26:27], v14 offset0:99 offset1:107
	ds_read2_b32 v[28:29], v14 offset0:132 offset1:140
	ds_read2_b32 v[30:31], v14 offset0:165 offset1:173
	ds_read2_b32 v[32:33], v14 offset0:198 offset1:206
	ds_read2_b32 v[34:35], v14 offset0:231 offset1:239
	v_or_b32_e32 v36, s8, v13
	s_ashr_i32 s7, s6, 31
	v_ashrrev_i32_e32 v37, 31, v36
	v_lshl_add_u64 v[18:19], s[6:7], 1, v[4:5]
	v_lshlrev_b64 v[36:37], 12, v[36:37]
	s_waitcnt lgkmcnt(6)
	v_cvt_pk_bf16_f32 v8, v22, v20
	s_waitcnt lgkmcnt(4)
	v_cvt_pk_bf16_f32 v9, v24, v26
	s_waitcnt lgkmcnt(2)
	v_cvt_pk_bf16_f32 v10, v28, v30
	s_waitcnt lgkmcnt(0)
	v_cvt_pk_bf16_f32 v11, v32, v34
	v_lshl_add_u64 v[36:37], v[18:19], 0, v[36:37]
	v_or_b32_e32 v20, s8, v15
	global_store_dwordx4 v[36:37], v[8:11], off
	v_or_b32_e32 v36, s8, v16
	v_ashrrev_i32_e32 v37, 31, v36
	v_cvt_pk_bf16_f32 v8, v23, v21
	v_ashrrev_i32_e32 v21, 31, v20
	v_lshlrev_b64 v[20:21], 12, v[20:21]
	v_cvt_pk_bf16_f32 v9, v25, v27
	v_cvt_pk_bf16_f32 v10, v29, v31
	v_cvt_pk_bf16_f32 v11, v33, v35
	v_lshl_add_u64 v[20:21], v[18:19], 0, v[20:21]
	global_store_dwordx4 v[20:21], v[8:11], off
	ds_read2_b32 v[20:21], v14 offset0:49 offset1:57
	ds_read2_b32 v[22:23], v14 offset0:16 offset1:24
	ds_read2_b32 v[24:25], v14 offset0:82 offset1:90
	ds_read2_b32 v[26:27], v14 offset0:115 offset1:123
	ds_read2_b32 v[28:29], v14 offset0:148 offset1:156
	ds_read2_b32 v[30:31], v14 offset0:181 offset1:189
	ds_read2_b32 v[32:33], v14 offset0:214 offset1:222
	ds_read2_b32 v[34:35], v14 offset0:247 offset1:255
	v_lshlrev_b64 v[36:37], 12, v[36:37]
	s_waitcnt lgkmcnt(6)
	v_cvt_pk_bf16_f32 v8, v22, v20
	s_waitcnt lgkmcnt(4)
	v_cvt_pk_bf16_f32 v9, v24, v26
	s_waitcnt lgkmcnt(2)
	v_cvt_pk_bf16_f32 v10, v28, v30
	s_waitcnt lgkmcnt(0)
	v_cvt_pk_bf16_f32 v11, v32, v34
	v_lshl_add_u64 v[36:37], v[18:19], 0, v[36:37]
	v_or_b32_e32 v20, s8, v17
	global_store_dwordx4 v[36:37], v[8:11], off
	s_nop 1
	v_cvt_pk_bf16_f32 v8, v23, v21
	v_ashrrev_i32_e32 v21, 31, v20
	v_lshlrev_b64 v[20:21], 12, v[20:21]
	v_cvt_pk_bf16_f32 v9, v25, v27
	v_cvt_pk_bf16_f32 v10, v29, v31
	v_cvt_pk_bf16_f32 v11, v33, v35
	v_lshl_add_u64 v[18:19], v[18:19], 0, v[20:21]
	global_store_dwordx4 v[18:19], v[8:11], off
	s_waitcnt lgkmcnt(0)
	s_branch .LBB0_742

; __device__ __forceinline__ unsigned f2bf(float f) { return cvt_pk_bf16(f, f) & 0xffffu; }
; __device__ __forceinline__ void phase_wconv(const Frame& F, const Args& a, int l, unsigned char* wt, unsigned char* wth, int part) {
;     ...
;     for (int i = gt; i < 2560 * 384; i += NGT) {
;         const int n = i / 384, k = i % 384; float v = 0.f;
;         if (n < 1024) { const int z = n >> 9, c = n & 511; if (k >= 64 * z && k < 64 * z + 64) v = w2[((size_t)z * 64 + (k - 64 * z)) * 512 + c]; }
;         else if (n < 2048) { const int z = (n - 1024) >> 9, c = n & 511; if (k >= 128 + 64 * z && k < 192 + 64 * z) v = a2[((size_t)z * 64 + (k - 128 - 64 * z)) * 512 + c]; }
;         else { const int c = n - 2048; if (k >= 256) v = g2[(size_t)(k - 256) * 512 + c]; }
;         lr[i] = (bf16)f2bf(v);
.LBB0_759:
	s_mov_b32 s4, 0x2aaaaaab
	v_mul_hi_i32 v1, v2, s4
	v_lshrrev_b32_e32 v3, 31, v1
	v_ashrrev_i32_e32 v1, 6, v1
	v_add_u32_e32 v4, v1, v3
	v_mul_i32_i24_e32 v1, 0x180, v4
	s_mov_b32 s4, 0x5ffff
	v_sub_u32_e32 v1, v2, v1
	v_cmp_lt_i32_e32 vcc, s4, v2
	s_and_saveexec_b64 s[4:5], vcc
	s_xor_b64 s[20:21], exec, s[4:5]
	s_cbranch_execz .LBB0_769
	s_mov_b32 s4, 0xbffff
	v_cmp_lt_u32_e32 vcc, s4, v2
	s_and_saveexec_b64 s[4:5], vcc
	s_xor_b64 s[4:5], exec, s[4:5]
	s_cbranch_execz .LBB0_764
	s_movk_i32 s9, 0xff
	v_cmp_lt_i32_e32 vcc, s9, v1
	v_mov_b32_e32 v3, 0
	s_and_saveexec_b64 s[22:23], vcc
	s_cbranch_execz .LBB0_763
	v_add_u32_e32 v184, 0xffffff00, v1
	v_lshlrev_b64 v[6:7], 11, v[184:185]
	v_lshl_add_u64 v[6:7], s[6:7], 0, v[6:7]
	v_mov_b32_e32 v5, v185
	v_lshl_add_u64 v[4:5], v[4:5], 2, v[6:7]
	v_add_co_u32_e32 v4, vcc, 0x3e000, v4
	s_nop 1
	v_addc_co_u32_e32 v5, vcc, 0, v5, vcc
	global_load_dword v3, v[4:5], off nt

; __device__ __forceinline__ unsigned f2bf(float f) { return cvt_pk_bf16(f, f) & 0xffffu; }
; __device__ __forceinline__ void phase_wconv(const Frame& F, const Args& a, int l, unsigned char* wt, unsigned char* wth, int part) {
;     ...
;     for (int i = gt; i < 2560 * 384; i += NGT) {
;         const int n = i / 384, k = i % 384; float v = 0.f;
;         if (n < 1024) { const int z = n >> 9, c = n & 511; if (k >= 64 * z && k < 64 * z + 64) v = w2[((size_t)z * 64 + (k - 64 * z)) * 512 + c]; }
;         else if (n < 2048) { const int z = (n - 1024) >> 9, c = n & 511; if (k >= 128 + 64 * z && k < 192 + 64 * z) v = a2[((size_t)z * 64 + (k - 128 - 64 * z)) * 512 + c]; }
;         else { const int c = n - 2048; if (k >= 256) v = g2[(size_t)(k - 256) * 512 + c]; }
;         lr[i] = (bf16)f2bf(v);
.LBB0_764:
	s_andn2_saveexec_b64 s[22:23], s[4:5]
	s_cbranch_execz .LBB0_768
	s_waitcnt vmcnt(0)
	v_add_u32_e32 v3, 0xfffffc00, v4
	v_lshrrev_b32_e32 v3, 3, v3
	v_and_b32_e32 v184, 0x1fffffc0, v3
	v_add_u32_e32 v3, 0x80, v184
	v_cmp_ge_i32_e32 vcc, v1, v3
	v_add_u32_e32 v3, 0xc0, v184
	v_cmp_lt_i32_e64 s[4:5], v1, v3
	s_and_b64 s[26:27], vcc, s[4:5]
	v_mov_b32_e32 v3, 0
	s_and_saveexec_b64 s[4:5], s[26:27]
	s_cbranch_execz .LBB0_767
	v_sub_u32_e32 v1, v1, v184
	v_and_b32_e32 v3, 0x1ff, v4
	v_add_u32_e32 v4, 0xffffff80, v1
	v_ashrrev_i32_e32 v5, 31, v4
	v_lshl_add_u64 v[4:5], v[4:5], 0, v[184:185]
	v_lshlrev_b64 v[4:5], 11, v[4:5]
	v_lshl_add_u64 v[4:5], s[16:17], 0, v[4:5]
	v_lshlrev_b32_e32 v184, 2, v3
	v_lshl_add_u64 v[4:5], v[4:5], 0, v[184:185]
	global_load_dword v3, v[4:5], off nt

; __device__ __forceinline__ unsigned f2bf(float f) { return cvt_pk_bf16(f, f) & 0xffffu; }
; __device__ __forceinline__ void phase_wconv(const Frame& F, const Args& a, int l, unsigned char* wt, unsigned char* wth, int part) {
;     ...
;     for (int i = gt; i < 2560 * 384; i += NGT) {
;         const int n = i / 384, k = i % 384; float v = 0.f;
;         if (n < 1024) { const int z = n >> 9, c = n & 511; if (k >= 64 * z && k < 64 * z + 64) v = w2[((size_t)z * 64 + (k - 64 * z)) * 512 + c]; }
;         else if (n < 2048) { const int z = (n - 1024) >> 9, c = n & 511; if (k >= 128 + 64 * z && k < 192 + 64 * z) v = a2[((size_t)z * 64 + (k - 128 - 64 * z)) * 512 + c]; }
;         else { const int c = n - 2048; if (k >= 256) v = g2[(size_t)(k - 256) * 512 + c]; }
;         lr[i] = (bf16)f2bf(v);
.LBB0_769:
	s_andn2_saveexec_b64 s[20:21], s[20:21]
	s_cbranch_execz .LBB0_758
	v_ashrrev_i32_e32 v6, 9, v4
	v_lshlrev_b32_e32 v5, 6, v6
	s_waitcnt vmcnt(0)
	v_add_u32_e32 v3, 64, v5
	v_cmp_ge_i32_e32 vcc, v1, v5
	v_cmp_lt_i32_e64 s[4:5], v1, v3
	s_and_b64 s[22:23], vcc, s[4:5]
	v_mov_b32_e32 v3, 0
	s_and_saveexec_b64 s[4:5], s[22:23]
	s_cbranch_execz .LBB0_757
	v_ashrrev_i32_e32 v7, 31, v6
	v_and_b32_e32 v3, 0x1ff, v4
	v_sub_u32_e32 v184, v1, v5
	v_lshlrev_b64 v[4:5], 17, v[6:7]
	v_lshl_add_u64 v[4:5], s[14:15], 0, v[4:5]
	v_lshlrev_b64 v[6:7], 11, v[184:185]
	v_lshl_add_u64 v[4:5], v[4:5], 0, v[6:7]
	v_lshlrev_b32_e32 v184, 2, v3
	v_lshl_add_u64 v[4:5], v[4:5], 0, v[184:185]
	global_load_dword v3, v[4:5], off nt
	s_branch .LBB0_757

; #define GAS __attribute__((address_space(1)))
; __device__ __forceinline__ unsigned cvt_pk_bf16(float lo, float hi) { f32x2 v = {lo, hi}; bf16v2_t r = __builtin_convertvector(v, bf16v2_t); return __builtin_bit_cast(unsigned, r); }
; __device__ __forceinline__ float fsigmoid(float x) { return __builtin_amdgcn_rcpf(1.0f + fexp(-x)); }
;     __device__ __forceinline__ void operator()(const f32x4 (&acc)[2][2][4][2], const UnitG& u, int wr, int wc, int fr, int fq) const {
;     ...
;         const int row0 = u.x0 * 256 + wr * 64 + fr, col0 = u.x1 * 256 + wc * 32 + 8 * fq;
;         const GAS v4u* pp = (const GAS v4u*)scrP + tid; GAS v4u* pm_ = (GAS v4u*)scrM + tid;
; #pragma unroll
;         for (int ai = 0; ai < 2; ++ai)
; #pragma unroll
;             for (int bj = 0; bj < 2; ++bj)
; #pragma unroll
;                 for (int m = 0; m < 4; ++m) {
;                     const v4u pw = *pp; v4u mw = {0u, 0u, 0u, 0u}; if (su > 1) mw = *pm_;
;                     const f32x4 g0 = acc[ai][bj][m][0], g1 = acc[ai][bj][m][1];
;                     float v[8];
;                     v[0] = fsigmoid(g0.x) * bf_lo(pw.x) + bf_lo(mw.x); v[1] = fsigmoid(g0.y) * bf_hi(pw.x) + bf_hi(mw.x);
;                     v[2] = fsigmoid(g0.z) * bf_lo(pw.y) + bf_lo(mw.y); v[3] = fsigmoid(g0.w) * bf_hi(pw.y) + bf_hi(mw.y);
;                     v[4] = fsigmoid(g1.x) * bf_lo(pw.z) + bf_lo(mw.z); v[5] = fsigmoid(g1.y) * bf_hi(pw.z) + bf_hi(mw.z);
;                     v[6] = fsigmoid(g1.z) * bf_lo(pw.w) + bf_lo(mw.w); v[7] = fsigmoid(g1.w) * bf_hi(pw.w) + bf_hi(mw.w);
;                     v4u w; w.x = cvt_pk_bf16(v[0], v[1]); w.y = cvt_pk_bf16(v[2], v[3]); w.z = cvt_pk_bf16(v[4], v[5]); w.w = cvt_pk_bf16(v[6], v[7]);
;                     if (su < 5) *pm_ = w;
;                     else *(v4u*)(MG + (size_t)(row0 + ai * 128 + m * 16) * D + col0 + bj * 128) = w;
.LBB0_1283:
	v_lshlrev_b64 v[132:133], 4, v[140:141]
	v_lshl_add_u64 v[146:147], s[18:19], 0, v[132:133]
	global_load_dwordx4 v[128:131], v[146:147], off
	v_readlane_b32 s4, v255, 35
	v_readlane_b32 s5, v255, 36
	s_cmp_gt_i32 s20, 1
	s_cselect_b64 s[6:7], -1, 0
	v_lshl_add_u64 v[148:149], s[4:5], 0, v[132:133]
	s_cmp_lt_i32 s20, 2
	v_mov_b32_e32 v132, 0
	v_mov_b32_e32 v133, 0
	v_mov_b32_e32 v134, 0
	v_mov_b32_e32 v135, 0
	s_cbranch_scc1 .LBB0_1285
	global_load_dwordx4 v[132:135], v[148:149], off
.LBB0_1285:
	v_readlane_b32 s4, v255, 13
	v_readlane_b32 s5, v255, 14
	v_readlane_b32 s5, v255, 31
	s_lshl_b32 s5, s5, 8
	v_readlane_b32 s8, v255, 37
	s_lshl_b32 s4, s4, 8
	s_or_b32 s5, s5, s8
	s_cmp_gt_i32 s20, 4
	s_cselect_b64 s[46:47], -1, 0
	s_add_i32 s4, s4, s77
	v_add_u32_e32 v144, s4, v137
	v_mul_f32_e32 v137, 0xbfb8aa3b, v120
	v_exp_f32_e32 v137, v137
	s_waitcnt vmcnt(0)
	v_lshlrev_b32_e32 v152, 16, v128
	v_and_b32_e32 v153, 0xffff0000, v128
	v_mul_f32_e32 v128, 0xbfb8aa3b, v122
	v_add_f32_e32 v137, 1.0, v137
	v_rcp_f32_e32 v150, v137
	v_mul_f32_e32 v137, 0xbfb8aa3b, v121
	v_exp_f32_e32 v137, v137
	v_exp_f32_e32 v128, v128
	v_lshlrev_b32_e32 v154, 16, v132
	v_and_b32_e32 v155, 0xffff0000, v132
	v_add_f32_e32 v137, 1.0, v137
	v_rcp_f32_e32 v151, v137
	v_add_f32_e32 v128, 1.0, v128
	v_lshlrev_b32_e32 v132, 16, v133
	v_and_b32_e32 v133, 0xffff0000, v133
	v_pk_fma_f32 v[150:151], v[150:151], v[152:153], v[154:155]
	v_rcp_f32_e32 v152, v128
	v_mul_f32_e32 v128, 0xbfb8aa3b, v123
	v_exp_f32_e32 v128, v128
	v_lshlrev_b32_e32 v154, 16, v134
	v_and_b32_e32 v155, 0xffff0000, v134
	v_lshlrev_b32_e32 v134, 16, v135
	v_add_f32_e32 v128, 1.0, v128
	v_rcp_f32_e32 v153, v128
	v_lshlrev_b32_e32 v128, 16, v129
	v_and_b32_e32 v129, 0xffff0000, v129
	v_and_b32_e32 v135, 0xffff0000, v135
	v_pk_fma_f32 v[132:133], v[152:153], v[128:129], v[132:133]
	v_mul_f32_e32 v128, 0xbfb8aa3b, v124
	v_mul_f32_e32 v129, 0xbfb8aa3b, v125
	v_exp_f32_e32 v128, v128
	v_exp_f32_e32 v129, v129
	v_lshlrev_b32_e32 v152, 16, v130
	v_and_b32_e32 v153, 0xffff0000, v130
	v_add_f32_e32 v128, 1.0, v128
	v_add_f32_e32 v129, 1.0, v129
	v_rcp_f32_e32 v128, v128
	v_rcp_f32_e32 v129, v129
	v_lshlrev_b32_e32 v130, 16, v131
	v_and_b32_e32 v131, 0xffff0000, v131
	v_lshl_add_u32 v142, v139, 3, s5
	v_pk_fma_f32 v[152:153], v[128:129], v[152:153], v[154:155]
	v_mul_f32_e32 v128, 0xbfb8aa3b, v126
	v_mul_f32_e32 v129, 0xbfb8aa3b, v127
	v_exp_f32_e32 v128, v128
	v_exp_f32_e32 v129, v129
	v_ashrrev_i32_e32 v143, 31, v142
	s_mov_b64 s[4:5], -1
	v_add_f32_e32 v128, 1.0, v128
	v_add_f32_e32 v129, 1.0, v129
	v_rcp_f32_e32 v128, v128
	v_rcp_f32_e32 v129, v129
	s_and_b64 vcc, exec, s[46:47]
	v_ashrrev_i32_e32 v145, 31, v144
	v_pk_fma_f32 v[134:135], v[128:129], v[130:131], v[134:135]
	v_cvt_pk_bf16_f32 v128, v150, v151
	v_cvt_pk_bf16_f32 v129, v132, v133
	v_cvt_pk_bf16_f32 v130, v152, v153
	v_cvt_pk_bf16_f32 v131, v134, v135
	s_cbranch_vccz .LBB0_1287
	v_lshlrev_b64 v[132:133], 12, v[144:145]
	v_lshl_add_u64 v[132:133], s[22:23], 0, v[132:133]
	v_lshl_add_u64 v[132:133], v[142:143], 1, v[132:133]
	global_store_dwordx4 v[132:133], v[128:131], off
	s_mov_b64 s[4:5], 0

; __device__ __forceinline__ unsigned cvt_pk_bf16(float lo, float hi) { f32x2 v = {lo, hi}; bf16v2_t r = __builtin_convertvector(v, bf16v2_t); return __builtin_bit_cast(unsigned, r); }
; __device__ __forceinline__ float fsigmoid(float x) { return __builtin_amdgcn_rcpf(1.0f + fexp(-x)); }
;     __device__ __forceinline__ void operator()(const f32x4 (&acc)[2][2][4][2], const UnitG& u, int wr, int wc, int fr, int fq) const {
;     ...
;                 for (int m = 0; m < 4; ++m) {
;                     const v4u pw = *pp; v4u mw = {0u, 0u, 0u, 0u}; if (su > 1) mw = *pm_;
;                     const f32x4 g0 = acc[ai][bj][m][0], g1 = acc[ai][bj][m][1];
;                     float v[8];
;                     v[0] = fsigmoid(g0.x) * bf_lo(pw.x) + bf_lo(mw.x); v[1] = fsigmoid(g0.y) * bf_hi(pw.x) + bf_hi(mw.x);
;                     v[2] = fsigmoid(g0.z) * bf_lo(pw.y) + bf_lo(mw.y); v[3] = fsigmoid(g0.w) * bf_hi(pw.y) + bf_hi(mw.y);
;                     v[4] = fsigmoid(g1.x) * bf_lo(pw.z) + bf_lo(mw.z); v[5] = fsigmoid(g1.y) * bf_hi(pw.z) + bf_hi(mw.z);
;                     v[6] = fsigmoid(g1.z) * bf_lo(pw.w) + bf_lo(mw.w); v[7] = fsigmoid(g1.w) * bf_hi(pw.w) + bf_hi(mw.w);
;                     v4u w; w.x = cvt_pk_bf16(v[0], v[1]); w.y = cvt_pk_bf16(v[2], v[3]); w.z = cvt_pk_bf16(v[4], v[5]); w.w = cvt_pk_bf16(v[6], v[7]);
;                     if (su < 5) *pm_ = w;
;                     else *(v4u*)(MG + (size_t)(row0 + ai * 128 + m * 16) * D + col0 + bj * 128) = w;
;                     pp += NTHR; pm_ += NTHR; asm volatile("" : "+v"(pp), "+v"(pm_) :: "memory");
.LBB0_1289:
	s_mov_b64 s[4:5], 0x2000
	v_lshl_add_u64 v[146:147], v[146:147], 0, s[4:5]
	v_lshl_add_u64 v[148:149], v[148:149], 0, s[4:5]
	global_load_dwordx4 v[132:135], v[146:147], off
	v_cndmask_b32_e64 v129, 0, 1, s[6:7]
	v_mov_b32_e32 v128, 0
	v_cmp_ne_u32_e64 s[4:5], 1, v129
	s_andn2_b64 vcc, exec, s[6:7]
	v_mov_b32_e32 v129, 0
	v_mov_b32_e32 v130, 0
	v_mov_b32_e32 v131, 0
	s_cbranch_vccnz .LBB0_1291
	global_load_dwordx4 v[128:131], v[148:149], off
.LBB0_1291:
	v_mul_f32_e32 v137, 0xbfb8aa3b, v112
	v_exp_f32_e32 v137, v137
	s_waitcnt vmcnt(0)
	v_lshlrev_b32_e32 v154, 16, v128
	v_and_b32_e32 v155, 0xffff0000, v128
	v_mul_f32_e32 v128, 0xbfb8aa3b, v114
	v_add_f32_e32 v137, 1.0, v137
	v_rcp_f32_e32 v150, v137
	v_mul_f32_e32 v137, 0xbfb8aa3b, v113
	v_exp_f32_e32 v137, v137
	v_exp_f32_e32 v128, v128
	v_lshlrev_b32_e32 v152, 16, v132
	v_and_b32_e32 v153, 0xffff0000, v132
	v_add_f32_e32 v137, 1.0, v137
	v_rcp_f32_e32 v151, v137
	v_add_f32_e32 v128, 1.0, v128
	v_lshlrev_b32_e32 v132, 16, v133
	v_and_b32_e32 v133, 0xffff0000, v133
	v_pk_fma_f32 v[150:151], v[150:151], v[152:153], v[154:155]
	v_rcp_f32_e32 v152, v128
	v_mul_f32_e32 v128, 0xbfb8aa3b, v115
	v_exp_f32_e32 v128, v128
	v_lshlrev_b32_e32 v154, 16, v130
	v_and_b32_e32 v155, 0xffff0000, v130
	v_lshlrev_b32_e32 v130, 16, v131
	v_add_f32_e32 v128, 1.0, v128
	v_rcp_f32_e32 v153, v128
	v_lshlrev_b32_e32 v128, 16, v129
	v_and_b32_e32 v129, 0xffff0000, v129
	v_and_b32_e32 v131, 0xffff0000, v131
	v_pk_fma_f32 v[132:133], v[152:153], v[132:133], v[128:129]
	v_mul_f32_e32 v128, 0xbfb8aa3b, v116
	v_mul_f32_e32 v129, 0xbfb8aa3b, v117
	v_exp_f32_e32 v128, v128
	v_exp_f32_e32 v129, v129
	v_lshlrev_b32_e32 v152, 16, v134
	v_and_b32_e32 v153, 0xffff0000, v134
	v_add_f32_e32 v128, 1.0, v128
	v_add_f32_e32 v129, 1.0, v129
	v_rcp_f32_e32 v128, v128
	v_rcp_f32_e32 v129, v129
	v_lshlrev_b32_e32 v134, 16, v135
	v_and_b32_e32 v135, 0xffff0000, v135
	s_mov_b64 s[48:49], -1
	v_pk_fma_f32 v[152:153], v[128:129], v[152:153], v[154:155]
	v_mul_f32_e32 v128, 0xbfb8aa3b, v118
	v_mul_f32_e32 v129, 0xbfb8aa3b, v119
	v_exp_f32_e32 v128, v128
	v_exp_f32_e32 v129, v129
	s_andn2_b64 vcc, exec, s[46:47]
	v_add_f32_e32 v128, 1.0, v128
	v_add_f32_e32 v129, 1.0, v129
	v_rcp_f32_e32 v128, v128
	v_rcp_f32_e32 v129, v129
	s_nop 0
	v_pk_fma_f32 v[134:135], v[128:129], v[134:135], v[130:131]
	v_cvt_pk_bf16_f32 v129, v132, v133
	v_cndmask_b32_e64 v132, 0, 1, s[46:47]
	v_cvt_pk_bf16_f32 v128, v150, v151
	v_cvt_pk_bf16_f32 v130, v152, v153
	v_cvt_pk_bf16_f32 v131, v134, v135
	v_cmp_ne_u32_e64 s[6:7], 1, v132
	s_cbranch_vccnz .LBB0_1293
	v_lshlrev_b64 v[132:133], 12, v[144:145]
	v_lshl_add_u64 v[132:133], s[22:23], 0, v[132:133]
	v_lshl_add_u64 v[132:133], v[142:143], 1, v[132:133]
	v_add_co_u32_e32 v132, vcc, 0x10000, v132
	s_mov_b64 s[48:49], 0
	s_nop 0
	v_addc_co_u32_e32 v133, vcc, 0, v133, vcc
	global_store_dwordx4 v[132:133], v[128:131], off

; __device__ __forceinline__ unsigned cvt_pk_bf16(float lo, float hi) { f32x2 v = {lo, hi}; bf16v2_t r = __builtin_convertvector(v, bf16v2_t); return __builtin_bit_cast(unsigned, r); }
; __device__ __forceinline__ float fsigmoid(float x) { return __builtin_amdgcn_rcpf(1.0f + fexp(-x)); }
;     __device__ __forceinline__ void operator()(const f32x4 (&acc)[2][2][4][2], const UnitG& u, int wr, int wc, int fr, int fq) const {
;     ...
;                     const v4u pw = *pp; v4u mw = {0u, 0u, 0u, 0u}; if (su > 1) mw = *pm_;
;                     const f32x4 g0 = acc[ai][bj][m][0], g1 = acc[ai][bj][m][1];
;                     float v[8];
;                     v[0] = fsigmoid(g0.x) * bf_lo(pw.x) + bf_lo(mw.x); v[1] = fsigmoid(g0.y) * bf_hi(pw.x) + bf_hi(mw.x);
;                     v[2] = fsigmoid(g0.z) * bf_lo(pw.y) + bf_lo(mw.y); v[3] = fsigmoid(g0.w) * bf_hi(pw.y) + bf_hi(mw.y);
;                     v[4] = fsigmoid(g1.x) * bf_lo(pw.z) + bf_lo(mw.z); v[5] = fsigmoid(g1.y) * bf_hi(pw.z) + bf_hi(mw.z);
;                     v[6] = fsigmoid(g1.z) * bf_lo(pw.w) + bf_lo(mw.w); v[7] = fsigmoid(g1.w) * bf_hi(pw.w) + bf_hi(mw.w);
;                     v4u w; w.x = cvt_pk_bf16(v[0], v[1]); w.y = cvt_pk_bf16(v[2], v[3]); w.z = cvt_pk_bf16(v[4], v[5]); w.w = cvt_pk_bf16(v[6], v[7]);
;                     if (su < 5) *pm_ = w;
;                     else *(v4u*)(MG + (size_t)(row0 + ai * 128 + m * 16) * D + col0 + bj * 128) = w;
.LBB0_1295:
	s_mov_b64 s[10:11], 0x2000
	v_lshl_add_u64 v[146:147], v[146:147], 0, s[10:11]
	v_lshl_add_u64 v[148:149], v[148:149], 0, s[10:11]
	global_load_dwordx4 v[132:135], v[146:147], off
	v_mov_b32_e32 v128, 0
	s_and_b64 vcc, exec, s[4:5]
	v_mov_b32_e32 v129, 0
	v_mov_b32_e32 v130, 0
	v_mov_b32_e32 v131, 0
	s_cbranch_vccnz .LBB0_1297
	global_load_dwordx4 v[128:131], v[148:149], off
.LBB0_1297:
	v_mul_f32_e32 v137, 0xbfb8aa3b, v104
	v_exp_f32_e32 v137, v137
	s_waitcnt vmcnt(0)
	v_lshlrev_b32_e32 v154, 16, v128
	v_and_b32_e32 v155, 0xffff0000, v128
	v_mul_f32_e32 v128, 0xbfb8aa3b, v106
	v_add_f32_e32 v137, 1.0, v137
	v_rcp_f32_e32 v150, v137
	v_mul_f32_e32 v137, 0xbfb8aa3b, v105
	v_exp_f32_e32 v137, v137
	v_exp_f32_e32 v128, v128
	v_lshlrev_b32_e32 v152, 16, v132
	v_and_b32_e32 v153, 0xffff0000, v132
	v_add_f32_e32 v137, 1.0, v137
	v_rcp_f32_e32 v151, v137
	v_add_f32_e32 v128, 1.0, v128
	v_lshlrev_b32_e32 v132, 16, v133
	v_and_b32_e32 v133, 0xffff0000, v133
	v_pk_fma_f32 v[150:151], v[150:151], v[152:153], v[154:155]
	v_rcp_f32_e32 v152, v128
	v_mul_f32_e32 v128, 0xbfb8aa3b, v107
	v_exp_f32_e32 v128, v128
	v_lshlrev_b32_e32 v154, 16, v130
	v_and_b32_e32 v155, 0xffff0000, v130
	v_lshlrev_b32_e32 v130, 16, v131
	v_add_f32_e32 v128, 1.0, v128
	v_rcp_f32_e32 v153, v128
	v_lshlrev_b32_e32 v128, 16, v129
	v_and_b32_e32 v129, 0xffff0000, v129
	v_and_b32_e32 v131, 0xffff0000, v131
	v_pk_fma_f32 v[132:133], v[152:153], v[132:133], v[128:129]
	v_mul_f32_e32 v128, 0xbfb8aa3b, v108
	v_mul_f32_e32 v129, 0xbfb8aa3b, v109
	v_exp_f32_e32 v128, v128
	v_exp_f32_e32 v129, v129
	v_lshlrev_b32_e32 v152, 16, v134
	v_and_b32_e32 v153, 0xffff0000, v134
	v_add_f32_e32 v128, 1.0, v128
	v_add_f32_e32 v129, 1.0, v129
	v_rcp_f32_e32 v128, v128
	v_rcp_f32_e32 v129, v129
	v_lshlrev_b32_e32 v134, 16, v135
	v_and_b32_e32 v135, 0xffff0000, v135
	s_mov_b64 s[46:47], -1
	v_pk_fma_f32 v[152:153], v[128:129], v[152:153], v[154:155]
	v_mul_f32_e32 v128, 0xbfb8aa3b, v110
	v_mul_f32_e32 v129, 0xbfb8aa3b, v111
	v_exp_f32_e32 v128, v128
	v_exp_f32_e32 v129, v129
	s_and_b64 vcc, exec, s[6:7]
	v_add_f32_e32 v128, 1.0, v128
	v_add_f32_e32 v129, 1.0, v129
	v_rcp_f32_e32 v128, v128
	v_rcp_f32_e32 v129, v129
	s_nop 0
	v_pk_fma_f32 v[134:135], v[128:129], v[134:135], v[130:131]
	v_cvt_pk_bf16_f32 v128, v150, v151
	v_cvt_pk_bf16_f32 v129, v132, v133
	v_cvt_pk_bf16_f32 v130, v152, v153
	v_cvt_pk_bf16_f32 v131, v134, v135
	s_cbranch_vccnz .LBB0_1299
	v_lshlrev_b64 v[132:133], 12, v[144:145]
	v_lshl_add_u64 v[132:133], s[22:23], 0, v[132:133]
	v_lshl_add_u64 v[132:133], v[142:143], 1, v[132:133]
	v_add_co_u32_e32 v132, vcc, 0x20000, v132
	s_mov_b64 s[46:47], 0
	s_nop 0
	v_addc_co_u32_e32 v133, vcc, 0, v133, vcc
	global_store_dwordx4 v[132:133], v[128:131], off

; __device__ __forceinline__ unsigned cvt_pk_bf16(float lo, float hi) { f32x2 v = {lo, hi}; bf16v2_t r = __builtin_convertvector(v, bf16v2_t); return __builtin_bit_cast(unsigned, r); }
; __device__ __forceinline__ float fsigmoid(float x) { return __builtin_amdgcn_rcpf(1.0f + fexp(-x)); }
;     __device__ __forceinline__ void operator()(const f32x4 (&acc)[2][2][4][2], const UnitG& u, int wr, int wc, int fr, int fq) const {
;     ...
;                     const v4u pw = *pp; v4u mw = {0u, 0u, 0u, 0u}; if (su > 1) mw = *pm_;
;                     const f32x4 g0 = acc[ai][bj][m][0], g1 = acc[ai][bj][m][1];
;                     float v[8];
;                     v[0] = fsigmoid(g0.x) * bf_lo(pw.x) + bf_lo(mw.x); v[1] = fsigmoid(g0.y) * bf_hi(pw.x) + bf_hi(mw.x);
;                     v[2] = fsigmoid(g0.z) * bf_lo(pw.y) + bf_lo(mw.y); v[3] = fsigmoid(g0.w) * bf_hi(pw.y) + bf_hi(mw.y);
;                     v[4] = fsigmoid(g1.x) * bf_lo(pw.z) + bf_lo(mw.z); v[5] = fsigmoid(g1.y) * bf_hi(pw.z) + bf_hi(mw.z);
;                     v[6] = fsigmoid(g1.z) * bf_lo(pw.w) + bf_lo(mw.w); v[7] = fsigmoid(g1.w) * bf_hi(pw.w) + bf_hi(mw.w);
;                     v4u w; w.x = cvt_pk_bf16(v[0], v[1]); w.y = cvt_pk_bf16(v[2], v[3]); w.z = cvt_pk_bf16(v[4], v[5]); w.w = cvt_pk_bf16(v[6], v[7]);
;                     if (su < 5) *pm_ = w;
;                     else *(v4u*)(MG + (size_t)(row0 + ai * 128 + m * 16) * D + col0 + bj * 128) = w;
.LBB0_1301:
	v_lshl_add_u64 v[146:147], v[146:147], 0, s[10:11]
	v_lshl_add_u64 v[148:149], v[148:149], 0, s[10:11]
	global_load_dwordx4 v[132:135], v[146:147], off
	v_mov_b32_e32 v128, 0
	s_and_b64 vcc, exec, s[4:5]
	v_mov_b32_e32 v129, 0
	v_mov_b32_e32 v130, 0
	v_mov_b32_e32 v131, 0
	s_cbranch_vccnz .LBB0_1303
	global_load_dwordx4 v[128:131], v[148:149], off
.LBB0_1303:
	v_mul_f32_e32 v137, 0xbfb8aa3b, v96
	v_exp_f32_e32 v137, v137
	s_waitcnt vmcnt(0)
	v_lshlrev_b32_e32 v154, 16, v128
	v_and_b32_e32 v155, 0xffff0000, v128
	v_mul_f32_e32 v128, 0xbfb8aa3b, v98
	v_add_f32_e32 v137, 1.0, v137
	v_rcp_f32_e32 v150, v137
	v_mul_f32_e32 v137, 0xbfb8aa3b, v97
	v_exp_f32_e32 v137, v137
	v_exp_f32_e32 v128, v128
	v_lshlrev_b32_e32 v152, 16, v132
	v_and_b32_e32 v153, 0xffff0000, v132
	v_add_f32_e32 v137, 1.0, v137
	v_rcp_f32_e32 v151, v137
	v_add_f32_e32 v128, 1.0, v128
	v_lshlrev_b32_e32 v132, 16, v133
	v_and_b32_e32 v133, 0xffff0000, v133
	v_pk_fma_f32 v[150:151], v[150:151], v[152:153], v[154:155]
	v_rcp_f32_e32 v152, v128
	v_mul_f32_e32 v128, 0xbfb8aa3b, v99
	v_exp_f32_e32 v128, v128
	v_lshlrev_b32_e32 v154, 16, v130
	v_and_b32_e32 v155, 0xffff0000, v130
	v_lshlrev_b32_e32 v130, 16, v131
	v_add_f32_e32 v128, 1.0, v128
	v_rcp_f32_e32 v153, v128
	v_lshlrev_b32_e32 v128, 16, v129
	v_and_b32_e32 v129, 0xffff0000, v129
	v_and_b32_e32 v131, 0xffff0000, v131
	v_pk_fma_f32 v[132:133], v[152:153], v[132:133], v[128:129]
	v_mul_f32_e32 v128, 0xbfb8aa3b, v100
	v_mul_f32_e32 v129, 0xbfb8aa3b, v101
	v_exp_f32_e32 v128, v128
	v_exp_f32_e32 v129, v129
	v_lshlrev_b32_e32 v152, 16, v134
	v_and_b32_e32 v153, 0xffff0000, v134
	v_add_f32_e32 v128, 1.0, v128
	v_add_f32_e32 v129, 1.0, v129
	v_rcp_f32_e32 v128, v128
	v_rcp_f32_e32 v129, v129
	v_lshlrev_b32_e32 v134, 16, v135
	v_and_b32_e32 v135, 0xffff0000, v135
	s_mov_b64 s[46:47], -1
	v_pk_fma_f32 v[152:153], v[128:129], v[152:153], v[154:155]
	v_mul_f32_e32 v128, 0xbfb8aa3b, v102
	v_mul_f32_e32 v129, 0xbfb8aa3b, v103
	v_exp_f32_e32 v128, v128
	v_exp_f32_e32 v129, v129
	s_and_b64 vcc, exec, s[6:7]
	v_add_f32_e32 v128, 1.0, v128
	v_add_f32_e32 v129, 1.0, v129
	v_rcp_f32_e32 v128, v128
	v_rcp_f32_e32 v129, v129
	s_nop 0
	v_pk_fma_f32 v[134:135], v[128:129], v[134:135], v[130:131]
	v_cvt_pk_bf16_f32 v128, v150, v151
	v_cvt_pk_bf16_f32 v129, v132, v133
	v_cvt_pk_bf16_f32 v130, v152, v153
	v_cvt_pk_bf16_f32 v131, v134, v135
	s_cbranch_vccnz .LBB0_1305
	v_lshlrev_b64 v[132:133], 12, v[144:145]
	v_lshl_add_u64 v[132:133], s[22:23], 0, v[132:133]
	v_lshl_add_u64 v[132:133], v[142:143], 1, v[132:133]
	v_add_co_u32_e32 v132, vcc, 0x30000, v132
	s_mov_b64 s[46:47], 0
	s_nop 0
	v_addc_co_u32_e32 v133, vcc, 0, v133, vcc
	global_store_dwordx4 v[132:133], v[128:131], off

; __device__ __forceinline__ unsigned cvt_pk_bf16(float lo, float hi) { f32x2 v = {lo, hi}; bf16v2_t r = __builtin_convertvector(v, bf16v2_t); return __builtin_bit_cast(unsigned, r); }
; __device__ __forceinline__ float fsigmoid(float x) { return __builtin_amdgcn_rcpf(1.0f + fexp(-x)); }
;     __device__ __forceinline__ void operator()(const f32x4 (&acc)[2][2][4][2], const UnitG& u, int wr, int wc, int fr, int fq) const {
;     ...
;                     const v4u pw = *pp; v4u mw = {0u, 0u, 0u, 0u}; if (su > 1) mw = *pm_;
;                     const f32x4 g0 = acc[ai][bj][m][0], g1 = acc[ai][bj][m][1];
;                     float v[8];
;                     v[0] = fsigmoid(g0.x) * bf_lo(pw.x) + bf_lo(mw.x); v[1] = fsigmoid(g0.y) * bf_hi(pw.x) + bf_hi(mw.x);
;                     v[2] = fsigmoid(g0.z) * bf_lo(pw.y) + bf_lo(mw.y); v[3] = fsigmoid(g0.w) * bf_hi(pw.y) + bf_hi(mw.y);
;                     v[4] = fsigmoid(g1.x) * bf_lo(pw.z) + bf_lo(mw.z); v[5] = fsigmoid(g1.y) * bf_hi(pw.z) + bf_hi(mw.z);
;                     v[6] = fsigmoid(g1.z) * bf_lo(pw.w) + bf_lo(mw.w); v[7] = fsigmoid(g1.w) * bf_hi(pw.w) + bf_hi(mw.w);
;                     v4u w; w.x = cvt_pk_bf16(v[0], v[1]); w.y = cvt_pk_bf16(v[2], v[3]); w.z = cvt_pk_bf16(v[4], v[5]); w.w = cvt_pk_bf16(v[6], v[7]);
;                     if (su < 5) *pm_ = w;
;                     else *(v4u*)(MG + (size_t)(row0 + ai * 128 + m * 16) * D + col0 + bj * 128) = w;
.LBB0_1309:
	v_mul_f32_e32 v137, 0xbfb8aa3b, v80
	v_exp_f32_e32 v137, v137
	s_waitcnt vmcnt(0)
	v_lshlrev_b32_e32 v154, 16, v128
	v_and_b32_e32 v155, 0xffff0000, v128
	v_mul_f32_e32 v128, 0xbfb8aa3b, v82
	v_add_f32_e32 v137, 1.0, v137
	v_rcp_f32_e32 v150, v137
	v_mul_f32_e32 v137, 0xbfb8aa3b, v81
	v_exp_f32_e32 v137, v137
	v_exp_f32_e32 v128, v128
	v_lshlrev_b32_e32 v152, 16, v132
	v_and_b32_e32 v153, 0xffff0000, v132
	v_add_f32_e32 v137, 1.0, v137
	v_rcp_f32_e32 v151, v137
	v_add_f32_e32 v128, 1.0, v128
	v_lshlrev_b32_e32 v132, 16, v133
	v_and_b32_e32 v133, 0xffff0000, v133
	v_pk_fma_f32 v[150:151], v[150:151], v[152:153], v[154:155]
	v_rcp_f32_e32 v152, v128
	v_mul_f32_e32 v128, 0xbfb8aa3b, v83
	v_exp_f32_e32 v128, v128
	v_lshlrev_b32_e32 v154, 16, v130
	v_and_b32_e32 v155, 0xffff0000, v130
	v_lshlrev_b32_e32 v130, 16, v131
	v_add_f32_e32 v128, 1.0, v128
	v_rcp_f32_e32 v153, v128
	v_lshlrev_b32_e32 v128, 16, v129
	v_and_b32_e32 v129, 0xffff0000, v129
	v_and_b32_e32 v131, 0xffff0000, v131
	v_pk_fma_f32 v[132:133], v[152:153], v[132:133], v[128:129]
	v_mul_f32_e32 v128, 0xbfb8aa3b, v84
	v_mul_f32_e32 v129, 0xbfb8aa3b, v85
	v_exp_f32_e32 v128, v128
	v_exp_f32_e32 v129, v129
	v_lshlrev_b32_e32 v152, 16, v134
	v_and_b32_e32 v153, 0xffff0000, v134
	v_add_f32_e32 v128, 1.0, v128
	v_add_f32_e32 v129, 1.0, v129
	v_rcp_f32_e32 v128, v128
	v_rcp_f32_e32 v129, v129
	v_lshlrev_b32_e32 v134, 16, v135
	v_and_b32_e32 v135, 0xffff0000, v135
	s_mov_b64 s[46:47], -1
	v_pk_fma_f32 v[152:153], v[128:129], v[152:153], v[154:155]
	v_mul_f32_e32 v128, 0xbfb8aa3b, v86
	v_mul_f32_e32 v129, 0xbfb8aa3b, v87
	v_exp_f32_e32 v128, v128
	v_exp_f32_e32 v129, v129
	s_and_b64 vcc, exec, s[6:7]
	v_add_f32_e32 v128, 1.0, v128
	v_add_f32_e32 v129, 1.0, v129
	v_rcp_f32_e32 v128, v128
	v_rcp_f32_e32 v129, v129
	s_nop 0
	v_pk_fma_f32 v[134:135], v[128:129], v[134:135], v[130:131]
	v_cvt_pk_bf16_f32 v128, v150, v151
	v_cvt_pk_bf16_f32 v129, v132, v133
	v_cvt_pk_bf16_f32 v130, v152, v153
	v_cvt_pk_bf16_f32 v131, v134, v135
	s_cbranch_vccnz .LBB0_1311
	v_lshlrev_b64 v[132:133], 12, v[144:145]
	v_lshl_add_u64 v[132:133], s[22:23], 0, v[132:133]
	v_lshl_add_u64 v[132:133], v[142:143], 1, v[132:133]
	s_mov_b64 s[46:47], 0
	global_store_dwordx4 v[132:133], v[128:131], off offset:256

; __device__ __forceinline__ unsigned cvt_pk_bf16(float lo, float hi) { f32x2 v = {lo, hi}; bf16v2_t r = __builtin_convertvector(v, bf16v2_t); return __builtin_bit_cast(unsigned, r); }
; __device__ __forceinline__ float fsigmoid(float x) { return __builtin_amdgcn_rcpf(1.0f + fexp(-x)); }
;     __device__ __forceinline__ void operator()(const f32x4 (&acc)[2][2][4][2], const UnitG& u, int wr, int wc, int fr, int fq) const {
;     ...
;                     const v4u pw = *pp; v4u mw = {0u, 0u, 0u, 0u}; if (su > 1) mw = *pm_;
;                     const f32x4 g0 = acc[ai][bj][m][0], g1 = acc[ai][bj][m][1];
;                     float v[8];
;                     v[0] = fsigmoid(g0.x) * bf_lo(pw.x) + bf_lo(mw.x); v[1] = fsigmoid(g0.y) * bf_hi(pw.x) + bf_hi(mw.x);
;                     v[2] = fsigmoid(g0.z) * bf_lo(pw.y) + bf_lo(mw.y); v[3] = fsigmoid(g0.w) * bf_hi(pw.y) + bf_hi(mw.y);
;                     v[4] = fsigmoid(g1.x) * bf_lo(pw.z) + bf_lo(mw.z); v[5] = fsigmoid(g1.y) * bf_hi(pw.z) + bf_hi(mw.z);
;                     v[6] = fsigmoid(g1.z) * bf_lo(pw.w) + bf_lo(mw.w); v[7] = fsigmoid(g1.w) * bf_hi(pw.w) + bf_hi(mw.w);
;                     v4u w; w.x = cvt_pk_bf16(v[0], v[1]); w.y = cvt_pk_bf16(v[2], v[3]); w.z = cvt_pk_bf16(v[4], v[5]); w.w = cvt_pk_bf16(v[6], v[7]);
;                     if (su < 5) *pm_ = w;
;                     else *(v4u*)(MG + (size_t)(row0 + ai * 128 + m * 16) * D + col0 + bj * 128) = w;
.LBB0_1315:
	v_mul_f32_e32 v137, 0xbfb8aa3b, v64
	v_exp_f32_e32 v137, v137
	s_waitcnt vmcnt(0)
	v_lshlrev_b32_e32 v154, 16, v128
	v_and_b32_e32 v155, 0xffff0000, v128
	v_mul_f32_e32 v128, 0xbfb8aa3b, v66
	v_add_f32_e32 v137, 1.0, v137
	v_rcp_f32_e32 v150, v137
	v_mul_f32_e32 v137, 0xbfb8aa3b, v65
	v_exp_f32_e32 v137, v137
	v_exp_f32_e32 v128, v128
	v_lshlrev_b32_e32 v152, 16, v132
	v_and_b32_e32 v153, 0xffff0000, v132
	v_add_f32_e32 v137, 1.0, v137
	v_rcp_f32_e32 v151, v137
	v_add_f32_e32 v128, 1.0, v128
	v_lshlrev_b32_e32 v132, 16, v133
	v_and_b32_e32 v133, 0xffff0000, v133
	v_pk_fma_f32 v[150:151], v[150:151], v[152:153], v[154:155]
	v_rcp_f32_e32 v152, v128
	v_mul_f32_e32 v128, 0xbfb8aa3b, v67
	v_exp_f32_e32 v128, v128
	v_lshlrev_b32_e32 v154, 16, v130
	v_and_b32_e32 v155, 0xffff0000, v130
	v_lshlrev_b32_e32 v130, 16, v131
	v_add_f32_e32 v128, 1.0, v128
	v_rcp_f32_e32 v153, v128
	v_lshlrev_b32_e32 v128, 16, v129
	v_and_b32_e32 v129, 0xffff0000, v129
	v_and_b32_e32 v131, 0xffff0000, v131
	v_pk_fma_f32 v[132:133], v[152:153], v[132:133], v[128:129]
	v_mul_f32_e32 v128, 0xbfb8aa3b, v68
	v_mul_f32_e32 v129, 0xbfb8aa3b, v69
	v_exp_f32_e32 v128, v128
	v_exp_f32_e32 v129, v129
	v_lshlrev_b32_e32 v152, 16, v134
	v_and_b32_e32 v153, 0xffff0000, v134
	v_add_f32_e32 v128, 1.0, v128
	v_add_f32_e32 v129, 1.0, v129
	v_rcp_f32_e32 v128, v128
	v_rcp_f32_e32 v129, v129
	v_lshlrev_b32_e32 v134, 16, v135
	v_and_b32_e32 v135, 0xffff0000, v135
	s_mov_b64 s[46:47], -1
	v_pk_fma_f32 v[152:153], v[128:129], v[152:153], v[154:155]
	v_mul_f32_e32 v128, 0xbfb8aa3b, v70
	v_mul_f32_e32 v129, 0xbfb8aa3b, v71
	v_exp_f32_e32 v128, v128
	v_exp_f32_e32 v129, v129
	s_and_b64 vcc, exec, s[6:7]
	v_add_f32_e32 v128, 1.0, v128
	v_add_f32_e32 v129, 1.0, v129
	v_rcp_f32_e32 v128, v128
	v_rcp_f32_e32 v129, v129
	s_nop 0
	v_pk_fma_f32 v[134:135], v[128:129], v[134:135], v[130:131]
	v_cvt_pk_bf16_f32 v128, v150, v151
	v_cvt_pk_bf16_f32 v129, v132, v133
	v_cvt_pk_bf16_f32 v130, v152, v153
	v_cvt_pk_bf16_f32 v131, v134, v135
	s_cbranch_vccnz .LBB0_1317
	v_lshlrev_b64 v[132:133], 12, v[144:145]
	v_lshl_add_u64 v[132:133], s[22:23], 0, v[132:133]
	v_lshl_add_u64 v[132:133], v[142:143], 1, v[132:133]
	v_add_co_u32_e32 v132, vcc, 0x10000, v132
	s_mov_b64 s[46:47], 0
	s_nop 0
	v_addc_co_u32_e32 v133, vcc, 0, v133, vcc
	global_store_dwordx4 v[132:133], v[128:131], off offset:256

; __device__ __forceinline__ unsigned cvt_pk_bf16(float lo, float hi) { f32x2 v = {lo, hi}; bf16v2_t r = __builtin_convertvector(v, bf16v2_t); return __builtin_bit_cast(unsigned, r); }
; __device__ __forceinline__ float fsigmoid(float x) { return __builtin_amdgcn_rcpf(1.0f + fexp(-x)); }
;     __device__ __forceinline__ void operator()(const f32x4 (&acc)[2][2][4][2], const UnitG& u, int wr, int wc, int fr, int fq) const {
;     ...
;                     const v4u pw = *pp; v4u mw = {0u, 0u, 0u, 0u}; if (su > 1) mw = *pm_;
;                     const f32x4 g0 = acc[ai][bj][m][0], g1 = acc[ai][bj][m][1];
;                     float v[8];
;                     v[0] = fsigmoid(g0.x) * bf_lo(pw.x) + bf_lo(mw.x); v[1] = fsigmoid(g0.y) * bf_hi(pw.x) + bf_hi(mw.x);
;                     v[2] = fsigmoid(g0.z) * bf_lo(pw.y) + bf_lo(mw.y); v[3] = fsigmoid(g0.w) * bf_hi(pw.y) + bf_hi(mw.y);
;                     v[4] = fsigmoid(g1.x) * bf_lo(pw.z) + bf_lo(mw.z); v[5] = fsigmoid(g1.y) * bf_hi(pw.z) + bf_hi(mw.z);
;                     v[6] = fsigmoid(g1.z) * bf_lo(pw.w) + bf_lo(mw.w); v[7] = fsigmoid(g1.w) * bf_hi(pw.w) + bf_hi(mw.w);
;                     v4u w; w.x = cvt_pk_bf16(v[0], v[1]); w.y = cvt_pk_bf16(v[2], v[3]); w.z = cvt_pk_bf16(v[4], v[5]); w.w = cvt_pk_bf16(v[6], v[7]);
;                     if (su < 5) *pm_ = w;
;                     else *(v4u*)(MG + (size_t)(row0 + ai * 128 + m * 16) * D + col0 + bj * 128) = w;
.LBB0_1321:
	v_mul_f32_e32 v137, 0xbfb8aa3b, v48
	v_exp_f32_e32 v137, v137
	s_waitcnt vmcnt(0)
	v_lshlrev_b32_e32 v154, 16, v128
	v_and_b32_e32 v155, 0xffff0000, v128
	v_mul_f32_e32 v128, 0xbfb8aa3b, v50
	v_add_f32_e32 v137, 1.0, v137
	v_rcp_f32_e32 v150, v137
	v_mul_f32_e32 v137, 0xbfb8aa3b, v49
	v_exp_f32_e32 v137, v137
	v_exp_f32_e32 v128, v128
	v_lshlrev_b32_e32 v152, 16, v132
	v_and_b32_e32 v153, 0xffff0000, v132
	v_add_f32_e32 v137, 1.0, v137
	v_rcp_f32_e32 v151, v137
	v_add_f32_e32 v128, 1.0, v128
	v_lshlrev_b32_e32 v132, 16, v133
	v_and_b32_e32 v133, 0xffff0000, v133
	v_pk_fma_f32 v[150:151], v[150:151], v[152:153], v[154:155]
	v_rcp_f32_e32 v152, v128
	v_mul_f32_e32 v128, 0xbfb8aa3b, v51
	v_exp_f32_e32 v128, v128
	v_lshlrev_b32_e32 v154, 16, v130
	v_and_b32_e32 v155, 0xffff0000, v130
	v_lshlrev_b32_e32 v130, 16, v131
	v_add_f32_e32 v128, 1.0, v128
	v_rcp_f32_e32 v153, v128
	v_lshlrev_b32_e32 v128, 16, v129
	v_and_b32_e32 v129, 0xffff0000, v129
	v_and_b32_e32 v131, 0xffff0000, v131
	v_pk_fma_f32 v[132:133], v[152:153], v[132:133], v[128:129]
	v_mul_f32_e32 v128, 0xbfb8aa3b, v52
	v_mul_f32_e32 v129, 0xbfb8aa3b, v53
	v_exp_f32_e32 v128, v128
	v_exp_f32_e32 v129, v129
	v_lshlrev_b32_e32 v152, 16, v134
	v_and_b32_e32 v153, 0xffff0000, v134
	v_add_f32_e32 v128, 1.0, v128
	v_add_f32_e32 v129, 1.0, v129
	v_rcp_f32_e32 v128, v128
	v_rcp_f32_e32 v129, v129
	v_lshlrev_b32_e32 v134, 16, v135
	v_and_b32_e32 v135, 0xffff0000, v135
	s_mov_b64 s[46:47], -1
	v_pk_fma_f32 v[152:153], v[128:129], v[152:153], v[154:155]
	v_mul_f32_e32 v128, 0xbfb8aa3b, v54
	v_mul_f32_e32 v129, 0xbfb8aa3b, v55
	v_exp_f32_e32 v128, v128
	v_exp_f32_e32 v129, v129
	s_and_b64 vcc, exec, s[6:7]
	v_add_f32_e32 v128, 1.0, v128
	v_add_f32_e32 v129, 1.0, v129
	v_rcp_f32_e32 v128, v128
	v_rcp_f32_e32 v129, v129
	s_nop 0
	v_pk_fma_f32 v[134:135], v[128:129], v[134:135], v[130:131]
	v_cvt_pk_bf16_f32 v128, v150, v151
	v_cvt_pk_bf16_f32 v129, v132, v133
	v_cvt_pk_bf16_f32 v130, v152, v153
	v_cvt_pk_bf16_f32 v131, v134, v135
	s_cbranch_vccnz .LBB0_1323
	v_lshlrev_b64 v[132:133], 12, v[144:145]
	v_lshl_add_u64 v[132:133], s[22:23], 0, v[132:133]
	v_lshl_add_u64 v[132:133], v[142:143], 1, v[132:133]
	v_add_co_u32_e32 v132, vcc, 0x20000, v132
	s_mov_b64 s[46:47], 0
	s_nop 0
	v_addc_co_u32_e32 v133, vcc, 0, v133, vcc
	global_store_dwordx4 v[132:133], v[128:131], off offset:256

; __device__ __forceinline__ unsigned cvt_pk_bf16(float lo, float hi) { f32x2 v = {lo, hi}; bf16v2_t r = __builtin_convertvector(v, bf16v2_t); return __builtin_bit_cast(unsigned, r); }
; __device__ __forceinline__ float fsigmoid(float x) { return __builtin_amdgcn_rcpf(1.0f + fexp(-x)); }
;     __device__ __forceinline__ void operator()(const f32x4 (&acc)[2][2][4][2], const UnitG& u, int wr, int wc, int fr, int fq) const {
;     ...
;                     const v4u pw = *pp; v4u mw = {0u, 0u, 0u, 0u}; if (su > 1) mw = *pm_;
;                     const f32x4 g0 = acc[ai][bj][m][0], g1 = acc[ai][bj][m][1];
;                     float v[8];
;                     v[0] = fsigmoid(g0.x) * bf_lo(pw.x) + bf_lo(mw.x); v[1] = fsigmoid(g0.y) * bf_hi(pw.x) + bf_hi(mw.x);
;                     v[2] = fsigmoid(g0.z) * bf_lo(pw.y) + bf_lo(mw.y); v[3] = fsigmoid(g0.w) * bf_hi(pw.y) + bf_hi(mw.y);
;                     v[4] = fsigmoid(g1.x) * bf_lo(pw.z) + bf_lo(mw.z); v[5] = fsigmoid(g1.y) * bf_hi(pw.z) + bf_hi(mw.z);
;                     v[6] = fsigmoid(g1.z) * bf_lo(pw.w) + bf_lo(mw.w); v[7] = fsigmoid(g1.w) * bf_hi(pw.w) + bf_hi(mw.w);
;                     v4u w; w.x = cvt_pk_bf16(v[0], v[1]); w.y = cvt_pk_bf16(v[2], v[3]); w.z = cvt_pk_bf16(v[4], v[5]); w.w = cvt_pk_bf16(v[6], v[7]);
;                     if (su < 5) *pm_ = w;
;                     else *(v4u*)(MG + (size_t)(row0 + ai * 128 + m * 16) * D + col0 + bj * 128) = w;
.LBB0_1327:
	v_mul_f32_e32 v137, 0xbfb8aa3b, v32
	v_exp_f32_e32 v137, v137
	s_waitcnt vmcnt(0)
	v_lshlrev_b32_e32 v154, 16, v128
	v_and_b32_e32 v155, 0xffff0000, v128
	v_mul_f32_e32 v128, 0xbfb8aa3b, v34
	v_add_f32_e32 v137, 1.0, v137
	v_rcp_f32_e32 v150, v137
	v_mul_f32_e32 v137, 0xbfb8aa3b, v33
	v_exp_f32_e32 v137, v137
	v_exp_f32_e32 v128, v128
	v_lshlrev_b32_e32 v152, 16, v132
	v_and_b32_e32 v153, 0xffff0000, v132
	v_add_f32_e32 v137, 1.0, v137
	v_rcp_f32_e32 v151, v137
	v_add_f32_e32 v128, 1.0, v128
	v_lshlrev_b32_e32 v132, 16, v133
	v_and_b32_e32 v133, 0xffff0000, v133
	v_pk_fma_f32 v[150:151], v[150:151], v[152:153], v[154:155]
	v_rcp_f32_e32 v152, v128
	v_mul_f32_e32 v128, 0xbfb8aa3b, v35
	v_exp_f32_e32 v128, v128
	v_lshlrev_b32_e32 v154, 16, v130
	v_and_b32_e32 v155, 0xffff0000, v130
	v_lshlrev_b32_e32 v130, 16, v131
	v_add_f32_e32 v128, 1.0, v128
	v_rcp_f32_e32 v153, v128
	v_lshlrev_b32_e32 v128, 16, v129
	v_and_b32_e32 v129, 0xffff0000, v129
	v_and_b32_e32 v131, 0xffff0000, v131
	v_pk_fma_f32 v[132:133], v[152:153], v[132:133], v[128:129]
	v_mul_f32_e32 v128, 0xbfb8aa3b, v36
	v_mul_f32_e32 v129, 0xbfb8aa3b, v37
	v_exp_f32_e32 v128, v128
	v_exp_f32_e32 v129, v129
	v_lshlrev_b32_e32 v152, 16, v134
	v_and_b32_e32 v153, 0xffff0000, v134
	v_add_f32_e32 v128, 1.0, v128
	v_add_f32_e32 v129, 1.0, v129
	v_rcp_f32_e32 v128, v128
	v_rcp_f32_e32 v129, v129
	v_lshlrev_b32_e32 v134, 16, v135
	v_and_b32_e32 v135, 0xffff0000, v135
	s_mov_b64 s[46:47], -1
	v_pk_fma_f32 v[152:153], v[128:129], v[152:153], v[154:155]
	v_mul_f32_e32 v128, 0xbfb8aa3b, v38
	v_mul_f32_e32 v129, 0xbfb8aa3b, v39
	v_exp_f32_e32 v128, v128
	v_exp_f32_e32 v129, v129
	s_and_b64 vcc, exec, s[6:7]
	v_add_f32_e32 v128, 1.0, v128
	v_add_f32_e32 v129, 1.0, v129
	v_rcp_f32_e32 v128, v128
	v_rcp_f32_e32 v129, v129
	s_nop 0
	v_pk_fma_f32 v[134:135], v[128:129], v[134:135], v[130:131]
	v_cvt_pk_bf16_f32 v128, v150, v151
	v_cvt_pk_bf16_f32 v129, v132, v133
	v_cvt_pk_bf16_f32 v130, v152, v153
	v_cvt_pk_bf16_f32 v131, v134, v135
	s_cbranch_vccnz .LBB0_1329
	v_lshlrev_b64 v[132:133], 12, v[144:145]
	v_lshl_add_u64 v[132:133], s[22:23], 0, v[132:133]
	v_lshl_add_u64 v[132:133], v[142:143], 1, v[132:133]
	v_add_co_u32_e32 v132, vcc, 0x30000, v132
	s_mov_b64 s[46:47], 0
	s_nop 0
	v_addc_co_u32_e32 v133, vcc, 0, v133, vcc
	global_store_dwordx4 v[132:133], v[128:131], off offset:256

; __device__ __forceinline__ unsigned cvt_pk_bf16(float lo, float hi) { f32x2 v = {lo, hi}; bf16v2_t r = __builtin_convertvector(v, bf16v2_t); return __builtin_bit_cast(unsigned, r); }
; __device__ __forceinline__ float fsigmoid(float x) { return __builtin_amdgcn_rcpf(1.0f + fexp(-x)); }
;     __device__ __forceinline__ void operator()(const f32x4 (&acc)[2][2][4][2], const UnitG& u, int wr, int wc, int fr, int fq) const {
;     ...
;                     const v4u pw = *pp; v4u mw = {0u, 0u, 0u, 0u}; if (su > 1) mw = *pm_;
;                     const f32x4 g0 = acc[ai][bj][m][0], g1 = acc[ai][bj][m][1];
;                     float v[8];
;                     v[0] = fsigmoid(g0.x) * bf_lo(pw.x) + bf_lo(mw.x); v[1] = fsigmoid(g0.y) * bf_hi(pw.x) + bf_hi(mw.x);
;                     v[2] = fsigmoid(g0.z) * bf_lo(pw.y) + bf_lo(mw.y); v[3] = fsigmoid(g0.w) * bf_hi(pw.y) + bf_hi(mw.y);
;                     v[4] = fsigmoid(g1.x) * bf_lo(pw.z) + bf_lo(mw.z); v[5] = fsigmoid(g1.y) * bf_hi(pw.z) + bf_hi(mw.z);
;                     v[6] = fsigmoid(g1.z) * bf_lo(pw.w) + bf_lo(mw.w); v[7] = fsigmoid(g1.w) * bf_hi(pw.w) + bf_hi(mw.w);
;                     v4u w; w.x = cvt_pk_bf16(v[0], v[1]); w.y = cvt_pk_bf16(v[2], v[3]); w.z = cvt_pk_bf16(v[4], v[5]); w.w = cvt_pk_bf16(v[6], v[7]);
;                     if (su < 5) *pm_ = w;
;                     else *(v4u*)(MG + (size_t)(row0 + ai * 128 + m * 16) * D + col0 + bj * 128) = w;
.LBB0_1331:
	v_lshl_add_u64 v[150:151], v[146:147], 0, s[10:11]
	v_lshl_add_u64 v[152:153], v[148:149], 0, s[10:11]
	global_load_dwordx4 v[132:135], v[150:151], off
	v_mov_b32_e32 v128, 0
	s_and_b64 vcc, exec, s[4:5]
	v_mov_b32_e32 v129, 0
	v_mov_b32_e32 v130, 0
	v_mov_b32_e32 v131, 0
	s_cbranch_vccnz .LBB0_1333
	global_load_dwordx4 v[128:131], v[152:153], off
.LBB0_1333:
	v_mul_f32_e32 v137, 0xbfb8aa3b, v88
	v_exp_f32_e32 v137, v137
	s_waitcnt vmcnt(0)
	v_lshlrev_b32_e32 v156, 16, v128
	v_and_b32_e32 v157, 0xffff0000, v128
	v_mul_f32_e32 v128, 0xbfb8aa3b, v90
	v_add_f32_e32 v137, 1.0, v137
	v_rcp_f32_e32 v148, v137
	v_mul_f32_e32 v137, 0xbfb8aa3b, v89
	v_exp_f32_e32 v137, v137
	v_exp_f32_e32 v128, v128
	v_lshlrev_b32_e32 v154, 16, v132
	v_and_b32_e32 v155, 0xffff0000, v132
	v_add_f32_e32 v137, 1.0, v137
	v_rcp_f32_e32 v149, v137
	v_add_f32_e32 v128, 1.0, v128
	v_lshlrev_b32_e32 v132, 16, v133
	v_and_b32_e32 v133, 0xffff0000, v133
	v_pk_fma_f32 v[148:149], v[148:149], v[154:155], v[156:157]
	v_rcp_f32_e32 v154, v128
	v_mul_f32_e32 v128, 0xbfb8aa3b, v91
	v_exp_f32_e32 v128, v128
	v_lshlrev_b32_e32 v156, 16, v130
	v_and_b32_e32 v157, 0xffff0000, v130
	v_lshlrev_b32_e32 v130, 16, v131
	v_add_f32_e32 v128, 1.0, v128
	v_rcp_f32_e32 v155, v128
	v_lshlrev_b32_e32 v128, 16, v129
	v_and_b32_e32 v129, 0xffff0000, v129
	v_and_b32_e32 v131, 0xffff0000, v131
	v_pk_fma_f32 v[132:133], v[154:155], v[132:133], v[128:129]
	v_mul_f32_e32 v128, 0xbfb8aa3b, v92
	v_mul_f32_e32 v129, 0xbfb8aa3b, v93
	v_exp_f32_e32 v128, v128
	v_exp_f32_e32 v129, v129
	v_lshlrev_b32_e32 v154, 16, v134
	v_and_b32_e32 v155, 0xffff0000, v134
	v_add_f32_e32 v128, 1.0, v128
	v_add_f32_e32 v129, 1.0, v129
	v_rcp_f32_e32 v128, v128
	v_rcp_f32_e32 v129, v129
	v_lshlrev_b32_e32 v134, 16, v135
	v_and_b32_e32 v135, 0xffff0000, v135
	v_add_u32_e32 v146, 0x80, v144
	v_pk_fma_f32 v[154:155], v[128:129], v[154:155], v[156:157]
	v_mul_f32_e32 v128, 0xbfb8aa3b, v94
	v_mul_f32_e32 v129, 0xbfb8aa3b, v95
	v_exp_f32_e32 v128, v128
	v_exp_f32_e32 v129, v129
	s_mov_b64 s[46:47], -1
	s_and_b64 vcc, exec, s[6:7]
	v_add_f32_e32 v128, 1.0, v128
	v_add_f32_e32 v129, 1.0, v129
	v_rcp_f32_e32 v128, v128
	v_rcp_f32_e32 v129, v129
	v_ashrrev_i32_e32 v147, 31, v146
	v_pk_fma_f32 v[134:135], v[128:129], v[134:135], v[130:131]
	v_cvt_pk_bf16_f32 v128, v148, v149
	v_cvt_pk_bf16_f32 v129, v132, v133
	v_cvt_pk_bf16_f32 v130, v154, v155
	v_cvt_pk_bf16_f32 v131, v134, v135
	s_cbranch_vccnz .LBB0_1335
	v_lshlrev_b64 v[132:133], 12, v[146:147]
	v_lshl_add_u64 v[132:133], s[22:23], 0, v[132:133]
	v_lshl_add_u64 v[132:133], v[142:143], 1, v[132:133]
	s_mov_b64 s[46:47], 0
	global_store_dwordx4 v[132:133], v[128:131], off

; __device__ __forceinline__ unsigned cvt_pk_bf16(float lo, float hi) { f32x2 v = {lo, hi}; bf16v2_t r = __builtin_convertvector(v, bf16v2_t); return __builtin_bit_cast(unsigned, r); }
; __device__ __forceinline__ float fsigmoid(float x) { return __builtin_amdgcn_rcpf(1.0f + fexp(-x)); }
;     __device__ __forceinline__ void operator()(const f32x4 (&acc)[2][2][4][2], const UnitG& u, int wr, int wc, int fr, int fq) const {
;     ...
;                     const v4u pw = *pp; v4u mw = {0u, 0u, 0u, 0u}; if (su > 1) mw = *pm_;
;                     const f32x4 g0 = acc[ai][bj][m][0], g1 = acc[ai][bj][m][1];
;                     float v[8];
;                     v[0] = fsigmoid(g0.x) * bf_lo(pw.x) + bf_lo(mw.x); v[1] = fsigmoid(g0.y) * bf_hi(pw.x) + bf_hi(mw.x);
;                     v[2] = fsigmoid(g0.z) * bf_lo(pw.y) + bf_lo(mw.y); v[3] = fsigmoid(g0.w) * bf_hi(pw.y) + bf_hi(mw.y);
;                     v[4] = fsigmoid(g1.x) * bf_lo(pw.z) + bf_lo(mw.z); v[5] = fsigmoid(g1.y) * bf_hi(pw.z) + bf_hi(mw.z);
;                     v[6] = fsigmoid(g1.z) * bf_lo(pw.w) + bf_lo(mw.w); v[7] = fsigmoid(g1.w) * bf_hi(pw.w) + bf_hi(mw.w);
;                     v4u w; w.x = cvt_pk_bf16(v[0], v[1]); w.y = cvt_pk_bf16(v[2], v[3]); w.z = cvt_pk_bf16(v[4], v[5]); w.w = cvt_pk_bf16(v[6], v[7]);
;                     if (su < 5) *pm_ = w;
;                     else *(v4u*)(MG + (size_t)(row0 + ai * 128 + m * 16) * D + col0 + bj * 128) = w;
.LBB0_1337:
	v_lshl_add_u64 v[148:149], v[150:151], 0, s[10:11]
	v_lshl_add_u64 v[150:151], v[152:153], 0, s[10:11]
	global_load_dwordx4 v[132:135], v[148:149], off
	v_mov_b32_e32 v128, 0
	s_and_b64 vcc, exec, s[4:5]
	v_mov_b32_e32 v129, 0
	v_mov_b32_e32 v130, 0
	v_mov_b32_e32 v131, 0
	s_cbranch_vccnz .LBB0_1339
	global_load_dwordx4 v[128:131], v[150:151], off
.LBB0_1339:
	v_mul_f32_e32 v137, 0xbfb8aa3b, v72
	v_exp_f32_e32 v137, v137
	s_waitcnt vmcnt(0)
	v_lshlrev_b32_e32 v156, 16, v128
	v_and_b32_e32 v157, 0xffff0000, v128
	v_mul_f32_e32 v128, 0xbfb8aa3b, v74
	v_add_f32_e32 v137, 1.0, v137
	v_rcp_f32_e32 v152, v137
	v_mul_f32_e32 v137, 0xbfb8aa3b, v73
	v_exp_f32_e32 v137, v137
	v_exp_f32_e32 v128, v128
	v_lshlrev_b32_e32 v154, 16, v132
	v_and_b32_e32 v155, 0xffff0000, v132
	v_add_f32_e32 v137, 1.0, v137
	v_rcp_f32_e32 v153, v137
	v_add_f32_e32 v128, 1.0, v128
	v_lshlrev_b32_e32 v132, 16, v133
	v_and_b32_e32 v133, 0xffff0000, v133
	v_pk_fma_f32 v[152:153], v[152:153], v[154:155], v[156:157]
	v_rcp_f32_e32 v154, v128
	v_mul_f32_e32 v128, 0xbfb8aa3b, v75
	v_exp_f32_e32 v128, v128
	v_lshlrev_b32_e32 v156, 16, v130
	v_and_b32_e32 v157, 0xffff0000, v130
	v_lshlrev_b32_e32 v130, 16, v131
	v_add_f32_e32 v128, 1.0, v128
	v_rcp_f32_e32 v155, v128
	v_lshlrev_b32_e32 v128, 16, v129
	v_and_b32_e32 v129, 0xffff0000, v129
	v_and_b32_e32 v131, 0xffff0000, v131
	v_pk_fma_f32 v[132:133], v[154:155], v[132:133], v[128:129]
	v_mul_f32_e32 v128, 0xbfb8aa3b, v76
	v_mul_f32_e32 v129, 0xbfb8aa3b, v77
	v_exp_f32_e32 v128, v128
	v_exp_f32_e32 v129, v129
	v_lshlrev_b32_e32 v154, 16, v134
	v_and_b32_e32 v155, 0xffff0000, v134
	v_add_f32_e32 v128, 1.0, v128
	v_add_f32_e32 v129, 1.0, v129
	v_rcp_f32_e32 v128, v128
	v_rcp_f32_e32 v129, v129
	v_lshlrev_b32_e32 v134, 16, v135
	v_and_b32_e32 v135, 0xffff0000, v135
	s_mov_b64 s[46:47], -1
	v_pk_fma_f32 v[154:155], v[128:129], v[154:155], v[156:157]
	v_mul_f32_e32 v128, 0xbfb8aa3b, v78
	v_mul_f32_e32 v129, 0xbfb8aa3b, v79
	v_exp_f32_e32 v128, v128
	v_exp_f32_e32 v129, v129
	s_and_b64 vcc, exec, s[6:7]
	v_add_f32_e32 v128, 1.0, v128
	v_add_f32_e32 v129, 1.0, v129
	v_rcp_f32_e32 v128, v128
	v_rcp_f32_e32 v129, v129
	s_nop 0
	v_pk_fma_f32 v[134:135], v[128:129], v[134:135], v[130:131]
	v_cvt_pk_bf16_f32 v128, v152, v153
	v_cvt_pk_bf16_f32 v129, v132, v133
	v_cvt_pk_bf16_f32 v130, v154, v155
	v_cvt_pk_bf16_f32 v131, v134, v135
	s_cbranch_vccnz .LBB0_1341
	v_lshlrev_b64 v[132:133], 12, v[144:145]
	v_lshl_add_u64 v[132:133], s[22:23], 0, v[132:133]
	v_lshl_add_u64 v[132:133], v[142:143], 1, v[132:133]
	v_add_co_u32_e32 v132, vcc, 0x90000, v132
	s_mov_b64 s[46:47], 0
	s_nop 0
	v_addc_co_u32_e32 v133, vcc, 0, v133, vcc
	global_store_dwordx4 v[132:133], v[128:131], off

; __device__ __forceinline__ unsigned cvt_pk_bf16(float lo, float hi) { f32x2 v = {lo, hi}; bf16v2_t r = __builtin_convertvector(v, bf16v2_t); return __builtin_bit_cast(unsigned, r); }
; __device__ __forceinline__ float fsigmoid(float x) { return __builtin_amdgcn_rcpf(1.0f + fexp(-x)); }
;     __device__ __forceinline__ void operator()(const f32x4 (&acc)[2][2][4][2], const UnitG& u, int wr, int wc, int fr, int fq) const {
;     ...
;                     const v4u pw = *pp; v4u mw = {0u, 0u, 0u, 0u}; if (su > 1) mw = *pm_;
;                     const f32x4 g0 = acc[ai][bj][m][0], g1 = acc[ai][bj][m][1];
;                     float v[8];
;                     v[0] = fsigmoid(g0.x) * bf_lo(pw.x) + bf_lo(mw.x); v[1] = fsigmoid(g0.y) * bf_hi(pw.x) + bf_hi(mw.x);
;                     v[2] = fsigmoid(g0.z) * bf_lo(pw.y) + bf_lo(mw.y); v[3] = fsigmoid(g0.w) * bf_hi(pw.y) + bf_hi(mw.y);
;                     v[4] = fsigmoid(g1.x) * bf_lo(pw.z) + bf_lo(mw.z); v[5] = fsigmoid(g1.y) * bf_hi(pw.z) + bf_hi(mw.z);
;                     v[6] = fsigmoid(g1.z) * bf_lo(pw.w) + bf_lo(mw.w); v[7] = fsigmoid(g1.w) * bf_hi(pw.w) + bf_hi(mw.w);
;                     v4u w; w.x = cvt_pk_bf16(v[0], v[1]); w.y = cvt_pk_bf16(v[2], v[3]); w.z = cvt_pk_bf16(v[4], v[5]); w.w = cvt_pk_bf16(v[6], v[7]);
;                     if (su < 5) *pm_ = w;
;                     else *(v4u*)(MG + (size_t)(row0 + ai * 128 + m * 16) * D + col0 + bj * 128) = w;
.LBB0_1343:
	v_lshl_add_u64 v[148:149], v[148:149], 0, s[10:11]
	v_lshl_add_u64 v[150:151], v[150:151], 0, s[10:11]
	global_load_dwordx4 v[132:135], v[148:149], off
	v_mov_b32_e32 v128, 0
	s_and_b64 vcc, exec, s[4:5]
	v_mov_b32_e32 v129, 0
	v_mov_b32_e32 v130, 0
	v_mov_b32_e32 v131, 0
	s_cbranch_vccnz .LBB0_1345
	global_load_dwordx4 v[128:131], v[150:151], off
.LBB0_1345:
	v_mul_f32_e32 v137, 0xbfb8aa3b, v56
	v_exp_f32_e32 v137, v137
	s_waitcnt vmcnt(0)
	v_lshlrev_b32_e32 v156, 16, v128
	v_and_b32_e32 v157, 0xffff0000, v128
	v_mul_f32_e32 v128, 0xbfb8aa3b, v58
	v_add_f32_e32 v137, 1.0, v137
	v_rcp_f32_e32 v152, v137
	v_mul_f32_e32 v137, 0xbfb8aa3b, v57
	v_exp_f32_e32 v137, v137
	v_exp_f32_e32 v128, v128
	v_lshlrev_b32_e32 v154, 16, v132
	v_and_b32_e32 v155, 0xffff0000, v132
	v_add_f32_e32 v137, 1.0, v137
	v_rcp_f32_e32 v153, v137
	v_add_f32_e32 v128, 1.0, v128
	v_lshlrev_b32_e32 v132, 16, v133
	v_and_b32_e32 v133, 0xffff0000, v133
	v_pk_fma_f32 v[152:153], v[152:153], v[154:155], v[156:157]
	v_rcp_f32_e32 v154, v128
	v_mul_f32_e32 v128, 0xbfb8aa3b, v59
	v_exp_f32_e32 v128, v128
	v_lshlrev_b32_e32 v156, 16, v130
	v_and_b32_e32 v157, 0xffff0000, v130
	v_lshlrev_b32_e32 v130, 16, v131
	v_add_f32_e32 v128, 1.0, v128
	v_rcp_f32_e32 v155, v128
	v_lshlrev_b32_e32 v128, 16, v129
	v_and_b32_e32 v129, 0xffff0000, v129
	v_and_b32_e32 v131, 0xffff0000, v131
	v_pk_fma_f32 v[132:133], v[154:155], v[132:133], v[128:129]
	v_mul_f32_e32 v128, 0xbfb8aa3b, v60
	v_mul_f32_e32 v129, 0xbfb8aa3b, v61
	v_exp_f32_e32 v128, v128
	v_exp_f32_e32 v129, v129
	v_lshlrev_b32_e32 v154, 16, v134
	v_and_b32_e32 v155, 0xffff0000, v134
	v_add_f32_e32 v128, 1.0, v128
	v_add_f32_e32 v129, 1.0, v129
	v_rcp_f32_e32 v128, v128
	v_rcp_f32_e32 v129, v129
	v_lshlrev_b32_e32 v134, 16, v135
	v_and_b32_e32 v135, 0xffff0000, v135
	s_mov_b64 s[46:47], -1
	v_pk_fma_f32 v[154:155], v[128:129], v[154:155], v[156:157]
	v_mul_f32_e32 v128, 0xbfb8aa3b, v62
	v_mul_f32_e32 v129, 0xbfb8aa3b, v63
	v_exp_f32_e32 v128, v128
	v_exp_f32_e32 v129, v129
	s_and_b64 vcc, exec, s[6:7]
	v_add_f32_e32 v128, 1.0, v128
	v_add_f32_e32 v129, 1.0, v129
	v_rcp_f32_e32 v128, v128
	v_rcp_f32_e32 v129, v129
	s_nop 0
	v_pk_fma_f32 v[134:135], v[128:129], v[134:135], v[130:131]
	v_cvt_pk_bf16_f32 v128, v152, v153
	v_cvt_pk_bf16_f32 v129, v132, v133
	v_cvt_pk_bf16_f32 v130, v154, v155
	v_cvt_pk_bf16_f32 v131, v134, v135
	s_cbranch_vccnz .LBB0_1347
	v_lshlrev_b64 v[132:133], 12, v[144:145]
	v_lshl_add_u64 v[132:133], s[22:23], 0, v[132:133]
	v_lshl_add_u64 v[132:133], v[142:143], 1, v[132:133]
	v_add_co_u32_e32 v132, vcc, 0xa0000, v132
	s_mov_b64 s[46:47], 0
	s_nop 0
	v_addc_co_u32_e32 v133, vcc, 0, v133, vcc
	global_store_dwordx4 v[132:133], v[128:131], off

; __device__ __forceinline__ unsigned cvt_pk_bf16(float lo, float hi) { f32x2 v = {lo, hi}; bf16v2_t r = __builtin_convertvector(v, bf16v2_t); return __builtin_bit_cast(unsigned, r); }
; __device__ __forceinline__ float fsigmoid(float x) { return __builtin_amdgcn_rcpf(1.0f + fexp(-x)); }
;     __device__ __forceinline__ void operator()(const f32x4 (&acc)[2][2][4][2], const UnitG& u, int wr, int wc, int fr, int fq) const {
;     ...
;                     const v4u pw = *pp; v4u mw = {0u, 0u, 0u, 0u}; if (su > 1) mw = *pm_;
;                     const f32x4 g0 = acc[ai][bj][m][0], g1 = acc[ai][bj][m][1];
;                     float v[8];
;                     v[0] = fsigmoid(g0.x) * bf_lo(pw.x) + bf_lo(mw.x); v[1] = fsigmoid(g0.y) * bf_hi(pw.x) + bf_hi(mw.x);
;                     v[2] = fsigmoid(g0.z) * bf_lo(pw.y) + bf_lo(mw.y); v[3] = fsigmoid(g0.w) * bf_hi(pw.y) + bf_hi(mw.y);
;                     v[4] = fsigmoid(g1.x) * bf_lo(pw.z) + bf_lo(mw.z); v[5] = fsigmoid(g1.y) * bf_hi(pw.z) + bf_hi(mw.z);
;                     v[6] = fsigmoid(g1.z) * bf_lo(pw.w) + bf_lo(mw.w); v[7] = fsigmoid(g1.w) * bf_hi(pw.w) + bf_hi(mw.w);
;                     v4u w; w.x = cvt_pk_bf16(v[0], v[1]); w.y = cvt_pk_bf16(v[2], v[3]); w.z = cvt_pk_bf16(v[4], v[5]); w.w = cvt_pk_bf16(v[6], v[7]);
;                     if (su < 5) *pm_ = w;
;                     else *(v4u*)(MG + (size_t)(row0 + ai * 128 + m * 16) * D + col0 + bj * 128) = w;
.LBB0_1351:
	v_mul_f32_e32 v137, 0xbfb8aa3b, v40
	v_exp_f32_e32 v137, v137
	s_waitcnt vmcnt(0)
	v_lshlrev_b32_e32 v156, 16, v128
	v_and_b32_e32 v157, 0xffff0000, v128
	v_mul_f32_e32 v128, 0xbfb8aa3b, v42
	v_add_f32_e32 v137, 1.0, v137
	v_rcp_f32_e32 v152, v137
	v_mul_f32_e32 v137, 0xbfb8aa3b, v41
	v_exp_f32_e32 v137, v137
	v_exp_f32_e32 v128, v128
	v_lshlrev_b32_e32 v154, 16, v132
	v_and_b32_e32 v155, 0xffff0000, v132
	v_add_f32_e32 v137, 1.0, v137
	v_rcp_f32_e32 v153, v137
	v_add_f32_e32 v128, 1.0, v128
	v_lshlrev_b32_e32 v132, 16, v133
	v_and_b32_e32 v133, 0xffff0000, v133
	v_pk_fma_f32 v[152:153], v[152:153], v[154:155], v[156:157]
	v_rcp_f32_e32 v154, v128
	v_mul_f32_e32 v128, 0xbfb8aa3b, v43
	v_exp_f32_e32 v128, v128
	v_lshlrev_b32_e32 v156, 16, v130
	v_and_b32_e32 v157, 0xffff0000, v130
	v_lshlrev_b32_e32 v130, 16, v131
	v_add_f32_e32 v128, 1.0, v128
	v_rcp_f32_e32 v155, v128
	v_lshlrev_b32_e32 v128, 16, v129
	v_and_b32_e32 v129, 0xffff0000, v129
	v_and_b32_e32 v131, 0xffff0000, v131
	v_pk_fma_f32 v[132:133], v[154:155], v[132:133], v[128:129]
	v_mul_f32_e32 v128, 0xbfb8aa3b, v44
	v_mul_f32_e32 v129, 0xbfb8aa3b, v45
	v_exp_f32_e32 v128, v128
	v_exp_f32_e32 v129, v129
	v_lshlrev_b32_e32 v154, 16, v134
	v_and_b32_e32 v155, 0xffff0000, v134
	v_add_f32_e32 v128, 1.0, v128
	v_add_f32_e32 v129, 1.0, v129
	v_rcp_f32_e32 v128, v128
	v_rcp_f32_e32 v129, v129
	v_lshlrev_b32_e32 v134, 16, v135
	v_and_b32_e32 v135, 0xffff0000, v135
	s_mov_b64 s[46:47], -1
	v_pk_fma_f32 v[154:155], v[128:129], v[154:155], v[156:157]
	v_mul_f32_e32 v128, 0xbfb8aa3b, v46
	v_mul_f32_e32 v129, 0xbfb8aa3b, v47
	v_exp_f32_e32 v128, v128
	v_exp_f32_e32 v129, v129
	s_and_b64 vcc, exec, s[6:7]
	v_add_f32_e32 v128, 1.0, v128
	v_add_f32_e32 v129, 1.0, v129
	v_rcp_f32_e32 v128, v128
	v_rcp_f32_e32 v129, v129
	s_nop 0
	v_pk_fma_f32 v[134:135], v[128:129], v[134:135], v[130:131]
	v_cvt_pk_bf16_f32 v128, v152, v153
	v_cvt_pk_bf16_f32 v129, v132, v133
	v_cvt_pk_bf16_f32 v130, v154, v155
	v_cvt_pk_bf16_f32 v131, v134, v135
	s_cbranch_vccnz .LBB0_1353
	v_lshlrev_b64 v[132:133], 12, v[144:145]
	v_lshl_add_u64 v[132:133], s[22:23], 0, v[132:133]
	v_lshl_add_u64 v[132:133], v[142:143], 1, v[132:133]
	v_add_co_u32_e32 v132, vcc, 0xb0000, v132
	s_mov_b64 s[46:47], 0
	s_nop 0
	v_addc_co_u32_e32 v133, vcc, 0, v133, vcc
	global_store_dwordx4 v[132:133], v[128:131], off

; __device__ __forceinline__ unsigned cvt_pk_bf16(float lo, float hi) { f32x2 v = {lo, hi}; bf16v2_t r = __builtin_convertvector(v, bf16v2_t); return __builtin_bit_cast(unsigned, r); }
; __device__ __forceinline__ float fsigmoid(float x) { return __builtin_amdgcn_rcpf(1.0f + fexp(-x)); }
;     __device__ __forceinline__ void operator()(const f32x4 (&acc)[2][2][4][2], const UnitG& u, int wr, int wc, int fr, int fq) const {
;     ...
;                     const v4u pw = *pp; v4u mw = {0u, 0u, 0u, 0u}; if (su > 1) mw = *pm_;
;                     const f32x4 g0 = acc[ai][bj][m][0], g1 = acc[ai][bj][m][1];
;                     float v[8];
;                     v[0] = fsigmoid(g0.x) * bf_lo(pw.x) + bf_lo(mw.x); v[1] = fsigmoid(g0.y) * bf_hi(pw.x) + bf_hi(mw.x);
;                     v[2] = fsigmoid(g0.z) * bf_lo(pw.y) + bf_lo(mw.y); v[3] = fsigmoid(g0.w) * bf_hi(pw.y) + bf_hi(mw.y);
;                     v[4] = fsigmoid(g1.x) * bf_lo(pw.z) + bf_lo(mw.z); v[5] = fsigmoid(g1.y) * bf_hi(pw.z) + bf_hi(mw.z);
;                     v[6] = fsigmoid(g1.z) * bf_lo(pw.w) + bf_lo(mw.w); v[7] = fsigmoid(g1.w) * bf_hi(pw.w) + bf_hi(mw.w);
;                     v4u w; w.x = cvt_pk_bf16(v[0], v[1]); w.y = cvt_pk_bf16(v[2], v[3]); w.z = cvt_pk_bf16(v[4], v[5]); w.w = cvt_pk_bf16(v[6], v[7]);
;                     if (su < 5) *pm_ = w;
;                     else *(v4u*)(MG + (size_t)(row0 + ai * 128 + m * 16) * D + col0 + bj * 128) = w;
.LBB0_1357:
	v_mul_f32_e32 v137, 0xbfb8aa3b, v24
	v_exp_f32_e32 v137, v137
	s_waitcnt vmcnt(0)
	v_lshlrev_b32_e32 v156, 16, v128
	v_and_b32_e32 v157, 0xffff0000, v128
	v_mul_f32_e32 v128, 0xbfb8aa3b, v26
	v_add_f32_e32 v137, 1.0, v137
	v_rcp_f32_e32 v152, v137
	v_mul_f32_e32 v137, 0xbfb8aa3b, v25
	v_exp_f32_e32 v137, v137
	v_exp_f32_e32 v128, v128
	v_lshlrev_b32_e32 v154, 16, v132
	v_and_b32_e32 v155, 0xffff0000, v132
	v_add_f32_e32 v137, 1.0, v137
	v_rcp_f32_e32 v153, v137
	v_add_f32_e32 v128, 1.0, v128
	v_lshlrev_b32_e32 v132, 16, v133
	v_and_b32_e32 v133, 0xffff0000, v133
	v_pk_fma_f32 v[152:153], v[152:153], v[154:155], v[156:157]
	v_rcp_f32_e32 v154, v128
	v_mul_f32_e32 v128, 0xbfb8aa3b, v27
	v_exp_f32_e32 v128, v128
	v_lshlrev_b32_e32 v156, 16, v130
	v_and_b32_e32 v157, 0xffff0000, v130
	v_lshlrev_b32_e32 v130, 16, v131
	v_add_f32_e32 v128, 1.0, v128
	v_rcp_f32_e32 v155, v128
	v_lshlrev_b32_e32 v128, 16, v129
	v_and_b32_e32 v129, 0xffff0000, v129
	v_and_b32_e32 v131, 0xffff0000, v131
	v_pk_fma_f32 v[132:133], v[154:155], v[132:133], v[128:129]
	v_mul_f32_e32 v128, 0xbfb8aa3b, v28
	v_mul_f32_e32 v129, 0xbfb8aa3b, v29
	v_exp_f32_e32 v128, v128
	v_exp_f32_e32 v129, v129
	v_lshlrev_b32_e32 v154, 16, v134
	v_and_b32_e32 v155, 0xffff0000, v134
	v_add_f32_e32 v128, 1.0, v128
	v_add_f32_e32 v129, 1.0, v129
	v_rcp_f32_e32 v128, v128
	v_rcp_f32_e32 v129, v129
	v_lshlrev_b32_e32 v134, 16, v135
	v_and_b32_e32 v135, 0xffff0000, v135
	s_mov_b64 s[46:47], -1
	v_pk_fma_f32 v[154:155], v[128:129], v[154:155], v[156:157]
	v_mul_f32_e32 v128, 0xbfb8aa3b, v30
	v_mul_f32_e32 v129, 0xbfb8aa3b, v31
	v_exp_f32_e32 v128, v128
	v_exp_f32_e32 v129, v129
	s_and_b64 vcc, exec, s[6:7]
	v_add_f32_e32 v128, 1.0, v128
	v_add_f32_e32 v129, 1.0, v129
	v_rcp_f32_e32 v128, v128
	v_rcp_f32_e32 v129, v129
	s_nop 0
	v_pk_fma_f32 v[134:135], v[128:129], v[134:135], v[130:131]
	v_cvt_pk_bf16_f32 v128, v152, v153
	v_cvt_pk_bf16_f32 v129, v132, v133
	v_cvt_pk_bf16_f32 v130, v154, v155
	v_cvt_pk_bf16_f32 v131, v134, v135
	s_cbranch_vccnz .LBB0_1359
	v_lshlrev_b64 v[132:133], 12, v[146:147]
	v_lshl_add_u64 v[132:133], s[22:23], 0, v[132:133]
	v_lshl_add_u64 v[132:133], v[142:143], 1, v[132:133]
	s_mov_b64 s[46:47], 0
	global_store_dwordx4 v[132:133], v[128:131], off offset:256

; __device__ __forceinline__ unsigned cvt_pk_bf16(float lo, float hi) { f32x2 v = {lo, hi}; bf16v2_t r = __builtin_convertvector(v, bf16v2_t); return __builtin_bit_cast(unsigned, r); }
; __device__ __forceinline__ float fsigmoid(float x) { return __builtin_amdgcn_rcpf(1.0f + fexp(-x)); }
;     __device__ __forceinline__ void operator()(const f32x4 (&acc)[2][2][4][2], const UnitG& u, int wr, int wc, int fr, int fq) const {
;     ...
;                     const v4u pw = *pp; v4u mw = {0u, 0u, 0u, 0u}; if (su > 1) mw = *pm_;
;                     const f32x4 g0 = acc[ai][bj][m][0], g1 = acc[ai][bj][m][1];
;                     float v[8];
;                     v[0] = fsigmoid(g0.x) * bf_lo(pw.x) + bf_lo(mw.x); v[1] = fsigmoid(g0.y) * bf_hi(pw.x) + bf_hi(mw.x);
;                     v[2] = fsigmoid(g0.z) * bf_lo(pw.y) + bf_lo(mw.y); v[3] = fsigmoid(g0.w) * bf_hi(pw.y) + bf_hi(mw.y);
;                     v[4] = fsigmoid(g1.x) * bf_lo(pw.z) + bf_lo(mw.z); v[5] = fsigmoid(g1.y) * bf_hi(pw.z) + bf_hi(mw.z);
;                     v[6] = fsigmoid(g1.z) * bf_lo(pw.w) + bf_lo(mw.w); v[7] = fsigmoid(g1.w) * bf_hi(pw.w) + bf_hi(mw.w);
;                     v4u w; w.x = cvt_pk_bf16(v[0], v[1]); w.y = cvt_pk_bf16(v[2], v[3]); w.z = cvt_pk_bf16(v[4], v[5]); w.w = cvt_pk_bf16(v[6], v[7]);
;                     if (su < 5) *pm_ = w;
;                     else *(v4u*)(MG + (size_t)(row0 + ai * 128 + m * 16) * D + col0 + bj * 128) = w;
.LBB0_1361:
	v_lshl_add_u64 v[146:147], v[148:149], 0, s[10:11]
	v_lshl_add_u64 v[148:149], v[150:151], 0, s[10:11]
	global_load_dwordx4 v[132:135], v[146:147], off
	v_mov_b32_e32 v128, 0
	s_and_b64 vcc, exec, s[4:5]
	v_mov_b32_e32 v129, 0
	v_mov_b32_e32 v130, 0
	v_mov_b32_e32 v131, 0
	s_cbranch_vccnz .LBB0_1363
	global_load_dwordx4 v[128:131], v[148:149], off
.LBB0_1363:
	v_mul_f32_e32 v137, 0xbfb8aa3b, v16
	v_exp_f32_e32 v137, v137
	s_waitcnt vmcnt(0)
	v_lshlrev_b32_e32 v154, 16, v128
	v_and_b32_e32 v155, 0xffff0000, v128
	v_mul_f32_e32 v128, 0xbfb8aa3b, v18
	v_add_f32_e32 v137, 1.0, v137
	v_rcp_f32_e32 v150, v137
	v_mul_f32_e32 v137, 0xbfb8aa3b, v17
	v_exp_f32_e32 v137, v137
	v_exp_f32_e32 v128, v128
	v_lshlrev_b32_e32 v152, 16, v132
	v_and_b32_e32 v153, 0xffff0000, v132
	v_add_f32_e32 v137, 1.0, v137
	v_rcp_f32_e32 v151, v137
	v_add_f32_e32 v128, 1.0, v128
	v_lshlrev_b32_e32 v132, 16, v133
	v_and_b32_e32 v133, 0xffff0000, v133
	v_pk_fma_f32 v[150:151], v[150:151], v[152:153], v[154:155]
	v_rcp_f32_e32 v152, v128
	v_mul_f32_e32 v128, 0xbfb8aa3b, v19
	v_exp_f32_e32 v128, v128
	v_lshlrev_b32_e32 v154, 16, v130
	v_and_b32_e32 v155, 0xffff0000, v130
	v_lshlrev_b32_e32 v130, 16, v131
	v_add_f32_e32 v128, 1.0, v128
	v_rcp_f32_e32 v153, v128
	v_lshlrev_b32_e32 v128, 16, v129
	v_and_b32_e32 v129, 0xffff0000, v129
	v_and_b32_e32 v131, 0xffff0000, v131
	v_pk_fma_f32 v[132:133], v[152:153], v[132:133], v[128:129]
	v_mul_f32_e32 v128, 0xbfb8aa3b, v20
	v_mul_f32_e32 v129, 0xbfb8aa3b, v21
	v_exp_f32_e32 v128, v128
	v_exp_f32_e32 v129, v129
	v_lshlrev_b32_e32 v152, 16, v134
	v_and_b32_e32 v153, 0xffff0000, v134
	v_add_f32_e32 v128, 1.0, v128
	v_add_f32_e32 v129, 1.0, v129
	v_rcp_f32_e32 v128, v128
	v_rcp_f32_e32 v129, v129
	v_lshlrev_b32_e32 v134, 16, v135
	v_and_b32_e32 v135, 0xffff0000, v135
	s_mov_b64 s[46:47], -1
	v_pk_fma_f32 v[152:153], v[128:129], v[152:153], v[154:155]
	v_mul_f32_e32 v128, 0xbfb8aa3b, v22
	v_mul_f32_e32 v129, 0xbfb8aa3b, v23
	v_exp_f32_e32 v128, v128
	v_exp_f32_e32 v129, v129
	s_and_b64 vcc, exec, s[6:7]
	v_add_f32_e32 v128, 1.0, v128
	v_add_f32_e32 v129, 1.0, v129
	v_rcp_f32_e32 v128, v128
	v_rcp_f32_e32 v129, v129
	s_nop 0
	v_pk_fma_f32 v[134:135], v[128:129], v[134:135], v[130:131]
	v_cvt_pk_bf16_f32 v128, v150, v151
	v_cvt_pk_bf16_f32 v129, v132, v133
	v_cvt_pk_bf16_f32 v130, v152, v153
	v_cvt_pk_bf16_f32 v131, v134, v135
	s_cbranch_vccnz .LBB0_1365
	v_lshlrev_b64 v[132:133], 12, v[144:145]
	v_lshl_add_u64 v[132:133], s[22:23], 0, v[132:133]
	v_lshl_add_u64 v[132:133], v[142:143], 1, v[132:133]
	v_add_co_u32_e32 v132, vcc, 0x90000, v132
	s_mov_b64 s[46:47], 0
	s_nop 0
	v_addc_co_u32_e32 v133, vcc, 0, v133, vcc
	global_store_dwordx4 v[132:133], v[128:131], off offset:256

; __device__ __forceinline__ unsigned cvt_pk_bf16(float lo, float hi) { f32x2 v = {lo, hi}; bf16v2_t r = __builtin_convertvector(v, bf16v2_t); return __builtin_bit_cast(unsigned, r); }
; __device__ __forceinline__ float fsigmoid(float x) { return __builtin_amdgcn_rcpf(1.0f + fexp(-x)); }
;     __device__ __forceinline__ void operator()(const f32x4 (&acc)[2][2][4][2], const UnitG& u, int wr, int wc, int fr, int fq) const {
;     ...
;                     const v4u pw = *pp; v4u mw = {0u, 0u, 0u, 0u}; if (su > 1) mw = *pm_;
;                     const f32x4 g0 = acc[ai][bj][m][0], g1 = acc[ai][bj][m][1];
;                     float v[8];
;                     v[0] = fsigmoid(g0.x) * bf_lo(pw.x) + bf_lo(mw.x); v[1] = fsigmoid(g0.y) * bf_hi(pw.x) + bf_hi(mw.x);
;                     v[2] = fsigmoid(g0.z) * bf_lo(pw.y) + bf_lo(mw.y); v[3] = fsigmoid(g0.w) * bf_hi(pw.y) + bf_hi(mw.y);
;                     v[4] = fsigmoid(g1.x) * bf_lo(pw.z) + bf_lo(mw.z); v[5] = fsigmoid(g1.y) * bf_hi(pw.z) + bf_hi(mw.z);
;                     v[6] = fsigmoid(g1.z) * bf_lo(pw.w) + bf_lo(mw.w); v[7] = fsigmoid(g1.w) * bf_hi(pw.w) + bf_hi(mw.w);
;                     v4u w; w.x = cvt_pk_bf16(v[0], v[1]); w.y = cvt_pk_bf16(v[2], v[3]); w.z = cvt_pk_bf16(v[4], v[5]); w.w = cvt_pk_bf16(v[6], v[7]);
;                     if (su < 5) *pm_ = w;
;                     else *(v4u*)(MG + (size_t)(row0 + ai * 128 + m * 16) * D + col0 + bj * 128) = w;
.LBB0_1369:
	v_mul_f32_e32 v137, 0xbfb8aa3b, v8
	v_exp_f32_e32 v137, v137
	s_waitcnt vmcnt(0)
	v_lshlrev_b32_e32 v154, 16, v128
	v_and_b32_e32 v155, 0xffff0000, v128
	v_mul_f32_e32 v128, 0xbfb8aa3b, v10
	v_add_f32_e32 v137, 1.0, v137
	v_rcp_f32_e32 v150, v137
	v_mul_f32_e32 v137, 0xbfb8aa3b, v9
	v_exp_f32_e32 v137, v137
	v_exp_f32_e32 v128, v128
	v_lshlrev_b32_e32 v152, 16, v132
	v_and_b32_e32 v153, 0xffff0000, v132
	v_add_f32_e32 v137, 1.0, v137
	v_rcp_f32_e32 v151, v137
	v_add_f32_e32 v128, 1.0, v128
	v_lshlrev_b32_e32 v132, 16, v133
	v_and_b32_e32 v133, 0xffff0000, v133
	v_pk_fma_f32 v[150:151], v[150:151], v[152:153], v[154:155]
	v_rcp_f32_e32 v152, v128
	v_mul_f32_e32 v128, 0xbfb8aa3b, v11
	v_exp_f32_e32 v128, v128
	v_lshlrev_b32_e32 v154, 16, v130
	v_and_b32_e32 v155, 0xffff0000, v130
	v_lshlrev_b32_e32 v130, 16, v131
	v_add_f32_e32 v128, 1.0, v128
	v_rcp_f32_e32 v153, v128
	v_lshlrev_b32_e32 v128, 16, v129
	v_and_b32_e32 v129, 0xffff0000, v129
	v_and_b32_e32 v131, 0xffff0000, v131
	v_pk_fma_f32 v[132:133], v[152:153], v[132:133], v[128:129]
	v_mul_f32_e32 v128, 0xbfb8aa3b, v12
	v_mul_f32_e32 v129, 0xbfb8aa3b, v13
	v_exp_f32_e32 v128, v128
	v_exp_f32_e32 v129, v129
	v_lshlrev_b32_e32 v152, 16, v134
	v_and_b32_e32 v153, 0xffff0000, v134
	v_add_f32_e32 v128, 1.0, v128
	v_add_f32_e32 v129, 1.0, v129
	v_rcp_f32_e32 v128, v128
	v_rcp_f32_e32 v129, v129
	v_lshlrev_b32_e32 v134, 16, v135
	v_and_b32_e32 v135, 0xffff0000, v135
	s_mov_b64 s[46:47], -1
	v_pk_fma_f32 v[152:153], v[128:129], v[152:153], v[154:155]
	v_mul_f32_e32 v128, 0xbfb8aa3b, v14
	v_mul_f32_e32 v129, 0xbfb8aa3b, v15
	v_exp_f32_e32 v128, v128
	v_exp_f32_e32 v129, v129
	s_and_b64 vcc, exec, s[6:7]
	v_add_f32_e32 v128, 1.0, v128
	v_add_f32_e32 v129, 1.0, v129
	v_rcp_f32_e32 v128, v128
	v_rcp_f32_e32 v129, v129
	s_nop 0
	v_pk_fma_f32 v[134:135], v[128:129], v[134:135], v[130:131]
	v_cvt_pk_bf16_f32 v128, v150, v151
	v_cvt_pk_bf16_f32 v129, v132, v133
	v_cvt_pk_bf16_f32 v130, v152, v153
	v_cvt_pk_bf16_f32 v131, v134, v135
	s_cbranch_vccnz .LBB0_1371
	v_lshlrev_b64 v[132:133], 12, v[144:145]
	v_lshl_add_u64 v[132:133], s[22:23], 0, v[132:133]
	v_lshl_add_u64 v[132:133], v[142:143], 1, v[132:133]
	v_add_co_u32_e32 v132, vcc, 0xa0000, v132
	s_mov_b64 s[46:47], 0
	s_nop 0
	v_addc_co_u32_e32 v133, vcc, 0, v133, vcc
	global_store_dwordx4 v[132:133], v[128:131], off offset:256

; __device__ __forceinline__ unsigned cvt_pk_bf16(float lo, float hi) { f32x2 v = {lo, hi}; bf16v2_t r = __builtin_convertvector(v, bf16v2_t); return __builtin_bit_cast(unsigned, r); }
; __device__ __forceinline__ float fsigmoid(float x) { return __builtin_amdgcn_rcpf(1.0f + fexp(-x)); }
;     __device__ __forceinline__ void operator()(const f32x4 (&acc)[2][2][4][2], const UnitG& u, int wr, int wc, int fr, int fq) const {
;     ...
;                     const v4u pw = *pp; v4u mw = {0u, 0u, 0u, 0u}; if (su > 1) mw = *pm_;
;                     const f32x4 g0 = acc[ai][bj][m][0], g1 = acc[ai][bj][m][1];
;                     float v[8];
;                     v[0] = fsigmoid(g0.x) * bf_lo(pw.x) + bf_lo(mw.x); v[1] = fsigmoid(g0.y) * bf_hi(pw.x) + bf_hi(mw.x);
;                     v[2] = fsigmoid(g0.z) * bf_lo(pw.y) + bf_lo(mw.y); v[3] = fsigmoid(g0.w) * bf_hi(pw.y) + bf_hi(mw.y);
;                     v[4] = fsigmoid(g1.x) * bf_lo(pw.z) + bf_lo(mw.z); v[5] = fsigmoid(g1.y) * bf_hi(pw.z) + bf_hi(mw.z);
;                     v[6] = fsigmoid(g1.z) * bf_lo(pw.w) + bf_lo(mw.w); v[7] = fsigmoid(g1.w) * bf_hi(pw.w) + bf_hi(mw.w);
;                     v4u w; w.x = cvt_pk_bf16(v[0], v[1]); w.y = cvt_pk_bf16(v[2], v[3]); w.z = cvt_pk_bf16(v[4], v[5]); w.w = cvt_pk_bf16(v[6], v[7]);
;                     if (su < 5) *pm_ = w;
;                     else *(v4u*)(MG + (size_t)(row0 + ai * 128 + m * 16) * D + col0 + bj * 128) = w;
.LBB0_1375:
	v_mul_f32_e32 v137, 0xbfb8aa3b, v0
	v_mul_f32_e32 v139, 0xbfb8aa3b, v1
	v_exp_f32_e32 v137, v137
	v_exp_f32_e32 v139, v139
	s_waitcnt vmcnt(0)
	v_lshlrev_b32_e32 v154, 16, v128
	v_and_b32_e32 v155, 0xffff0000, v128
	v_mul_f32_e32 v128, 0xbfb8aa3b, v2
	v_add_f32_e32 v137, 1.0, v137
	v_add_f32_e32 v139, 1.0, v139
	v_lshlrev_b32_e32 v152, 16, v132
	v_and_b32_e32 v153, 0xffff0000, v132
	v_exp_f32_e32 v128, v128
	v_mul_f32_e32 v132, 0xbfb8aa3b, v3
	v_rcp_f32_e32 v150, v137
	v_rcp_f32_e32 v151, v139
	v_exp_f32_e32 v132, v132
	v_add_f32_e32 v128, 1.0, v128
	v_mul_f32_e32 v137, 0xbfb8aa3b, v4
	v_pk_fma_f32 v[150:151], v[150:151], v[152:153], v[154:155]
	v_rcp_f32_e32 v152, v128
	v_add_f32_e32 v128, 1.0, v132
	v_mul_f32_e32 v139, 0xbfb8aa3b, v5
	v_rcp_f32_e32 v153, v128
	v_exp_f32_e32 v137, v137
	v_exp_f32_e32 v139, v139
	v_lshlrev_b32_e32 v132, 16, v133
	v_and_b32_e32 v133, 0xffff0000, v133
	v_lshlrev_b32_e32 v128, 16, v129
	v_and_b32_e32 v129, 0xffff0000, v129
	v_pk_fma_f32 v[132:133], v[152:153], v[132:133], v[128:129]
	v_add_f32_e32 v128, 1.0, v137
	v_add_f32_e32 v129, 1.0, v139
	v_lshlrev_b32_e32 v152, 16, v134
	v_and_b32_e32 v153, 0xffff0000, v134
	v_lshlrev_b32_e32 v154, 16, v130
	v_and_b32_e32 v155, 0xffff0000, v130
	v_mul_f32_e32 v130, 0xbfb8aa3b, v6
	v_mul_f32_e32 v134, 0xbfb8aa3b, v7
	v_rcp_f32_e32 v128, v128
	v_rcp_f32_e32 v129, v129
	v_exp_f32_e32 v130, v130
	v_exp_f32_e32 v134, v134
	s_and_b64 vcc, exec, s[6:7]
	v_pk_fma_f32 v[152:153], v[128:129], v[152:153], v[154:155]
	v_add_f32_e32 v128, 1.0, v130
	v_add_f32_e32 v129, 1.0, v134
	v_rcp_f32_e32 v128, v128
	v_rcp_f32_e32 v129, v129
	v_lshlrev_b32_e32 v134, 16, v135
	v_and_b32_e32 v135, 0xffff0000, v135
	v_lshlrev_b32_e32 v130, 16, v131
	v_and_b32_e32 v131, 0xffff0000, v131
	v_pk_fma_f32 v[134:135], v[128:129], v[134:135], v[130:131]
	v_cvt_pk_bf16_f32 v128, v150, v151
	v_cvt_pk_bf16_f32 v129, v132, v133
	v_cvt_pk_bf16_f32 v130, v152, v153
	v_cvt_pk_bf16_f32 v131, v134, v135
	s_mov_b64 s[4:5], -1
	s_cbranch_vccnz .LBB0_1377
	v_lshlrev_b64 v[132:133], 12, v[144:145]
	v_lshl_add_u64 v[132:133], s[22:23], 0, v[132:133]
	v_lshl_add_u64 v[132:133], v[142:143], 1, v[132:133]
	v_add_co_u32_e32 v132, vcc, 0xb0000, v132
	s_mov_b64 s[4:5], 0
	s_nop 0
	v_addc_co_u32_e32 v133, vcc, 0, v133, vcc
	global_store_dwordx4 v[132:133], v[128:131], off offset:256
